# speedup vs baseline: 1.0634x; 1.0034x over previous
; #define P8_STAGE(P,BASE,br,kt) do{const bfr* _ub=(BASE)+((long)(br)*K+(long)(kt)*BK); \
;     __builtin_amdgcn_global_load_lds((const unsigned*)(_ub+so0),(unsigned*)((char*)(P)+wid*1024),16,0,0); \
;     __builtin_amdgcn_global_load_lds((const unsigned*)(_ub+so1),(unsigned*)((char*)(P)+wid*1024+8192),16,0,0);}while(0)
; #define P8_LDA(dst,b,h) _Pragma("unroll") for(int m=0;m<4;++m) _Pragma("unroll") for(int k=0;k<2;++k) \
;     dst[m][k]=*reinterpret_cast<const bf16x8*>((char*)P8_SA(b,h)+lds_byte(wr*64+m*16+fr,k*32+fq*8))
; #define P8_LDB(dst,b,h) _Pragma("unroll") for(int n=0;n<2;++n) _Pragma("unroll") for(int k=0;k<2;++k) \
;     dst[n][k]=*reinterpret_cast<const bf16x8*>((char*)P8_SB(b,h)+lds_byte(wc*32+n*16+fr,k*32+fq*8))
; #define P8_MMA(ai,bj,At,Bt) do{__builtin_amdgcn_s_setprio(1); \
;     _Pragma("unroll") for(int m=0;m<4;++m) _Pragma("unroll") for(int n=0;n<2;++n) _Pragma("unroll") for(int k=0;k<2;++k) \
;       acc[ai][bj][m][n]=__builtin_amdgcn_mfma_f32_16x16x32_bf16(At[m][k],Bt[n][k],acc[ai][bj][m][n],0,0,0); \
;     __builtin_amdgcn_s_setprio(0);}while(0)
; #define P8_WAIT_V(n) asm volatile("s_waitcnt vmcnt(" #n ")":::"memory")
; #define P8_WAIT_L(n) asm volatile("s_waitcnt lgkmcnt(" #n ")":::"memory")
; #define P8_BAR __builtin_amdgcn_s_barrier()
; #define P8_SCHED __builtin_amdgcn_sched_barrier(0)
; template <class EPI>
; DEVI void gemm8_tile(const bfr* __restrict__ A, const bfr* __restrict__ Bt, int K, int brow, int bcol, int nbrow, int nbcol, char* shmc, EPI epi) {
;     ...
;     P8_LDB(B0,0,0); P8_SCHED; P8_LDA(At,0,0); P8_STAGE(P8_SA(1,1),A,brow+128,t+1);
;     P8_WAIT_L(8); P8_BAR; P8_WAIT_L(0); P8_MMA(0,0,At,B0); P8_BAR; P8_SCHED;
;     P8_LDB(B1,0,1); P8_STAGE(P8_SB(0,0),Bt,bcol,t+2);
;     P8_BAR; P8_WAIT_L(0); P8_MMA(0,1,At,B1); P8_BAR;
;     P8_LDA(At,0,1); P8_STAGE(P8_SA(0,0),A,brow,t+2);
;     P8_BAR; P8_WAIT_L(0); P8_MMA(1,0,At,B0); P8_BAR; P8_SCHED;
;     P8_STAGE(P8_SB(0,1),Bt,bcol+128,t+2);
;     P8_WAIT_V(6); P8_BAR; P8_MMA(1,1,At,B1); P8_BAR;
.LBB0_85:
	ds_read_b128 v[174:177], v157
	ds_read_b128 v[178:181], v157 offset:1024
	ds_read_b128 v[182:185], v157 offset:2048
	ds_read_b128 v[186:189], v157 offset:3072
	v_add_u32_e32 v158, s54, v140
	s_add_i32 m0, s100, 0xc000
	ds_read_b128 v[160:163], v147
	ds_read_b128 v[190:193], v147 offset:1024
	ds_read_b128 v[196:199], v146
	ds_read_b128 v[200:203], v146 offset:1024
	ds_read_b128 v[204:207], v145
	ds_read_b128 v[208:211], v145 offset:1024
	ds_read_b128 v[212:215], v144
	ds_read_b128 v[216:219], v144 offset:1024
	global_load_lds_dwordx4 v158, s[86:87]
	v_add_u32_e32 v158, s54, v138
	s_add_i32 m0, s100, 0xe000
	s_nop 0
	global_load_lds_dwordx4 v158, s[86:87]
	s_waitcnt lgkmcnt(8)
	s_barrier
	s_waitcnt lgkmcnt(0)
	v_mfma_f32_16x16x32_bf16 v[124:127], v[160:163], v[174:177], v[124:127]
	v_mfma_f32_16x16x32_bf16 v[120:123], v[160:163], v[182:185], v[120:123]
	v_mfma_f32_16x16x32_bf16 v[116:119], v[196:199], v[174:177], v[116:119]
	v_mfma_f32_16x16x32_bf16 v[112:115], v[196:199], v[182:185], v[112:115]
	v_mfma_f32_16x16x32_bf16 v[108:111], v[204:207], v[174:177], v[108:111]
	v_mfma_f32_16x16x32_bf16 v[104:107], v[204:207], v[182:185], v[104:107]
	v_mfma_f32_16x16x32_bf16 v[100:103], v[212:215], v[174:177], v[100:103]
	v_mfma_f32_16x16x32_bf16 v[96:99], v[212:215], v[182:185], v[96:99]
	v_mfma_f32_16x16x32_bf16 v[124:127], v[190:193], v[178:181], v[124:127]
	v_mfma_f32_16x16x32_bf16 v[120:123], v[190:193], v[186:189], v[120:123]
	v_mfma_f32_16x16x32_bf16 v[116:119], v[200:203], v[178:181], v[116:119]
	v_mfma_f32_16x16x32_bf16 v[112:115], v[200:203], v[186:189], v[112:115]
	v_mfma_f32_16x16x32_bf16 v[108:111], v[208:211], v[178:181], v[108:111]
	v_mfma_f32_16x16x32_bf16 v[104:107], v[208:211], v[186:189], v[104:107]
	v_mfma_f32_16x16x32_bf16 v[100:103], v[216:219], v[178:181], v[100:103]
	v_mfma_f32_16x16x32_bf16 v[96:99], v[216:219], v[186:189], v[96:99]
	s_barrier
	v_add_u32_e32 v236, s66, v136
	s_add_i32 m0, s100, 0x10000
	ds_read_b128 v[220:223], v155
	ds_read_b128 v[224:227], v155 offset:1024
	ds_read_b128 v[228:231], v155 offset:2048
	ds_read_b128 v[232:235], v155 offset:3072
	global_load_lds_dwordx4 v236, s[86:87]
	v_add_u32_e32 v236, s66, v134
	s_add_i32 m0, s100, 0x12000
	s_nop 0
	global_load_lds_dwordx4 v236, s[86:87]
	s_barrier
	s_waitcnt lgkmcnt(0)
	v_mfma_f32_16x16x32_bf16 v[92:95], v[160:163], v[220:223], v[92:95]
	v_mfma_f32_16x16x32_bf16 v[88:91], v[160:163], v[228:231], v[88:91]
	v_mfma_f32_16x16x32_bf16 v[84:87], v[196:199], v[220:223], v[84:87]
	v_mfma_f32_16x16x32_bf16 v[80:83], v[196:199], v[228:231], v[80:83]
	v_mfma_f32_16x16x32_bf16 v[76:79], v[204:207], v[220:223], v[76:79]
	v_mfma_f32_16x16x32_bf16 v[72:75], v[204:207], v[228:231], v[72:75]
	v_mfma_f32_16x16x32_bf16 v[68:71], v[212:215], v[220:223], v[68:71]
	v_mfma_f32_16x16x32_bf16 v[64:67], v[212:215], v[228:231], v[64:67]
	v_mfma_f32_16x16x32_bf16 v[92:95], v[190:193], v[224:227], v[92:95]
	v_mfma_f32_16x16x32_bf16 v[88:91], v[190:193], v[232:235], v[88:91]
	v_mfma_f32_16x16x32_bf16 v[84:87], v[200:203], v[224:227], v[84:87]
	v_mfma_f32_16x16x32_bf16 v[80:83], v[200:203], v[232:235], v[80:83]
	v_mfma_f32_16x16x32_bf16 v[76:79], v[208:211], v[224:227], v[76:79]
	v_mfma_f32_16x16x32_bf16 v[72:75], v[208:211], v[232:235], v[72:75]
	v_mfma_f32_16x16x32_bf16 v[68:71], v[216:219], v[224:227], v[68:71]
	v_mfma_f32_16x16x32_bf16 v[64:67], v[216:219], v[232:235], v[64:67]
	v_add_u32_e32 v160, s60, v140
	s_mov_b32 m0, s100
	s_barrier
	ds_read_b128 v[190:193], v147 offset:16384
	ds_read_b128 v[196:199], v147 offset:17408
	ds_read_b128 v[200:203], v146 offset:16384
	ds_read_b128 v[204:207], v146 offset:17408
	ds_read_b128 v[208:211], v145 offset:16384
	ds_read_b128 v[212:215], v145 offset:17408
	ds_read_b128 v[216:219], v144 offset:16384
	ds_read_b128 v[236:239], v144 offset:17408
	global_load_lds_dwordx4 v160, s[86:87]
	v_add_u32_e32 v162, s60, v138
	s_add_i32 m0, s100, 0x2000
	s_nop 0
	global_load_lds_dwordx4 v162, s[86:87]
	s_barrier
	s_waitcnt lgkmcnt(0)
	v_mfma_f32_16x16x32_bf16 v[60:63], v[190:193], v[174:177], v[60:63]
	v_mfma_f32_16x16x32_bf16 v[56:59], v[190:193], v[182:185], v[56:59]
	v_mfma_f32_16x16x32_bf16 v[52:55], v[200:203], v[174:177], v[52:55]
	v_mfma_f32_16x16x32_bf16 v[48:51], v[200:203], v[182:185], v[48:51]
	v_mfma_f32_16x16x32_bf16 v[44:47], v[208:211], v[174:177], v[44:47]
	v_mfma_f32_16x16x32_bf16 v[40:43], v[208:211], v[182:185], v[40:43]
	v_mfma_f32_16x16x32_bf16 v[36:39], v[216:219], v[174:177], v[36:39]
	v_mfma_f32_16x16x32_bf16 v[32:35], v[216:219], v[182:185], v[32:35]
	v_mfma_f32_16x16x32_bf16 v[60:63], v[196:199], v[178:181], v[60:63]
	v_mfma_f32_16x16x32_bf16 v[56:59], v[196:199], v[186:189], v[56:59]
	v_mfma_f32_16x16x32_bf16 v[52:55], v[204:207], v[178:181], v[52:55]
	v_mfma_f32_16x16x32_bf16 v[48:51], v[204:207], v[186:189], v[48:51]
	v_mfma_f32_16x16x32_bf16 v[44:47], v[212:215], v[178:181], v[44:47]
	v_mfma_f32_16x16x32_bf16 v[40:43], v[212:215], v[186:189], v[40:43]
	v_mfma_f32_16x16x32_bf16 v[36:39], v[236:239], v[178:181], v[36:39]
	v_mfma_f32_16x16x32_bf16 v[32:35], v[236:239], v[186:189], v[32:35]
	s_barrier
	v_add_u32_e32 v162, s70, v136
	s_add_i32 m0, s100, 0x14000
	v_add_u32_e32 v174, s70, v134
	global_load_lds_dwordx4 v162, s[86:87]
	s_nop 0
	s_add_i32 m0, s100, 0x16000
	s_nop 0
	global_load_lds_dwordx4 v174, s[86:87]
	s_waitcnt vmcnt(6)
	s_barrier
; #define P8_STAGE(P,BASE,br,kt) do{const bfr* _ub=(BASE)+((long)(br)*K+(long)(kt)*BK); \
;     __builtin_amdgcn_global_load_lds((const unsigned*)(_ub+so0),(unsigned*)((char*)(P)+wid*1024),16,0,0); \
;     __builtin_amdgcn_global_load_lds((const unsigned*)(_ub+so1),(unsigned*)((char*)(P)+wid*1024+8192),16,0,0);}while(0)
; #define P8_LDA(dst,b,h) _Pragma("unroll") for(int m=0;m<4;++m) _Pragma("unroll") for(int k=0;k<2;++k) \
;     dst[m][k]=*reinterpret_cast<const bf16x8*>((char*)P8_SA(b,h)+lds_byte(wr*64+m*16+fr,k*32+fq*8))
; #define P8_LDB(dst,b,h) _Pragma("unroll") for(int n=0;n<2;++n) _Pragma("unroll") for(int k=0;k<2;++k) \
;     dst[n][k]=*reinterpret_cast<const bf16x8*>((char*)P8_SB(b,h)+lds_byte(wc*32+n*16+fr,k*32+fq*8))
; #define P8_MMA(ai,bj,At,Bt) do{__builtin_amdgcn_s_setprio(1); \
;     _Pragma("unroll") for(int m=0;m<4;++m) _Pragma("unroll") for(int n=0;n<2;++n) _Pragma("unroll") for(int k=0;k<2;++k) \
;       acc[ai][bj][m][n]=__builtin_amdgcn_mfma_f32_16x16x32_bf16(At[m][k],Bt[n][k],acc[ai][bj][m][n],0,0,0); \
;     __builtin_amdgcn_s_setprio(0);}while(0)
; #define P8_WAIT_V(n) asm volatile("s_waitcnt vmcnt(" #n ")":::"memory")
; #define P8_WAIT_L(n) asm volatile("s_waitcnt lgkmcnt(" #n ")":::"memory")
; #define P8_BAR __builtin_amdgcn_s_barrier()
; #define P8_SCHED __builtin_amdgcn_sched_barrier(0)
; template <class EPI>
; DEVI void gemm8_tile(const bfr* __restrict__ A, const bfr* __restrict__ Bt, int K, int brow, int bcol, int nbrow, int nbcol, char* shmc, EPI epi) {
;     ...
;     P8_WAIT_V(6); P8_BAR; P8_MMA(1,1,At,B1); P8_BAR;
;     P8_LDB(B0,1,0); P8_SCHED; P8_LDA(At,1,0); P8_STAGE(P8_SA(0,1),A,brow+128,t+2);
;     P8_WAIT_L(8); P8_BAR; P8_WAIT_L(0); P8_MMA(0,0,At,B0); P8_BAR; P8_SCHED;
;     P8_LDB(B1,1,1); P8_STAGE(P8_SB(1,0),Bt,bcol,t+3);
;     P8_BAR; P8_WAIT_L(0); P8_MMA(0,1,At,B1); P8_BAR;
;     P8_LDA(At,1,1); P8_STAGE(P8_SA(1,0),A,brow,t+3);
	v_mfma_f32_16x16x32_bf16 v[28:31], v[190:193], v[220:223], v[28:31]
	v_mfma_f32_16x16x32_bf16 v[24:27], v[190:193], v[228:231], v[24:27]
	v_mfma_f32_16x16x32_bf16 v[20:23], v[200:203], v[220:223], v[20:23]
	v_mfma_f32_16x16x32_bf16 v[16:19], v[200:203], v[228:231], v[16:19]
	v_mfma_f32_16x16x32_bf16 v[12:15], v[208:211], v[220:223], v[12:15]
	v_mfma_f32_16x16x32_bf16 v[8:11], v[208:211], v[228:231], v[8:11]
	v_mfma_f32_16x16x32_bf16 v[4:7], v[216:219], v[220:223], v[4:7]
	v_mfma_f32_16x16x32_bf16 v[0:3], v[216:219], v[228:231], v[0:3]
	v_mfma_f32_16x16x32_bf16 v[28:31], v[196:199], v[224:227], v[28:31]
	v_mfma_f32_16x16x32_bf16 v[24:27], v[196:199], v[232:235], v[24:27]
	v_mfma_f32_16x16x32_bf16 v[20:23], v[204:207], v[224:227], v[20:23]
	v_mfma_f32_16x16x32_bf16 v[16:19], v[204:207], v[232:235], v[16:19]
	v_mfma_f32_16x16x32_bf16 v[12:15], v[212:215], v[224:227], v[12:15]
	v_mfma_f32_16x16x32_bf16 v[8:11], v[212:215], v[232:235], v[8:11]
	v_mfma_f32_16x16x32_bf16 v[4:7], v[236:239], v[224:227], v[4:7]
	v_mfma_f32_16x16x32_bf16 v[0:3], v[236:239], v[232:235], v[0:3]
	s_barrier
	ds_read_b128 v[174:177], v149
	ds_read_b128 v[178:181], v149 offset:1024
	ds_read_b128 v[182:185], v149 offset:2048
	ds_read_b128 v[186:189], v149 offset:3072
	v_add_u32_e32 v224, s72, v140
	s_add_i32 m0, s100, 0x4000
	ds_read_b128 v[190:193], v147 offset:32768
	ds_read_b128 v[196:199], v147 offset:33792
	ds_read_b128 v[200:203], v146 offset:32768
	ds_read_b128 v[204:207], v146 offset:33792
	ds_read_b128 v[208:211], v145 offset:32768
	ds_read_b128 v[212:215], v145 offset:33792
	ds_read_b128 v[216:219], v144 offset:32768
	ds_read_b128 v[220:223], v144 offset:33792
	global_load_lds_dwordx4 v224, s[86:87]
	v_add_u32_e32 v224, s72, v138
	s_add_i32 m0, s100, 0x6000
	s_nop 0
	global_load_lds_dwordx4 v224, s[86:87]
	s_waitcnt lgkmcnt(8)
	s_barrier
	s_waitcnt lgkmcnt(0)
	v_mfma_f32_16x16x32_bf16 v[124:127], v[190:193], v[174:177], v[124:127]
	v_mfma_f32_16x16x32_bf16 v[120:123], v[190:193], v[182:185], v[120:123]
	v_mfma_f32_16x16x32_bf16 v[116:119], v[200:203], v[174:177], v[116:119]
	v_mfma_f32_16x16x32_bf16 v[112:115], v[200:203], v[182:185], v[112:115]
	v_mfma_f32_16x16x32_bf16 v[108:111], v[208:211], v[174:177], v[108:111]
	v_mfma_f32_16x16x32_bf16 v[104:107], v[208:211], v[182:185], v[104:107]
	v_mfma_f32_16x16x32_bf16 v[100:103], v[216:219], v[174:177], v[100:103]
	v_mfma_f32_16x16x32_bf16 v[96:99], v[216:219], v[182:185], v[96:99]
	v_mfma_f32_16x16x32_bf16 v[124:127], v[196:199], v[178:181], v[124:127]
	v_mfma_f32_16x16x32_bf16 v[120:123], v[196:199], v[186:189], v[120:123]
	v_mfma_f32_16x16x32_bf16 v[116:119], v[204:207], v[178:181], v[116:119]
	v_mfma_f32_16x16x32_bf16 v[112:115], v[204:207], v[186:189], v[112:115]
	v_mfma_f32_16x16x32_bf16 v[108:111], v[212:215], v[178:181], v[108:111]
	v_mfma_f32_16x16x32_bf16 v[104:107], v[212:215], v[186:189], v[104:107]
	v_mfma_f32_16x16x32_bf16 v[100:103], v[220:223], v[178:181], v[100:103]
	v_mfma_f32_16x16x32_bf16 v[96:99], v[220:223], v[186:189], v[96:99]
	s_barrier
	v_add_u32_e32 v248, s74, v136
	s_add_i32 m0, s100, 0x18000
	ds_read_b128 v[224:227], v148
	ds_read_b128 v[228:231], v148 offset:1024
	ds_read_b128 v[232:235], v148 offset:2048
	ds_read_b128 v[236:239], v148 offset:3072
	global_load_lds_dwordx4 v248, s[86:87]
	v_add_u32_e32 v248, s74, v134
	s_add_i32 m0, s100, 0x1a000
	s_nop 0
	global_load_lds_dwordx4 v248, s[86:87]
	s_barrier
	s_waitcnt lgkmcnt(0)
	v_mfma_f32_16x16x32_bf16 v[92:95], v[190:193], v[224:227], v[92:95]
	v_mfma_f32_16x16x32_bf16 v[88:91], v[190:193], v[232:235], v[88:91]
	v_mfma_f32_16x16x32_bf16 v[84:87], v[200:203], v[224:227], v[84:87]
	v_mfma_f32_16x16x32_bf16 v[80:83], v[200:203], v[232:235], v[80:83]
	v_mfma_f32_16x16x32_bf16 v[76:79], v[208:211], v[224:227], v[76:79]
	v_mfma_f32_16x16x32_bf16 v[72:75], v[208:211], v[232:235], v[72:75]
	v_mfma_f32_16x16x32_bf16 v[68:71], v[216:219], v[224:227], v[68:71]
	v_mfma_f32_16x16x32_bf16 v[64:67], v[216:219], v[232:235], v[64:67]
	v_mfma_f32_16x16x32_bf16 v[92:95], v[196:199], v[228:231], v[92:95]
	v_mfma_f32_16x16x32_bf16 v[88:91], v[196:199], v[236:239], v[88:91]
	v_mfma_f32_16x16x32_bf16 v[84:87], v[204:207], v[228:231], v[84:87]
	v_mfma_f32_16x16x32_bf16 v[80:83], v[204:207], v[236:239], v[80:83]
	v_mfma_f32_16x16x32_bf16 v[76:79], v[212:215], v[228:231], v[76:79]
	v_mfma_f32_16x16x32_bf16 v[72:75], v[212:215], v[236:239], v[72:75]
	v_mfma_f32_16x16x32_bf16 v[68:71], v[220:223], v[228:231], v[68:71]
	v_mfma_f32_16x16x32_bf16 v[64:67], v[220:223], v[236:239], v[64:67]
	v_add_u32_e32 v240, s82, v140
	s_add_i32 m0, s100, 0x8000
	s_barrier
	ds_read_b128 v[190:193], v147 offset:49152
	ds_read_b128 v[196:199], v147 offset:50176
	ds_read_b128 v[200:203], v146 offset:49152
	ds_read_b128 v[204:207], v146 offset:50176
	ds_read_b128 v[208:211], v145 offset:49152
	ds_read_b128 v[212:215], v145 offset:50176
	ds_read_b128 v[216:219], v144 offset:49152
	ds_read_b128 v[220:223], v144 offset:50176
	global_load_lds_dwordx4 v240, s[86:87]
	v_add_u32_e32 v240, s82, v138
	s_add_i32 m0, s100, 0xa000
	s_nop 0
	global_load_lds_dwordx4 v240, s[86:87]
	s_barrier
; #define P8_STAGE(P,BASE,br,kt) do{const bfr* _ub=(BASE)+((long)(br)*K+(long)(kt)*BK); \
;     __builtin_amdgcn_global_load_lds((const unsigned*)(_ub+so0),(unsigned*)((char*)(P)+wid*1024),16,0,0); \
;     __builtin_amdgcn_global_load_lds((const unsigned*)(_ub+so1),(unsigned*)((char*)(P)+wid*1024+8192),16,0,0);}while(0)
; #define P8_LDA(dst,b,h) _Pragma("unroll") for(int m=0;m<4;++m) _Pragma("unroll") for(int k=0;k<2;++k) \
;     dst[m][k]=*reinterpret_cast<const bf16x8*>((char*)P8_SA(b,h)+lds_byte(wr*64+m*16+fr,k*32+fq*8))
; #define P8_LDB(dst,b,h) _Pragma("unroll") for(int n=0;n<2;++n) _Pragma("unroll") for(int k=0;k<2;++k) \
;     dst[n][k]=*reinterpret_cast<const bf16x8*>((char*)P8_SB(b,h)+lds_byte(wc*32+n*16+fr,k*32+fq*8))
; #define P8_MMA(ai,bj,At,Bt) do{__builtin_amdgcn_s_setprio(1); \
;     _Pragma("unroll") for(int m=0;m<4;++m) _Pragma("unroll") for(int n=0;n<2;++n) _Pragma("unroll") for(int k=0;k<2;++k) \
;       acc[ai][bj][m][n]=__builtin_amdgcn_mfma_f32_16x16x32_bf16(At[m][k],Bt[n][k],acc[ai][bj][m][n],0,0,0); \
;     __builtin_amdgcn_s_setprio(0);}while(0)
; #define P8_WAIT_V(n) asm volatile("s_waitcnt vmcnt(" #n ")":::"memory")
; #define P8_WAIT_L(n) asm volatile("s_waitcnt lgkmcnt(" #n ")":::"memory")
; #define P8_BAR __builtin_amdgcn_s_barrier()
; #define P8_SCHED __builtin_amdgcn_sched_barrier(0)
; template <class EPI>
; DEVI void gemm8_tile(const bfr* __restrict__ A, const bfr* __restrict__ Bt, int K, int brow, int bcol, int nbrow, int nbcol, char* shmc, EPI epi) {
;     ...
;     P8_LDA(At,1,1); P8_STAGE(P8_SA(1,0),A,brow,t+3);
;     P8_BAR; P8_WAIT_L(0); P8_MMA(1,0,At,B0); P8_BAR; P8_SCHED;
;     P8_STAGE(P8_SB(1,1),Bt,bcol+128,t+3);
;     P8_WAIT_V(6); P8_BAR; P8_MMA(1,1,At,B1); P8_BAR;
;   }
;   { P8_LDB(B0,0,0); P8_LDA(At,0,0); P8_STAGE(P8_SA(1,1),A,brow+128,nt-1);
;     P8_BAR; P8_WAIT_L(0); P8_MMA(0,0,At,B0); P8_BAR;
;     P8_LDB(B1,0,1); P8_BAR; P8_WAIT_L(0); P8_MMA(0,1,At,B1); P8_BAR;
	s_waitcnt lgkmcnt(0)
	v_mfma_f32_16x16x32_bf16 v[60:63], v[190:193], v[174:177], v[60:63]
	v_mfma_f32_16x16x32_bf16 v[56:59], v[190:193], v[182:185], v[56:59]
	v_mfma_f32_16x16x32_bf16 v[52:55], v[200:203], v[174:177], v[52:55]
	v_mfma_f32_16x16x32_bf16 v[48:51], v[200:203], v[182:185], v[48:51]
	v_mfma_f32_16x16x32_bf16 v[44:47], v[208:211], v[174:177], v[44:47]
	v_mfma_f32_16x16x32_bf16 v[40:43], v[208:211], v[182:185], v[40:43]
	v_mfma_f32_16x16x32_bf16 v[36:39], v[216:219], v[174:177], v[36:39]
	v_mfma_f32_16x16x32_bf16 v[32:35], v[216:219], v[182:185], v[32:35]
	v_mfma_f32_16x16x32_bf16 v[60:63], v[196:199], v[178:181], v[60:63]
	v_mfma_f32_16x16x32_bf16 v[56:59], v[196:199], v[186:189], v[56:59]
	v_mfma_f32_16x16x32_bf16 v[52:55], v[204:207], v[178:181], v[52:55]
	v_mfma_f32_16x16x32_bf16 v[48:51], v[204:207], v[186:189], v[48:51]
	v_mfma_f32_16x16x32_bf16 v[44:47], v[212:215], v[178:181], v[44:47]
	v_mfma_f32_16x16x32_bf16 v[40:43], v[212:215], v[186:189], v[40:43]
	v_mfma_f32_16x16x32_bf16 v[36:39], v[220:223], v[178:181], v[36:39]
	v_mfma_f32_16x16x32_bf16 v[32:35], v[220:223], v[186:189], v[32:35]
	s_barrier
	v_add_u32_e32 v174, s78, v136
	s_add_i32 m0, s100, 0x1c000
	s_nop 0
	global_load_lds_dwordx4 v174, s[86:87]
	v_add_u32_e32 v174, s78, v134
	s_add_i32 m0, s100, 0x1e000
	s_nop 0
	global_load_lds_dwordx4 v174, s[86:87]
	s_waitcnt vmcnt(6)
	s_barrier
	v_mfma_f32_16x16x32_bf16 v[28:31], v[190:193], v[224:227], v[28:31]
	v_mfma_f32_16x16x32_bf16 v[24:27], v[190:193], v[232:235], v[24:27]
	v_mfma_f32_16x16x32_bf16 v[20:23], v[200:203], v[224:227], v[20:23]
	v_mfma_f32_16x16x32_bf16 v[16:19], v[200:203], v[232:235], v[16:19]
	v_mfma_f32_16x16x32_bf16 v[12:15], v[208:211], v[224:227], v[12:15]
	v_mfma_f32_16x16x32_bf16 v[8:11], v[208:211], v[232:235], v[8:11]
	v_mfma_f32_16x16x32_bf16 v[4:7], v[216:219], v[224:227], v[4:7]
	v_mfma_f32_16x16x32_bf16 v[0:3], v[216:219], v[232:235], v[0:3]
	v_mfma_f32_16x16x32_bf16 v[28:31], v[196:199], v[228:231], v[28:31]
	v_mfma_f32_16x16x32_bf16 v[24:27], v[196:199], v[236:239], v[24:27]
	v_mfma_f32_16x16x32_bf16 v[20:23], v[204:207], v[228:231], v[20:23]
	v_mfma_f32_16x16x32_bf16 v[16:19], v[204:207], v[236:239], v[16:19]
	v_mfma_f32_16x16x32_bf16 v[12:15], v[212:215], v[228:231], v[12:15]
	v_mfma_f32_16x16x32_bf16 v[8:11], v[212:215], v[236:239], v[8:11]
	v_mfma_f32_16x16x32_bf16 v[4:7], v[220:223], v[228:231], v[4:7]
	v_mfma_f32_16x16x32_bf16 v[0:3], v[220:223], v[236:239], v[0:3]
	s_add_i32 s0, s0, 2
	v_lshl_add_u64 v[134:135], v[134:135], 0, s[80:81]
	v_lshl_add_u64 v[136:137], v[136:137], 0, s[80:81]
	v_lshl_add_u64 v[138:139], v[138:139], 0, s[80:81]
	s_cmp_lt_u32 s0, 28
	v_lshl_add_u64 v[140:141], v[140:141], 0, s[80:81]
	s_barrier
	s_cbranch_scc1 .LBB0_85
	v_add_u32_e32 v171, 0xc000, v143
	v_add_u32_e32 v172, 0xe000, v143
	v_add_u32_e32 v158, 0x10000, v143
	v_add_u32_e32 v159, 0x12000, v143
	v_add_u32_e32 v160, 0x2000, v143
	v_add_u32_e32 v161, 0x14000, v143
	v_add_u32_e32 v162, 0x16000, v143
	v_add_u32_e32 v163, 0x4000, v143
	v_add_u32_e32 v170, 0x6000, v143
	s_or_b32 s0, s8, 0x80
	s_ashr_i32 s1, s0, 31
	s_lshl_b64 s[0:1], s[0:1], 12
	s_add_u32 s0, s28, s0
	s_addc_u32 s1, s29, s1
	ds_read_b128 v[134:137], v157
	ds_read_b128 v[138:141], v157 offset:1024
	ds_read_b128 v[150:153], v157 offset:2048
	ds_read_b128 v[174:177], v157 offset:3072
	ds_read_b128 v[178:181], v147
	ds_read_b128 v[182:185], v147 offset:1024
	ds_read_b128 v[186:189], v146
	ds_read_b128 v[190:193], v146 offset:1024
	ds_read_b128 v[196:199], v145
	ds_read_b128 v[200:203], v145 offset:1024
	ds_read_b128 v[204:207], v144
	ds_read_b128 v[208:211], v144 offset:1024
	v_lshl_add_u64 v[156:157], v[166:167], 1, s[0:1]
	s_mov_b64 s[54:55], 0xf80
	v_lshl_add_u64 v[156:157], v[156:157], 0, s[54:55]
	s_add_i32 m0, s100, 0xc000
	v_lshl_add_u64 v[132:133], v[132:133], 1, s[0:1]
	global_load_lds_dwordx4 v[156:157], off
	v_lshl_add_u64 v[132:133], v[132:133], 0, s[54:55]
	s_add_i32 m0, s100, 0xe000
	s_nop 0
	global_load_lds_dwordx4 v[132:133], off
	s_barrier
	s_waitcnt lgkmcnt(0)
	s_setprio 1
	s_waitcnt lgkmcnt(0)
	v_mfma_f32_16x16x32_bf16 v[124:127], v[178:181], v[134:137], v[124:127]
	v_mfma_f32_16x16x32_bf16 v[116:119], v[186:189], v[134:137], v[116:119]
	v_mfma_f32_16x16x32_bf16 v[112:115], v[186:189], v[150:153], v[112:115]
	v_mfma_f32_16x16x32_bf16 v[96:99], v[204:207], v[150:153], v[96:99]
	v_mfma_f32_16x16x32_bf16 v[124:127], v[182:185], v[138:141], v[124:127]
	v_mfma_f32_16x16x32_bf16 v[120:123], v[178:181], v[150:153], v[120:123]
	v_mfma_f32_16x16x32_bf16 v[116:119], v[190:193], v[138:141], v[116:119]
	v_mfma_f32_16x16x32_bf16 v[112:115], v[190:193], v[174:177], v[112:115]
	v_mfma_f32_16x16x32_bf16 v[108:111], v[196:199], v[134:137], v[108:111]
	v_mfma_f32_16x16x32_bf16 v[104:107], v[196:199], v[150:153], v[104:107]
	v_mfma_f32_16x16x32_bf16 v[100:103], v[204:207], v[134:137], v[100:103]
	v_mfma_f32_16x16x32_bf16 v[96:99], v[208:211], v[174:177], v[96:99]
	v_mfma_f32_16x16x32_bf16 v[212:215], v[182:185], v[174:177], v[120:123]
	v_mfma_f32_16x16x32_bf16 v[216:219], v[200:203], v[138:141], v[108:111]
	v_mfma_f32_16x16x32_bf16 v[220:223], v[200:203], v[174:177], v[104:107]
	v_mfma_f32_16x16x32_bf16 v[224:227], v[208:211], v[138:141], v[100:103]
	s_setprio 0
	s_barrier
	s_nop 0
	ds_read_b128 v[100:103], v155
	ds_read_b128 v[104:107], v155 offset:1024
	ds_read_b128 v[108:111], v155 offset:2048
	ds_read_b128 v[120:123], v155 offset:3072
	s_barrier
; #define P8_LDA(dst,b,h) _Pragma("unroll") for(int m=0;m<4;++m) _Pragma("unroll") for(int k=0;k<2;++k) \
;     dst[m][k]=*reinterpret_cast<const bf16x8*>((char*)P8_SA(b,h)+lds_byte(wr*64+m*16+fr,k*32+fq*8))
; #define P8_LDB(dst,b,h) _Pragma("unroll") for(int n=0;n<2;++n) _Pragma("unroll") for(int k=0;k<2;++k) \
;     dst[n][k]=*reinterpret_cast<const bf16x8*>((char*)P8_SB(b,h)+lds_byte(wc*32+n*16+fr,k*32+fq*8))
; #define P8_MMA(ai,bj,At,Bt) do{__builtin_amdgcn_s_setprio(1); \
;     _Pragma("unroll") for(int m=0;m<4;++m) _Pragma("unroll") for(int n=0;n<2;++n) _Pragma("unroll") for(int k=0;k<2;++k) \
;       acc[ai][bj][m][n]=__builtin_amdgcn_mfma_f32_16x16x32_bf16(At[m][k],Bt[n][k],acc[ai][bj][m][n],0,0,0); \
;     __builtin_amdgcn_s_setprio(0);}while(0)
; #define P8_WAIT_V(n) asm volatile("s_waitcnt vmcnt(" #n ")":::"memory")
; #define P8_WAIT_L(n) asm volatile("s_waitcnt lgkmcnt(" #n ")":::"memory")
; #define P8_BAR __builtin_amdgcn_s_barrier()
; template <class EPI>
; DEVI void gemm8_tile(const bfr* __restrict__ A, const bfr* __restrict__ Bt, int K, int brow, int bcol, int nbrow, int nbcol, char* shmc, EPI epi) {
;     ...
;     P8_LDB(B1,0,1); P8_BAR; P8_WAIT_L(0); P8_MMA(0,1,At,B1); P8_BAR;
;     P8_LDA(At,0,1); P8_WAIT_V(4); P8_BAR; P8_WAIT_L(0); P8_MMA(1,0,At,B0); P8_MMA(1,1,At,B1); P8_BAR; }
;   { P8_LDB(B0,1,0); P8_LDA(At,1,0); P8_WAIT_V(2); P8_BAR; P8_WAIT_L(0); P8_MMA(0,0,At,B0); P8_BAR;
	s_waitcnt lgkmcnt(0)
	s_setprio 1
	s_waitcnt lgkmcnt(0)
	v_mfma_f32_16x16x32_bf16 v[92:95], v[178:181], v[100:103], v[92:95]
	v_mfma_f32_16x16x32_bf16 v[84:87], v[186:189], v[100:103], v[84:87]
	v_mfma_f32_16x16x32_bf16 v[80:83], v[186:189], v[108:111], v[80:83]
	v_mfma_f32_16x16x32_bf16 v[64:67], v[204:207], v[108:111], v[64:67]
	v_mfma_f32_16x16x32_bf16 v[92:95], v[182:185], v[104:107], v[92:95]
	v_mfma_f32_16x16x32_bf16 v[88:91], v[178:181], v[108:111], v[88:91]
	v_mfma_f32_16x16x32_bf16 v[84:87], v[190:193], v[104:107], v[84:87]
	v_mfma_f32_16x16x32_bf16 v[80:83], v[190:193], v[120:123], v[80:83]
	v_mfma_f32_16x16x32_bf16 v[76:79], v[196:199], v[100:103], v[76:79]
	v_mfma_f32_16x16x32_bf16 v[72:75], v[196:199], v[108:111], v[72:75]
	v_mfma_f32_16x16x32_bf16 v[68:71], v[204:207], v[100:103], v[68:71]
	v_mfma_f32_16x16x32_bf16 v[64:67], v[208:211], v[120:123], v[64:67]
	v_mfma_f32_16x16x32_bf16 v[154:157], v[182:185], v[120:123], v[88:91]
	v_mfma_f32_16x16x32_bf16 v[178:181], v[200:203], v[104:107], v[76:79]
	v_mfma_f32_16x16x32_bf16 v[182:185], v[200:203], v[120:123], v[72:75]
	v_mfma_f32_16x16x32_bf16 v[186:189], v[208:211], v[104:107], v[68:71]
	s_setprio 0
	s_barrier
	s_nop 0
	ds_read_b128 v[68:71], v147 offset:16384
	ds_read_b128 v[72:75], v147 offset:17408
	ds_read_b128 v[76:79], v146 offset:16384
	ds_read_b128 v[88:91], v146 offset:17408
	ds_read_b128 v[190:193], v145 offset:16384
	ds_read_b128 v[196:199], v145 offset:17408
	ds_read_b128 v[200:203], v144 offset:16384
	ds_read_b128 v[204:207], v144 offset:17408
	s_waitcnt vmcnt(4)
	s_barrier
	s_waitcnt lgkmcnt(0)
	s_setprio 1
	s_waitcnt lgkmcnt(0)
	v_mfma_f32_16x16x32_bf16 v[60:63], v[68:71], v[134:137], v[60:63]
	v_mfma_f32_16x16x32_bf16 v[52:55], v[76:79], v[134:137], v[52:55]
	v_mfma_f32_16x16x32_bf16 v[48:51], v[76:79], v[150:153], v[48:51]
	v_mfma_f32_16x16x32_bf16 v[32:35], v[200:203], v[150:153], v[32:35]
	v_mfma_f32_16x16x32_bf16 v[60:63], v[72:75], v[138:141], v[60:63]
	v_mfma_f32_16x16x32_bf16 v[56:59], v[68:71], v[150:153], v[56:59]
	v_mfma_f32_16x16x32_bf16 v[52:55], v[88:91], v[138:141], v[52:55]
	v_mfma_f32_16x16x32_bf16 v[48:51], v[88:91], v[174:177], v[48:51]
	v_mfma_f32_16x16x32_bf16 v[44:47], v[190:193], v[134:137], v[44:47]
	v_mfma_f32_16x16x32_bf16 v[40:43], v[190:193], v[150:153], v[40:43]
	v_mfma_f32_16x16x32_bf16 v[36:39], v[200:203], v[134:137], v[36:39]
	v_mfma_f32_16x16x32_bf16 v[32:35], v[204:207], v[174:177], v[32:35]
	v_mfma_f32_16x16x32_bf16 v[208:211], v[72:75], v[174:177], v[56:59]
	v_mfma_f32_16x16x32_bf16 v[228:231], v[196:199], v[138:141], v[44:47]
	v_mfma_f32_16x16x32_bf16 v[232:235], v[196:199], v[174:177], v[40:43]
	v_mfma_f32_16x16x32_bf16 v[132:135], v[204:207], v[138:141], v[36:39]
	s_setprio 0
	s_setprio 1
	v_mfma_f32_16x16x32_bf16 v[28:31], v[68:71], v[100:103], v[28:31]
	v_mfma_f32_16x16x32_bf16 v[20:23], v[76:79], v[100:103], v[20:23]
	v_mfma_f32_16x16x32_bf16 v[16:19], v[76:79], v[108:111], v[16:19]
	v_mfma_f32_16x16x32_bf16 v[0:3], v[200:203], v[108:111], v[0:3]
	v_mfma_f32_16x16x32_bf16 v[28:31], v[72:75], v[104:107], v[28:31]
	v_mfma_f32_16x16x32_bf16 v[24:27], v[68:71], v[108:111], v[24:27]
	v_mfma_f32_16x16x32_bf16 v[20:23], v[88:91], v[104:107], v[20:23]
	v_mfma_f32_16x16x32_bf16 v[16:19], v[88:91], v[120:123], v[16:19]
	v_mfma_f32_16x16x32_bf16 v[12:15], v[190:193], v[100:103], v[12:15]
	v_mfma_f32_16x16x32_bf16 v[8:11], v[190:193], v[108:111], v[8:11]
	v_mfma_f32_16x16x32_bf16 v[4:7], v[200:203], v[100:103], v[4:7]
	v_mfma_f32_16x16x32_bf16 v[0:3], v[204:207], v[120:123], v[0:3]
	v_mfma_f32_16x16x32_bf16 v[136:139], v[72:75], v[120:123], v[24:27]
	v_mfma_f32_16x16x32_bf16 v[150:153], v[196:199], v[104:107], v[12:15]
	v_mfma_f32_16x16x32_bf16 v[172:175], v[196:199], v[120:123], v[8:11]
	v_mfma_f32_16x16x32_bf16 v[190:193], v[204:207], v[104:107], v[4:7]
	s_setprio 0
	s_barrier
	s_nop 0
	ds_read_b128 v[4:7], v149
	ds_read_b128 v[8:11], v149 offset:1024
	ds_read_b128 v[12:15], v149 offset:2048
	ds_read_b128 v[24:27], v149 offset:3072
	ds_read_b128 v[36:39], v147 offset:32768
	ds_read_b128 v[40:43], v147 offset:33792
	ds_read_b128 v[44:47], v146 offset:32768
	ds_read_b128 v[56:59], v146 offset:33792
	ds_read_b128 v[68:71], v145 offset:32768
	ds_read_b128 v[196:199], v145 offset:33792
	ds_read_b128 v[200:203], v144 offset:32768
	ds_read_b128 v[204:207], v144 offset:33792
	s_waitcnt vmcnt(2)
	s_barrier
; #define P8_LDA(dst,b,h) _Pragma("unroll") for(int m=0;m<4;++m) _Pragma("unroll") for(int k=0;k<2;++k) \
;     dst[m][k]=*reinterpret_cast<const bf16x8*>((char*)P8_SA(b,h)+lds_byte(wr*64+m*16+fr,k*32+fq*8))
; #define P8_LDB(dst,b,h) _Pragma("unroll") for(int n=0;n<2;++n) _Pragma("unroll") for(int k=0;k<2;++k) \
;     dst[n][k]=*reinterpret_cast<const bf16x8*>((char*)P8_SB(b,h)+lds_byte(wc*32+n*16+fr,k*32+fq*8))
; #define P8_MMA(ai,bj,At,Bt) do{__builtin_amdgcn_s_setprio(1); \
;     _Pragma("unroll") for(int m=0;m<4;++m) _Pragma("unroll") for(int n=0;n<2;++n) _Pragma("unroll") for(int k=0;k<2;++k) \
;       acc[ai][bj][m][n]=__builtin_amdgcn_mfma_f32_16x16x32_bf16(At[m][k],Bt[n][k],acc[ai][bj][m][n],0,0,0); \
;     __builtin_amdgcn_s_setprio(0);}while(0)
; #define P8_WAIT_V(n) asm volatile("s_waitcnt vmcnt(" #n ")":::"memory")
; #define P8_WAIT_L(n) asm volatile("s_waitcnt lgkmcnt(" #n ")":::"memory")
; #define P8_BAR __builtin_amdgcn_s_barrier()
; template <class EPI>
; DEVI void gemm8_tile(const bfr* __restrict__ A, const bfr* __restrict__ Bt, int K, int brow, int bcol, int nbrow, int nbcol, char* shmc, EPI epi) {
;     ...
;   { P8_LDB(B0,1,0); P8_LDA(At,1,0); P8_WAIT_V(2); P8_BAR; P8_WAIT_L(0); P8_MMA(0,0,At,B0); P8_BAR;
;     P8_LDB(B1,1,1); P8_WAIT_V(0); P8_BAR; P8_WAIT_L(0); P8_MMA(0,1,At,B1); P8_BAR;
;     P8_LDA(At,1,1); P8_BAR; P8_WAIT_L(0); P8_MMA(1,0,At,B0); P8_MMA(1,1,At,B1); P8_BAR; }
;   if(wr==0)P8_BAR;
	s_waitcnt lgkmcnt(0)
	s_setprio 1
	s_waitcnt lgkmcnt(0)
	v_mfma_f32_16x16x32_bf16 v[72:75], v[36:39], v[4:7], v[124:127]
	v_mfma_f32_16x16x32_bf16 v[120:123], v[40:43], v[8:11], v[72:75]
	v_mfma_f32_16x16x32_bf16 v[72:75], v[36:39], v[12:15], v[212:215]
	v_mfma_f32_16x16x32_bf16 v[104:107], v[40:43], v[24:27], v[72:75]
	v_mfma_f32_16x16x32_bf16 v[72:75], v[44:47], v[4:7], v[116:119]
	v_mfma_f32_16x16x32_bf16 v[124:127], v[56:59], v[8:11], v[72:75]
	v_mfma_f32_16x16x32_bf16 v[72:75], v[44:47], v[12:15], v[112:115]
	v_mfma_f32_16x16x32_bf16 v[108:111], v[56:59], v[24:27], v[72:75]
	v_mfma_f32_16x16x32_bf16 v[72:75], v[68:71], v[4:7], v[216:219]
	v_mfma_f32_16x16x32_bf16 v[112:115], v[196:199], v[8:11], v[72:75]
	v_mfma_f32_16x16x32_bf16 v[72:75], v[68:71], v[12:15], v[220:223]
	v_mfma_f32_16x16x32_bf16 v[100:103], v[196:199], v[24:27], v[72:75]
	v_mfma_f32_16x16x32_bf16 v[72:75], v[200:203], v[4:7], v[224:227]
	v_mfma_f32_16x16x32_bf16 v[116:119], v[204:207], v[8:11], v[72:75]
	v_mfma_f32_16x16x32_bf16 v[72:75], v[200:203], v[12:15], v[96:99]
	v_mfma_f32_16x16x32_bf16 v[96:99], v[204:207], v[24:27], v[72:75]
	s_setprio 0
	s_barrier
	ds_read_b128 v[212:215], v148
	ds_read_b128 v[216:219], v148 offset:1024
	ds_read_b128 v[220:223], v148 offset:2048
	ds_read_b128 v[224:227], v148 offset:3072
	s_waitcnt vmcnt(0)
	s_barrier
	s_waitcnt lgkmcnt(0)
	s_setprio 1
	s_waitcnt lgkmcnt(0)
	v_mfma_f32_16x16x32_bf16 v[72:75], v[36:39], v[212:215], v[92:95]
	v_mfma_f32_16x16x32_bf16 v[36:39], v[36:39], v[220:223], v[154:157]
	v_mfma_f32_16x16x32_bf16 v[88:91], v[40:43], v[216:219], v[72:75]
	v_mfma_f32_16x16x32_bf16 v[72:75], v[40:43], v[224:227], v[36:39]
	v_mfma_f32_16x16x32_bf16 v[36:39], v[44:47], v[212:215], v[84:87]
	v_mfma_f32_16x16x32_bf16 v[92:95], v[56:59], v[216:219], v[36:39]
	v_mfma_f32_16x16x32_bf16 v[36:39], v[44:47], v[220:223], v[80:83]
	v_mfma_f32_16x16x32_bf16 v[76:79], v[56:59], v[224:227], v[36:39]
	v_mfma_f32_16x16x32_bf16 v[36:39], v[68:71], v[212:215], v[178:181]
	v_mfma_f32_16x16x32_bf16 v[80:83], v[196:199], v[216:219], v[36:39]
	v_mfma_f32_16x16x32_bf16 v[36:39], v[68:71], v[220:223], v[182:185]
	v_mfma_f32_16x16x32_bf16 v[68:71], v[196:199], v[224:227], v[36:39]
	v_mfma_f32_16x16x32_bf16 v[36:39], v[200:203], v[212:215], v[186:189]
	v_mfma_f32_16x16x32_bf16 v[84:87], v[204:207], v[216:219], v[36:39]
	v_mfma_f32_16x16x32_bf16 v[36:39], v[200:203], v[220:223], v[64:67]
	v_mfma_f32_16x16x32_bf16 v[64:67], v[204:207], v[224:227], v[36:39]
	s_setprio 0
	s_barrier
	ds_read_b128 v[154:157], v147 offset:49152
	ds_read_b128 v[176:179], v147 offset:50176
	ds_read_b128 v[180:183], v146 offset:49152
	ds_read_b128 v[146:149], v146 offset:50176
	ds_read_b128 v[184:187], v145 offset:49152
	ds_read_b128 v[196:199], v145 offset:50176
	ds_read_b128 v[200:203], v144 offset:49152
	ds_read_b128 v[204:207], v144 offset:50176
	s_barrier
	s_waitcnt lgkmcnt(0)
	s_setprio 1
	s_waitcnt lgkmcnt(0)
	v_mfma_f32_16x16x32_bf16 v[36:39], v[154:157], v[4:7], v[60:63]
	v_mfma_f32_16x16x32_bf16 v[56:59], v[176:179], v[8:11], v[36:39]
	v_mfma_f32_16x16x32_bf16 v[36:39], v[154:157], v[12:15], v[208:211]
	v_mfma_f32_16x16x32_bf16 v[40:43], v[176:179], v[24:27], v[36:39]
	v_mfma_f32_16x16x32_bf16 v[36:39], v[180:183], v[4:7], v[52:55]
	v_mfma_f32_16x16x32_bf16 v[60:63], v[146:149], v[8:11], v[36:39]
	v_mfma_f32_16x16x32_bf16 v[36:39], v[180:183], v[12:15], v[48:51]
	v_mfma_f32_16x16x32_bf16 v[44:47], v[146:149], v[24:27], v[36:39]
	v_mfma_f32_16x16x32_bf16 v[36:39], v[184:187], v[4:7], v[228:231]
	v_mfma_f32_16x16x32_bf16 v[4:7], v[200:203], v[4:7], v[132:135]
	v_mfma_f32_16x16x32_bf16 v[48:51], v[196:199], v[8:11], v[36:39]
	v_mfma_f32_16x16x32_bf16 v[36:39], v[184:187], v[12:15], v[232:235]
	v_mfma_f32_16x16x32_bf16 v[52:55], v[204:207], v[8:11], v[4:7]
	v_mfma_f32_16x16x32_bf16 v[4:7], v[200:203], v[12:15], v[32:35]
	v_mfma_f32_16x16x32_bf16 v[36:39], v[196:199], v[24:27], v[36:39]
	v_mfma_f32_16x16x32_bf16 v[32:35], v[204:207], v[24:27], v[4:7]
	s_setprio 0
	s_setprio 1
	v_mfma_f32_16x16x32_bf16 v[4:7], v[154:157], v[212:215], v[28:31]
	v_mfma_f32_16x16x32_bf16 v[24:27], v[176:179], v[216:219], v[4:7]
	v_mfma_f32_16x16x32_bf16 v[4:7], v[154:157], v[220:223], v[136:139]
	v_mfma_f32_16x16x32_bf16 v[8:11], v[176:179], v[224:227], v[4:7]
	v_mfma_f32_16x16x32_bf16 v[4:7], v[180:183], v[212:215], v[20:23]
	v_mfma_f32_16x16x32_bf16 v[28:31], v[146:149], v[216:219], v[4:7]
	v_mfma_f32_16x16x32_bf16 v[4:7], v[180:183], v[220:223], v[16:19]
	v_mfma_f32_16x16x32_bf16 v[12:15], v[146:149], v[224:227], v[4:7]
	v_mfma_f32_16x16x32_bf16 v[4:7], v[184:187], v[212:215], v[150:153]
	v_mfma_f32_16x16x32_bf16 v[16:19], v[196:199], v[216:219], v[4:7]
	v_mfma_f32_16x16x32_bf16 v[4:7], v[184:187], v[220:223], v[172:175]
	v_mfma_f32_16x16x32_bf16 v[20:23], v[200:203], v[212:215], v[190:193]
	v_mfma_f32_16x16x32_bf16 v[0:3], v[200:203], v[220:223], v[0:3]
	v_mfma_f32_16x16x32_bf16 v[4:7], v[196:199], v[224:227], v[4:7]
	v_mfma_f32_16x16x32_bf16 v[20:23], v[204:207], v[216:219], v[20:23]
	v_mfma_f32_16x16x32_bf16 v[0:3], v[204:207], v[224:227], v[0:3]
	s_setprio 0
	v_cmp_gt_u32_e32 vcc, s57, v142
	s_barrier
	s_and_saveexec_b64 s[0:1], vcc
	s_cbranch_execz .LBB0_88
	s_barrier

; #define P8_STAGE(P,BASE,br,kt) do{const bfr* _ub=(BASE)+((long)(br)*K+(long)(kt)*BK); \
;     __builtin_amdgcn_global_load_lds((const unsigned*)(_ub+so0),(unsigned*)((char*)(P)+wid*1024),16,0,0); \
;     __builtin_amdgcn_global_load_lds((const unsigned*)(_ub+so1),(unsigned*)((char*)(P)+wid*1024+8192),16,0,0);}while(0)
; #define P8_LDA(dst,b,h) _Pragma("unroll") for(int m=0;m<4;++m) _Pragma("unroll") for(int k=0;k<2;++k) \
;     dst[m][k]=*reinterpret_cast<const bf16x8*>((char*)P8_SA(b,h)+lds_byte(wr*64+m*16+fr,k*32+fq*8))
; #define P8_LDB(dst,b,h) _Pragma("unroll") for(int n=0;n<2;++n) _Pragma("unroll") for(int k=0;k<2;++k) \
;     dst[n][k]=*reinterpret_cast<const bf16x8*>((char*)P8_SB(b,h)+lds_byte(wc*32+n*16+fr,k*32+fq*8))
; #define P8_MMA(ai,bj,At,Bt) do{__builtin_amdgcn_s_setprio(1); \
;     _Pragma("unroll") for(int m=0;m<4;++m) _Pragma("unroll") for(int n=0;n<2;++n) _Pragma("unroll") for(int k=0;k<2;++k) \
;       acc[ai][bj][m][n]=__builtin_amdgcn_mfma_f32_16x16x32_bf16(At[m][k],Bt[n][k],acc[ai][bj][m][n],0,0,0); \
;     __builtin_amdgcn_s_setprio(0);}while(0)
; #define P8_WAIT_V(n) asm volatile("s_waitcnt vmcnt(" #n ")":::"memory")
; #define P8_WAIT_L(n) asm volatile("s_waitcnt lgkmcnt(" #n ")":::"memory")
; #define P8_BAR __builtin_amdgcn_s_barrier()
; #define P8_SCHED __builtin_amdgcn_sched_barrier(0)
; template <class EPI>
; DEVI void gemm8_tile(const bfr* __restrict__ A, const bfr* __restrict__ Bt, int K, int brow, int bcol, int nbrow, int nbcol, char* shmc, EPI epi) {
;     ...
;     P8_LDB(B0,0,0); P8_SCHED; P8_LDA(At,0,0); P8_STAGE(P8_SA(1,1),A,brow+128,t+1);
;     P8_WAIT_L(8); P8_BAR; P8_WAIT_L(0); P8_MMA(0,0,At,B0); P8_BAR; P8_SCHED;
;     P8_LDB(B1,0,1); P8_STAGE(P8_SB(0,0),Bt,bcol,t+2);
;     P8_BAR; P8_WAIT_L(0); P8_MMA(0,1,At,B1); P8_BAR;
;     P8_LDA(At,0,1); P8_STAGE(P8_SA(0,0),A,brow,t+2);
;     P8_BAR; P8_WAIT_L(0); P8_MMA(1,0,At,B0); P8_BAR; P8_SCHED;
;     P8_STAGE(P8_SB(0,1),Bt,bcol+128,t+2);
;     P8_WAIT_V(6); P8_BAR; P8_MMA(1,1,At,B1); P8_BAR;
.LBB0_141:
	ds_read_b128 v[174:177], v157
	ds_read_b128 v[178:181], v157 offset:1024
	ds_read_b128 v[182:185], v157 offset:2048
	ds_read_b128 v[186:189], v157 offset:3072
	v_add_u32_e32 v158, s8, v136
	s_add_i32 m0, s100, 0xc000
	ds_read_b128 v[160:163], v147
	ds_read_b128 v[190:193], v147 offset:1024
	ds_read_b128 v[196:199], v146
	ds_read_b128 v[208:211], v146 offset:1024
	ds_read_b128 v[212:215], v145
	ds_read_b128 v[216:219], v145 offset:1024
	ds_read_b128 v[220:223], v144
	ds_read_b128 v[224:227], v144 offset:1024
	global_load_lds_dwordx4 v158, s[86:87]
	v_add_u32_e32 v158, s8, v134
	s_add_i32 m0, s100, 0xe000
	s_nop 0
	global_load_lds_dwordx4 v158, s[86:87]
	s_waitcnt lgkmcnt(8)
	s_barrier
	s_waitcnt lgkmcnt(0)
	v_mfma_f32_16x16x32_bf16 v[124:127], v[160:163], v[174:177], v[124:127]
	v_mfma_f32_16x16x32_bf16 v[120:123], v[160:163], v[182:185], v[120:123]
	v_mfma_f32_16x16x32_bf16 v[116:119], v[196:199], v[174:177], v[116:119]
	v_mfma_f32_16x16x32_bf16 v[112:115], v[196:199], v[182:185], v[112:115]
	v_mfma_f32_16x16x32_bf16 v[108:111], v[212:215], v[174:177], v[108:111]
	v_mfma_f32_16x16x32_bf16 v[104:107], v[212:215], v[182:185], v[104:107]
	v_mfma_f32_16x16x32_bf16 v[100:103], v[220:223], v[174:177], v[100:103]
	v_mfma_f32_16x16x32_bf16 v[96:99], v[220:223], v[182:185], v[96:99]
	v_mfma_f32_16x16x32_bf16 v[124:127], v[190:193], v[178:181], v[124:127]
	v_mfma_f32_16x16x32_bf16 v[120:123], v[190:193], v[186:189], v[120:123]
	v_mfma_f32_16x16x32_bf16 v[116:119], v[208:211], v[178:181], v[116:119]
	v_mfma_f32_16x16x32_bf16 v[112:115], v[208:211], v[186:189], v[112:115]
	v_mfma_f32_16x16x32_bf16 v[108:111], v[216:219], v[178:181], v[108:111]
	v_mfma_f32_16x16x32_bf16 v[104:107], v[216:219], v[186:189], v[104:107]
	v_mfma_f32_16x16x32_bf16 v[100:103], v[224:227], v[178:181], v[100:103]
	v_mfma_f32_16x16x32_bf16 v[96:99], v[224:227], v[186:189], v[96:99]
	s_barrier
	v_add_u32_e32 v206, s66, v140
	s_add_i32 m0, s100, 0x10000
	ds_read_b128 v[228:231], v154
	ds_read_b128 v[232:235], v154 offset:1024
	ds_read_b128 v[236:239], v154 offset:2048
	ds_read_b128 v[240:243], v154 offset:3072
	global_load_lds_dwordx4 v206, s[86:87]
	v_add_u32_e32 v244, s66, v138
	s_add_i32 m0, s100, 0x12000
	s_nop 0
	global_load_lds_dwordx4 v244, s[86:87]
	s_barrier
	s_waitcnt lgkmcnt(0)
	v_mfma_f32_16x16x32_bf16 v[92:95], v[160:163], v[228:231], v[92:95]
	v_mfma_f32_16x16x32_bf16 v[88:91], v[160:163], v[236:239], v[88:91]
	v_mfma_f32_16x16x32_bf16 v[84:87], v[196:199], v[228:231], v[84:87]
	v_mfma_f32_16x16x32_bf16 v[80:83], v[196:199], v[236:239], v[80:83]
	v_mfma_f32_16x16x32_bf16 v[76:79], v[212:215], v[228:231], v[76:79]
	v_mfma_f32_16x16x32_bf16 v[72:75], v[212:215], v[236:239], v[72:75]
	v_mfma_f32_16x16x32_bf16 v[68:71], v[220:223], v[228:231], v[68:71]
	v_mfma_f32_16x16x32_bf16 v[64:67], v[220:223], v[236:239], v[64:67]
	v_mfma_f32_16x16x32_bf16 v[92:95], v[190:193], v[232:235], v[92:95]
	v_mfma_f32_16x16x32_bf16 v[88:91], v[190:193], v[240:243], v[88:91]
	v_mfma_f32_16x16x32_bf16 v[84:87], v[208:211], v[232:235], v[84:87]
	v_mfma_f32_16x16x32_bf16 v[80:83], v[208:211], v[240:243], v[80:83]
	v_mfma_f32_16x16x32_bf16 v[76:79], v[216:219], v[232:235], v[76:79]
	v_mfma_f32_16x16x32_bf16 v[72:75], v[216:219], v[240:243], v[72:75]
	v_mfma_f32_16x16x32_bf16 v[68:71], v[224:227], v[232:235], v[68:71]
	v_mfma_f32_16x16x32_bf16 v[64:67], v[224:227], v[240:243], v[64:67]
	v_add_u32_e32 v160, s54, v136
	s_mov_b32 m0, s100
	s_barrier
	ds_read_b128 v[190:193], v147 offset:16384
	ds_read_b128 v[196:199], v147 offset:17408
	ds_read_b128 v[208:211], v146 offset:16384
	ds_read_b128 v[212:215], v146 offset:17408
	ds_read_b128 v[216:219], v145 offset:16384
	ds_read_b128 v[220:223], v145 offset:17408
	ds_read_b128 v[224:227], v144 offset:16384
	ds_read_b128 v[244:247], v144 offset:17408
	global_load_lds_dwordx4 v160, s[86:87]
	v_add_u32_e32 v162, s54, v134
	s_add_i32 m0, s100, 0x2000
	s_nop 0
	global_load_lds_dwordx4 v162, s[86:87]
	s_barrier
	s_waitcnt lgkmcnt(0)
	v_mfma_f32_16x16x32_bf16 v[60:63], v[190:193], v[174:177], v[60:63]
	v_mfma_f32_16x16x32_bf16 v[56:59], v[190:193], v[182:185], v[56:59]
	v_mfma_f32_16x16x32_bf16 v[52:55], v[208:211], v[174:177], v[52:55]
	v_mfma_f32_16x16x32_bf16 v[48:51], v[208:211], v[182:185], v[48:51]
	v_mfma_f32_16x16x32_bf16 v[44:47], v[216:219], v[174:177], v[44:47]
	v_mfma_f32_16x16x32_bf16 v[40:43], v[216:219], v[182:185], v[40:43]
	v_mfma_f32_16x16x32_bf16 v[36:39], v[224:227], v[174:177], v[36:39]
	v_mfma_f32_16x16x32_bf16 v[32:35], v[224:227], v[182:185], v[32:35]
	v_mfma_f32_16x16x32_bf16 v[60:63], v[196:199], v[178:181], v[60:63]
	v_mfma_f32_16x16x32_bf16 v[56:59], v[196:199], v[186:189], v[56:59]
	v_mfma_f32_16x16x32_bf16 v[52:55], v[212:215], v[178:181], v[52:55]
	v_mfma_f32_16x16x32_bf16 v[48:51], v[212:215], v[186:189], v[48:51]
	v_mfma_f32_16x16x32_bf16 v[44:47], v[220:223], v[178:181], v[44:47]
	v_mfma_f32_16x16x32_bf16 v[40:43], v[220:223], v[186:189], v[40:43]
	v_mfma_f32_16x16x32_bf16 v[36:39], v[244:247], v[178:181], v[36:39]
	v_mfma_f32_16x16x32_bf16 v[32:35], v[244:247], v[186:189], v[32:35]
	s_barrier
	v_add_u32_e32 v162, s60, v140
	s_add_i32 m0, s100, 0x14000
	v_add_u32_e32 v174, s60, v138
	global_load_lds_dwordx4 v162, s[86:87]
	s_nop 0
	s_add_i32 m0, s100, 0x16000
	s_nop 0
	global_load_lds_dwordx4 v174, s[86:87]
	s_waitcnt vmcnt(6)
	s_barrier
; #define P8_STAGE(P,BASE,br,kt) do{const bfr* _ub=(BASE)+((long)(br)*K+(long)(kt)*BK); \
;     __builtin_amdgcn_global_load_lds((const unsigned*)(_ub+so0),(unsigned*)((char*)(P)+wid*1024),16,0,0); \
;     __builtin_amdgcn_global_load_lds((const unsigned*)(_ub+so1),(unsigned*)((char*)(P)+wid*1024+8192),16,0,0);}while(0)
; #define P8_LDA(dst,b,h) _Pragma("unroll") for(int m=0;m<4;++m) _Pragma("unroll") for(int k=0;k<2;++k) \
;     dst[m][k]=*reinterpret_cast<const bf16x8*>((char*)P8_SA(b,h)+lds_byte(wr*64+m*16+fr,k*32+fq*8))
; #define P8_LDB(dst,b,h) _Pragma("unroll") for(int n=0;n<2;++n) _Pragma("unroll") for(int k=0;k<2;++k) \
;     dst[n][k]=*reinterpret_cast<const bf16x8*>((char*)P8_SB(b,h)+lds_byte(wc*32+n*16+fr,k*32+fq*8))
; #define P8_MMA(ai,bj,At,Bt) do{__builtin_amdgcn_s_setprio(1); \
;     _Pragma("unroll") for(int m=0;m<4;++m) _Pragma("unroll") for(int n=0;n<2;++n) _Pragma("unroll") for(int k=0;k<2;++k) \
;       acc[ai][bj][m][n]=__builtin_amdgcn_mfma_f32_16x16x32_bf16(At[m][k],Bt[n][k],acc[ai][bj][m][n],0,0,0); \
;     __builtin_amdgcn_s_setprio(0);}while(0)
; #define P8_WAIT_V(n) asm volatile("s_waitcnt vmcnt(" #n ")":::"memory")
; #define P8_WAIT_L(n) asm volatile("s_waitcnt lgkmcnt(" #n ")":::"memory")
; #define P8_BAR __builtin_amdgcn_s_barrier()
; #define P8_SCHED __builtin_amdgcn_sched_barrier(0)
; template <class EPI>
; DEVI void gemm8_tile(const bfr* __restrict__ A, const bfr* __restrict__ Bt, int K, int brow, int bcol, int nbrow, int nbcol, char* shmc, EPI epi) {
;     ...
;     P8_WAIT_V(6); P8_BAR; P8_MMA(1,1,At,B1); P8_BAR;
;     P8_LDB(B0,1,0); P8_SCHED; P8_LDA(At,1,0); P8_STAGE(P8_SA(0,1),A,brow+128,t+2);
;     P8_WAIT_L(8); P8_BAR; P8_WAIT_L(0); P8_MMA(0,0,At,B0); P8_BAR; P8_SCHED;
;     P8_LDB(B1,1,1); P8_STAGE(P8_SB(1,0),Bt,bcol,t+3);
;     P8_BAR; P8_WAIT_L(0); P8_MMA(0,1,At,B1); P8_BAR;
;     P8_LDA(At,1,1); P8_STAGE(P8_SA(1,0),A,brow,t+3);
;     P8_BAR; P8_WAIT_L(0); P8_MMA(1,0,At,B0); P8_BAR; P8_SCHED;
	v_mfma_f32_16x16x32_bf16 v[28:31], v[190:193], v[228:231], v[28:31]
	v_mfma_f32_16x16x32_bf16 v[24:27], v[190:193], v[236:239], v[24:27]
	v_mfma_f32_16x16x32_bf16 v[20:23], v[208:211], v[228:231], v[20:23]
	v_mfma_f32_16x16x32_bf16 v[16:19], v[208:211], v[236:239], v[16:19]
	v_mfma_f32_16x16x32_bf16 v[12:15], v[216:219], v[228:231], v[12:15]
	v_mfma_f32_16x16x32_bf16 v[8:11], v[216:219], v[236:239], v[8:11]
	v_mfma_f32_16x16x32_bf16 v[4:7], v[224:227], v[228:231], v[4:7]
	v_mfma_f32_16x16x32_bf16 v[0:3], v[224:227], v[236:239], v[0:3]
	v_mfma_f32_16x16x32_bf16 v[28:31], v[196:199], v[232:235], v[28:31]
	v_mfma_f32_16x16x32_bf16 v[24:27], v[196:199], v[240:243], v[24:27]
	v_mfma_f32_16x16x32_bf16 v[20:23], v[212:215], v[232:235], v[20:23]
	v_mfma_f32_16x16x32_bf16 v[16:19], v[212:215], v[240:243], v[16:19]
	v_mfma_f32_16x16x32_bf16 v[12:15], v[220:223], v[232:235], v[12:15]
	v_mfma_f32_16x16x32_bf16 v[8:11], v[220:223], v[240:243], v[8:11]
	v_mfma_f32_16x16x32_bf16 v[4:7], v[244:247], v[232:235], v[4:7]
	v_mfma_f32_16x16x32_bf16 v[0:3], v[244:247], v[240:243], v[0:3]
	s_barrier
	ds_read_b128 v[174:177], v149
	ds_read_b128 v[178:181], v149 offset:1024
	ds_read_b128 v[182:185], v149 offset:2048
	ds_read_b128 v[186:189], v149 offset:3072
	v_add_u32_e32 v232, s72, v136
	s_add_i32 m0, s100, 0x4000
	ds_read_b128 v[190:193], v147 offset:32768
	ds_read_b128 v[196:199], v147 offset:33792
	ds_read_b128 v[208:211], v146 offset:32768
	ds_read_b128 v[212:215], v146 offset:33792
	ds_read_b128 v[216:219], v145 offset:32768
	ds_read_b128 v[220:223], v145 offset:33792
	ds_read_b128 v[224:227], v144 offset:32768
	ds_read_b128 v[228:231], v144 offset:33792
	global_load_lds_dwordx4 v232, s[86:87]
	v_add_u32_e32 v232, s72, v134
	s_add_i32 m0, s100, 0x6000
	s_nop 0
	global_load_lds_dwordx4 v232, s[86:87]
	s_waitcnt lgkmcnt(8)
	s_barrier
	s_waitcnt lgkmcnt(0)
	v_mfma_f32_16x16x32_bf16 v[124:127], v[190:193], v[174:177], v[124:127]
	v_mfma_f32_16x16x32_bf16 v[120:123], v[190:193], v[182:185], v[120:123]
	v_mfma_f32_16x16x32_bf16 v[116:119], v[208:211], v[174:177], v[116:119]
	v_mfma_f32_16x16x32_bf16 v[112:115], v[208:211], v[182:185], v[112:115]
	v_mfma_f32_16x16x32_bf16 v[108:111], v[216:219], v[174:177], v[108:111]
	v_mfma_f32_16x16x32_bf16 v[104:107], v[216:219], v[182:185], v[104:107]
	v_mfma_f32_16x16x32_bf16 v[100:103], v[224:227], v[174:177], v[100:103]
	v_mfma_f32_16x16x32_bf16 v[96:99], v[224:227], v[182:185], v[96:99]
	v_mfma_f32_16x16x32_bf16 v[124:127], v[196:199], v[178:181], v[124:127]
	v_mfma_f32_16x16x32_bf16 v[120:123], v[196:199], v[186:189], v[120:123]
	v_mfma_f32_16x16x32_bf16 v[116:119], v[212:215], v[178:181], v[116:119]
	v_mfma_f32_16x16x32_bf16 v[112:115], v[212:215], v[186:189], v[112:115]
	v_mfma_f32_16x16x32_bf16 v[108:111], v[220:223], v[178:181], v[108:111]
	v_mfma_f32_16x16x32_bf16 v[104:107], v[220:223], v[186:189], v[104:107]
	v_mfma_f32_16x16x32_bf16 v[100:103], v[228:231], v[178:181], v[100:103]
	v_mfma_f32_16x16x32_bf16 v[96:99], v[228:231], v[186:189], v[96:99]
	s_barrier
	v_add_u32_e32 v248, s74, v140
	s_add_i32 m0, s100, 0x18000
	ds_read_b128 v[232:235], v148
	ds_read_b128 v[236:239], v148 offset:1024
	ds_read_b128 v[240:243], v148 offset:2048
	ds_read_b128 v[244:247], v148 offset:3072
	global_load_lds_dwordx4 v248, s[86:87]
	v_add_u32_e32 v248, s74, v138
	s_add_i32 m0, s100, 0x1a000
	s_nop 0
	global_load_lds_dwordx4 v248, s[86:87]
	s_barrier
	s_waitcnt lgkmcnt(0)
	v_mfma_f32_16x16x32_bf16 v[92:95], v[190:193], v[232:235], v[92:95]
	v_mfma_f32_16x16x32_bf16 v[88:91], v[190:193], v[240:243], v[88:91]
	v_mfma_f32_16x16x32_bf16 v[84:87], v[208:211], v[232:235], v[84:87]
	v_mfma_f32_16x16x32_bf16 v[80:83], v[208:211], v[240:243], v[80:83]
	v_mfma_f32_16x16x32_bf16 v[76:79], v[216:219], v[232:235], v[76:79]
	v_mfma_f32_16x16x32_bf16 v[72:75], v[216:219], v[240:243], v[72:75]
	v_mfma_f32_16x16x32_bf16 v[68:71], v[224:227], v[232:235], v[68:71]
	v_mfma_f32_16x16x32_bf16 v[64:67], v[224:227], v[240:243], v[64:67]
	v_mfma_f32_16x16x32_bf16 v[92:95], v[196:199], v[236:239], v[92:95]
	v_mfma_f32_16x16x32_bf16 v[88:91], v[196:199], v[244:247], v[88:91]
	v_mfma_f32_16x16x32_bf16 v[84:87], v[212:215], v[236:239], v[84:87]
	v_mfma_f32_16x16x32_bf16 v[80:83], v[212:215], v[244:247], v[80:83]
	v_mfma_f32_16x16x32_bf16 v[76:79], v[220:223], v[236:239], v[76:79]
	v_mfma_f32_16x16x32_bf16 v[72:75], v[220:223], v[244:247], v[72:75]
	v_mfma_f32_16x16x32_bf16 v[68:71], v[228:231], v[236:239], v[68:71]
	v_mfma_f32_16x16x32_bf16 v[64:67], v[228:231], v[244:247], v[64:67]
	v_add_u32_e32 v200, s92, v136
	s_add_i32 m0, s100, 0x8000
	s_barrier
	ds_read_b128 v[190:193], v147 offset:49152
	ds_read_b128 v[196:199], v147 offset:50176
	ds_read_b128 v[208:211], v146 offset:49152
	ds_read_b128 v[212:215], v146 offset:50176
	ds_read_b128 v[216:219], v145 offset:49152
	ds_read_b128 v[220:223], v145 offset:50176
	ds_read_b128 v[224:227], v144 offset:49152
	ds_read_b128 v[228:231], v144 offset:50176
	global_load_lds_dwordx4 v200, s[86:87]
	v_add_u32_e32 v200, s92, v134
	s_add_i32 m0, s100, 0xa000
	s_nop 0
	global_load_lds_dwordx4 v200, s[86:87]
	s_barrier
; #define P8_STAGE(P,BASE,br,kt) do{const bfr* _ub=(BASE)+((long)(br)*K+(long)(kt)*BK); \
;     __builtin_amdgcn_global_load_lds((const unsigned*)(_ub+so0),(unsigned*)((char*)(P)+wid*1024),16,0,0); \
;     __builtin_amdgcn_global_load_lds((const unsigned*)(_ub+so1),(unsigned*)((char*)(P)+wid*1024+8192),16,0,0);}while(0)
; #define P8_LDA(dst,b,h) _Pragma("unroll") for(int m=0;m<4;++m) _Pragma("unroll") for(int k=0;k<2;++k) \
;     dst[m][k]=*reinterpret_cast<const bf16x8*>((char*)P8_SA(b,h)+lds_byte(wr*64+m*16+fr,k*32+fq*8))
; #define P8_LDB(dst,b,h) _Pragma("unroll") for(int n=0;n<2;++n) _Pragma("unroll") for(int k=0;k<2;++k) \
;     dst[n][k]=*reinterpret_cast<const bf16x8*>((char*)P8_SB(b,h)+lds_byte(wc*32+n*16+fr,k*32+fq*8))
; #define P8_MMA(ai,bj,At,Bt) do{__builtin_amdgcn_s_setprio(1); \
;     _Pragma("unroll") for(int m=0;m<4;++m) _Pragma("unroll") for(int n=0;n<2;++n) _Pragma("unroll") for(int k=0;k<2;++k) \
;       acc[ai][bj][m][n]=__builtin_amdgcn_mfma_f32_16x16x32_bf16(At[m][k],Bt[n][k],acc[ai][bj][m][n],0,0,0); \
;     __builtin_amdgcn_s_setprio(0);}while(0)
; #define P8_WAIT_V(n) asm volatile("s_waitcnt vmcnt(" #n ")":::"memory")
; #define P8_WAIT_L(n) asm volatile("s_waitcnt lgkmcnt(" #n ")":::"memory")
; #define P8_BAR __builtin_amdgcn_s_barrier()
; #define P8_SCHED __builtin_amdgcn_sched_barrier(0)
; template <class EPI>
; DEVI void gemm8_tile(const bfr* __restrict__ A, const bfr* __restrict__ Bt, int K, int brow, int bcol, int nbrow, int nbcol, char* shmc, EPI epi) {
;     ...
;     P8_BAR; P8_WAIT_L(0); P8_MMA(1,0,At,B0); P8_BAR; P8_SCHED;
;     P8_STAGE(P8_SB(1,1),Bt,bcol+128,t+3);
;     P8_WAIT_V(6); P8_BAR; P8_MMA(1,1,At,B1); P8_BAR;
;   }
;   { P8_LDB(B0,0,0); P8_LDA(At,0,0); P8_STAGE(P8_SA(1,1),A,brow+128,nt-1);
;     P8_BAR; P8_WAIT_L(0); P8_MMA(0,0,At,B0); P8_BAR;
	s_waitcnt lgkmcnt(0)
	v_mfma_f32_16x16x32_bf16 v[60:63], v[190:193], v[174:177], v[60:63]
	v_mfma_f32_16x16x32_bf16 v[56:59], v[190:193], v[182:185], v[56:59]
	v_mfma_f32_16x16x32_bf16 v[52:55], v[208:211], v[174:177], v[52:55]
	v_mfma_f32_16x16x32_bf16 v[48:51], v[208:211], v[182:185], v[48:51]
	v_mfma_f32_16x16x32_bf16 v[44:47], v[216:219], v[174:177], v[44:47]
	v_mfma_f32_16x16x32_bf16 v[40:43], v[216:219], v[182:185], v[40:43]
	v_mfma_f32_16x16x32_bf16 v[36:39], v[224:227], v[174:177], v[36:39]
	v_mfma_f32_16x16x32_bf16 v[32:35], v[224:227], v[182:185], v[32:35]
	v_mfma_f32_16x16x32_bf16 v[60:63], v[196:199], v[178:181], v[60:63]
	v_mfma_f32_16x16x32_bf16 v[56:59], v[196:199], v[186:189], v[56:59]
	v_mfma_f32_16x16x32_bf16 v[52:55], v[212:215], v[178:181], v[52:55]
	v_mfma_f32_16x16x32_bf16 v[48:51], v[212:215], v[186:189], v[48:51]
	v_mfma_f32_16x16x32_bf16 v[44:47], v[220:223], v[178:181], v[44:47]
	v_mfma_f32_16x16x32_bf16 v[40:43], v[220:223], v[186:189], v[40:43]
	v_mfma_f32_16x16x32_bf16 v[36:39], v[228:231], v[178:181], v[36:39]
	v_mfma_f32_16x16x32_bf16 v[32:35], v[228:231], v[186:189], v[32:35]
	s_barrier
	v_add_u32_e32 v174, s94, v140
	s_add_i32 m0, s100, 0x1c000
	s_nop 0
	global_load_lds_dwordx4 v174, s[86:87]
	v_add_u32_e32 v174, s94, v138
	s_add_i32 m0, s100, 0x1e000
	s_nop 0
	global_load_lds_dwordx4 v174, s[86:87]
	s_waitcnt vmcnt(6)
	s_barrier
	v_mfma_f32_16x16x32_bf16 v[28:31], v[190:193], v[232:235], v[28:31]
	v_mfma_f32_16x16x32_bf16 v[24:27], v[190:193], v[240:243], v[24:27]
	v_mfma_f32_16x16x32_bf16 v[20:23], v[208:211], v[232:235], v[20:23]
	v_mfma_f32_16x16x32_bf16 v[16:19], v[208:211], v[240:243], v[16:19]
	v_mfma_f32_16x16x32_bf16 v[12:15], v[216:219], v[232:235], v[12:15]
	v_mfma_f32_16x16x32_bf16 v[8:11], v[216:219], v[240:243], v[8:11]
	v_mfma_f32_16x16x32_bf16 v[4:7], v[224:227], v[232:235], v[4:7]
	v_mfma_f32_16x16x32_bf16 v[0:3], v[224:227], v[240:243], v[0:3]
	v_mfma_f32_16x16x32_bf16 v[28:31], v[196:199], v[236:239], v[28:31]
	v_mfma_f32_16x16x32_bf16 v[24:27], v[196:199], v[244:247], v[24:27]
	v_mfma_f32_16x16x32_bf16 v[20:23], v[212:215], v[236:239], v[20:23]
	v_mfma_f32_16x16x32_bf16 v[16:19], v[212:215], v[244:247], v[16:19]
	v_mfma_f32_16x16x32_bf16 v[12:15], v[220:223], v[236:239], v[12:15]
	v_mfma_f32_16x16x32_bf16 v[8:11], v[220:223], v[244:247], v[8:11]
	v_mfma_f32_16x16x32_bf16 v[4:7], v[228:231], v[236:239], v[4:7]
	v_mfma_f32_16x16x32_bf16 v[0:3], v[228:231], v[244:247], v[0:3]
	s_add_i32 s0, s0, 2
	v_lshl_add_u64 v[134:135], v[134:135], 0, s[80:81]
	v_lshl_add_u64 v[136:137], v[136:137], 0, s[80:81]
	v_lshl_add_u64 v[138:139], v[138:139], 0, s[80:81]
	s_cmp_lt_u32 s0, 4
	v_lshl_add_u64 v[140:141], v[140:141], 0, s[80:81]
	s_barrier
	s_cbranch_scc1 .LBB0_141
	v_add_u32_e32 v171, 0xc000, v143
	v_add_u32_e32 v172, 0xe000, v143
	v_add_u32_e32 v158, 0x10000, v143
	v_add_u32_e32 v159, 0x12000, v143
	v_add_u32_e32 v160, 0x2000, v143
	v_add_u32_e32 v161, 0x14000, v143
	v_add_u32_e32 v162, 0x16000, v143
	v_add_u32_e32 v163, 0x4000, v143
	v_add_u32_e32 v170, 0x6000, v143
	s_or_b32 s0, s6, 0x80
	s_ashr_i32 s1, s0, 31
	s_lshl_b64 s[0:1], s[0:1], 10
	s_add_u32 s0, s28, s0
	s_addc_u32 s1, s29, s1
	ds_read_b128 v[134:137], v157
	ds_read_b128 v[138:141], v157 offset:1024
	ds_read_b128 v[150:153], v157 offset:2048
	ds_read_b128 v[174:177], v157 offset:3072
	ds_read_b128 v[178:181], v147
	ds_read_b128 v[182:185], v147 offset:1024
	ds_read_b128 v[186:189], v146
	ds_read_b128 v[190:193], v146 offset:1024
	ds_read_b128 v[196:199], v145
	ds_read_b128 v[208:211], v145 offset:1024
	ds_read_b128 v[212:215], v144
	ds_read_b128 v[216:219], v144 offset:1024
	v_lshl_add_u64 v[156:157], v[166:167], 1, s[0:1]
	s_mov_b64 s[6:7], 0x380
	v_lshl_add_u64 v[156:157], v[156:157], 0, s[6:7]
	s_add_i32 m0, s100, 0xc000
	v_lshl_add_u64 v[132:133], v[132:133], 1, s[0:1]
	global_load_lds_dwordx4 v[156:157], off
	v_lshl_add_u64 v[132:133], v[132:133], 0, s[6:7]
	s_add_i32 m0, s100, 0xe000
	s_nop 0
	global_load_lds_dwordx4 v[132:133], off
	s_barrier
	s_waitcnt lgkmcnt(0)
	s_setprio 1
	s_waitcnt lgkmcnt(0)
	v_mfma_f32_16x16x32_bf16 v[124:127], v[178:181], v[134:137], v[124:127]
	v_mfma_f32_16x16x32_bf16 v[120:123], v[178:181], v[150:153], v[120:123]
	v_mfma_f32_16x16x32_bf16 v[116:119], v[186:189], v[134:137], v[116:119]
	v_mfma_f32_16x16x32_bf16 v[112:115], v[186:189], v[150:153], v[112:115]
	v_mfma_f32_16x16x32_bf16 v[108:111], v[196:199], v[134:137], v[108:111]
	v_mfma_f32_16x16x32_bf16 v[104:107], v[196:199], v[150:153], v[104:107]
	v_mfma_f32_16x16x32_bf16 v[100:103], v[212:215], v[134:137], v[100:103]
	v_mfma_f32_16x16x32_bf16 v[96:99], v[212:215], v[150:153], v[96:99]
	v_mfma_f32_16x16x32_bf16 v[124:127], v[182:185], v[138:141], v[124:127]
	v_mfma_f32_16x16x32_bf16 v[120:123], v[182:185], v[174:177], v[120:123]
	v_mfma_f32_16x16x32_bf16 v[116:119], v[190:193], v[138:141], v[116:119]
	v_mfma_f32_16x16x32_bf16 v[112:115], v[190:193], v[174:177], v[112:115]
	v_mfma_f32_16x16x32_bf16 v[108:111], v[208:211], v[138:141], v[108:111]
	v_mfma_f32_16x16x32_bf16 v[104:107], v[208:211], v[174:177], v[104:107]
	v_mfma_f32_16x16x32_bf16 v[100:103], v[216:219], v[138:141], v[100:103]
	v_mfma_f32_16x16x32_bf16 v[96:99], v[216:219], v[174:177], v[96:99]
	s_setprio 0
	s_barrier
	ds_read_b128 v[220:223], v154
	ds_read_b128 v[224:227], v154 offset:1024
	ds_read_b128 v[228:231], v154 offset:2048
	ds_read_b128 v[154:157], v154 offset:3072
	s_barrier
; #define P8_LDA(dst,b,h) _Pragma("unroll") for(int m=0;m<4;++m) _Pragma("unroll") for(int k=0;k<2;++k) \
;     dst[m][k]=*reinterpret_cast<const bf16x8*>((char*)P8_SA(b,h)+lds_byte(wr*64+m*16+fr,k*32+fq*8))
; #define P8_LDB(dst,b,h) _Pragma("unroll") for(int n=0;n<2;++n) _Pragma("unroll") for(int k=0;k<2;++k) \
;     dst[n][k]=*reinterpret_cast<const bf16x8*>((char*)P8_SB(b,h)+lds_byte(wc*32+n*16+fr,k*32+fq*8))
; #define P8_MMA(ai,bj,At,Bt) do{__builtin_amdgcn_s_setprio(1); \
;     _Pragma("unroll") for(int m=0;m<4;++m) _Pragma("unroll") for(int n=0;n<2;++n) _Pragma("unroll") for(int k=0;k<2;++k) \
;       acc[ai][bj][m][n]=__builtin_amdgcn_mfma_f32_16x16x32_bf16(At[m][k],Bt[n][k],acc[ai][bj][m][n],0,0,0); \
;     __builtin_amdgcn_s_setprio(0);}while(0)
; #define P8_WAIT_V(n) asm volatile("s_waitcnt vmcnt(" #n ")":::"memory")
; #define P8_WAIT_L(n) asm volatile("s_waitcnt lgkmcnt(" #n ")":::"memory")
; #define P8_BAR __builtin_amdgcn_s_barrier()
; template <class EPI>
; DEVI void gemm8_tile(const bfr* __restrict__ A, const bfr* __restrict__ Bt, int K, int brow, int bcol, int nbrow, int nbcol, char* shmc, EPI epi) {
;     ...
;     P8_LDB(B1,0,1); P8_BAR; P8_WAIT_L(0); P8_MMA(0,1,At,B1); P8_BAR;
;     P8_LDA(At,0,1); P8_WAIT_V(4); P8_BAR; P8_WAIT_L(0); P8_MMA(1,0,At,B0); P8_MMA(1,1,At,B1); P8_BAR; }
;   { P8_LDB(B0,1,0); P8_LDA(At,1,0); P8_WAIT_V(2); P8_BAR; P8_WAIT_L(0); P8_MMA(0,0,At,B0); P8_BAR;
	s_waitcnt lgkmcnt(0)
	s_setprio 1
	s_waitcnt lgkmcnt(0)
	v_mfma_f32_16x16x32_bf16 v[88:91], v[178:181], v[228:231], v[88:91]
	v_mfma_f32_16x16x32_bf16 v[76:79], v[196:199], v[220:223], v[76:79]
	v_mfma_f32_16x16x32_bf16 v[72:75], v[196:199], v[228:231], v[72:75]
	v_mfma_f32_16x16x32_bf16 v[68:71], v[212:215], v[220:223], v[68:71]
	v_mfma_f32_16x16x32_bf16 v[64:67], v[212:215], v[228:231], v[64:67]
	v_mfma_f32_16x16x32_bf16 v[92:95], v[178:181], v[220:223], v[92:95]
	v_mfma_f32_16x16x32_bf16 v[178:181], v[182:185], v[154:157], v[88:91]
	v_mfma_f32_16x16x32_bf16 v[84:87], v[186:189], v[220:223], v[84:87]
	v_mfma_f32_16x16x32_bf16 v[80:83], v[186:189], v[228:231], v[80:83]
	v_mfma_f32_16x16x32_bf16 v[76:79], v[208:211], v[224:227], v[76:79]
	v_mfma_f32_16x16x32_bf16 v[72:75], v[208:211], v[154:157], v[72:75]
	v_mfma_f32_16x16x32_bf16 v[68:71], v[216:219], v[224:227], v[68:71]
	v_mfma_f32_16x16x32_bf16 v[64:67], v[216:219], v[154:157], v[64:67]
	v_mfma_f32_16x16x32_bf16 v[232:235], v[182:185], v[224:227], v[92:95]
	v_mfma_f32_16x16x32_bf16 v[182:185], v[190:193], v[224:227], v[84:87]
	v_mfma_f32_16x16x32_bf16 v[186:189], v[190:193], v[154:157], v[80:83]
	s_setprio 0
	s_barrier
	s_nop 0
	ds_read_b128 v[80:83], v147 offset:16384
	ds_read_b128 v[84:87], v147 offset:17408
	ds_read_b128 v[88:91], v146 offset:16384
	ds_read_b128 v[92:95], v146 offset:17408
	ds_read_b128 v[190:193], v145 offset:16384
	ds_read_b128 v[196:199], v145 offset:17408
	ds_read_b128 v[208:211], v144 offset:16384
	ds_read_b128 v[212:215], v144 offset:17408
	s_waitcnt vmcnt(4)
	s_barrier
	s_waitcnt lgkmcnt(0)
	s_setprio 1
	s_waitcnt lgkmcnt(0)
	v_mfma_f32_16x16x32_bf16 v[44:47], v[190:193], v[134:137], v[44:47]
	v_mfma_f32_16x16x32_bf16 v[40:43], v[190:193], v[150:153], v[40:43]
	v_mfma_f32_16x16x32_bf16 v[36:39], v[208:211], v[134:137], v[36:39]
	v_mfma_f32_16x16x32_bf16 v[32:35], v[208:211], v[150:153], v[32:35]
	v_mfma_f32_16x16x32_bf16 v[60:63], v[80:83], v[134:137], v[60:63]
	v_mfma_f32_16x16x32_bf16 v[56:59], v[80:83], v[150:153], v[56:59]
	v_mfma_f32_16x16x32_bf16 v[52:55], v[88:91], v[134:137], v[52:55]
	v_mfma_f32_16x16x32_bf16 v[48:51], v[88:91], v[150:153], v[48:51]
	v_mfma_f32_16x16x32_bf16 v[44:47], v[196:199], v[138:141], v[44:47]
	v_mfma_f32_16x16x32_bf16 v[40:43], v[196:199], v[174:177], v[40:43]
	v_mfma_f32_16x16x32_bf16 v[36:39], v[212:215], v[138:141], v[36:39]
	v_mfma_f32_16x16x32_bf16 v[32:35], v[212:215], v[174:177], v[32:35]
	v_mfma_f32_16x16x32_bf16 v[216:219], v[84:87], v[138:141], v[60:63]
	v_mfma_f32_16x16x32_bf16 v[236:239], v[84:87], v[174:177], v[56:59]
	v_mfma_f32_16x16x32_bf16 v[240:243], v[92:95], v[138:141], v[52:55]
	v_mfma_f32_16x16x32_bf16 v[244:247], v[92:95], v[174:177], v[48:51]
	s_setprio 0
	s_setprio 1
	v_mfma_f32_16x16x32_bf16 v[12:15], v[190:193], v[220:223], v[12:15]
	v_mfma_f32_16x16x32_bf16 v[4:7], v[208:211], v[220:223], v[4:7]
	v_mfma_f32_16x16x32_bf16 v[28:31], v[80:83], v[220:223], v[28:31]
	v_mfma_f32_16x16x32_bf16 v[24:27], v[80:83], v[228:231], v[24:27]
	v_mfma_f32_16x16x32_bf16 v[20:23], v[88:91], v[220:223], v[20:23]
	v_mfma_f32_16x16x32_bf16 v[16:19], v[88:91], v[228:231], v[16:19]
	v_mfma_f32_16x16x32_bf16 v[12:15], v[196:199], v[224:227], v[12:15]
	v_mfma_f32_16x16x32_bf16 v[8:11], v[190:193], v[228:231], v[8:11]
	v_mfma_f32_16x16x32_bf16 v[4:7], v[212:215], v[224:227], v[4:7]
	v_mfma_f32_16x16x32_bf16 v[0:3], v[208:211], v[228:231], v[0:3]
	v_mfma_f32_16x16x32_bf16 v[132:135], v[84:87], v[224:227], v[28:31]
	v_mfma_f32_16x16x32_bf16 v[136:139], v[84:87], v[154:157], v[24:27]
	v_mfma_f32_16x16x32_bf16 v[150:153], v[92:95], v[224:227], v[20:23]
	v_mfma_f32_16x16x32_bf16 v[172:175], v[92:95], v[154:157], v[16:19]
	v_mfma_f32_16x16x32_bf16 v[190:193], v[196:199], v[154:157], v[8:11]
	v_mfma_f32_16x16x32_bf16 v[154:157], v[212:215], v[154:157], v[0:3]
	s_setprio 0
	s_barrier
	s_nop 0
	ds_read_b128 v[0:3], v149
	ds_read_b128 v[8:11], v149 offset:1024
	ds_read_b128 v[196:199], v149 offset:2048
	ds_read_b128 v[208:211], v149 offset:3072
	ds_read_b128 v[16:19], v147 offset:32768
	ds_read_b128 v[20:23], v147 offset:33792
	ds_read_b128 v[24:27], v146 offset:32768
	ds_read_b128 v[48:51], v146 offset:33792
	ds_read_b128 v[212:215], v145 offset:32768
	ds_read_b128 v[220:223], v145 offset:33792
	ds_read_b128 v[224:227], v144 offset:32768
	ds_read_b128 v[228:231], v144 offset:33792
	s_waitcnt vmcnt(2)
	s_barrier
; #define P8_LDA(dst,b,h) _Pragma("unroll") for(int m=0;m<4;++m) _Pragma("unroll") for(int k=0;k<2;++k) \
;     dst[m][k]=*reinterpret_cast<const bf16x8*>((char*)P8_SA(b,h)+lds_byte(wr*64+m*16+fr,k*32+fq*8))
; #define P8_LDB(dst,b,h) _Pragma("unroll") for(int n=0;n<2;++n) _Pragma("unroll") for(int k=0;k<2;++k) \
;     dst[n][k]=*reinterpret_cast<const bf16x8*>((char*)P8_SB(b,h)+lds_byte(wc*32+n*16+fr,k*32+fq*8))
; #define P8_MMA(ai,bj,At,Bt) do{__builtin_amdgcn_s_setprio(1); \
;     _Pragma("unroll") for(int m=0;m<4;++m) _Pragma("unroll") for(int n=0;n<2;++n) _Pragma("unroll") for(int k=0;k<2;++k) \
;       acc[ai][bj][m][n]=__builtin_amdgcn_mfma_f32_16x16x32_bf16(At[m][k],Bt[n][k],acc[ai][bj][m][n],0,0,0); \
;     __builtin_amdgcn_s_setprio(0);}while(0)
; #define P8_WAIT_V(n) asm volatile("s_waitcnt vmcnt(" #n ")":::"memory")
; #define P8_WAIT_L(n) asm volatile("s_waitcnt lgkmcnt(" #n ")":::"memory")
; #define P8_BAR __builtin_amdgcn_s_barrier()
; template <class EPI>
; DEVI void gemm8_tile(const bfr* __restrict__ A, const bfr* __restrict__ Bt, int K, int brow, int bcol, int nbrow, int nbcol, char* shmc, EPI epi) {
;     ...
;   { P8_LDB(B0,1,0); P8_LDA(At,1,0); P8_WAIT_V(2); P8_BAR; P8_WAIT_L(0); P8_MMA(0,0,At,B0); P8_BAR;
;     P8_LDB(B1,1,1); P8_WAIT_V(0); P8_BAR; P8_WAIT_L(0); P8_MMA(0,1,At,B1); P8_BAR;
;     P8_LDA(At,1,1); P8_BAR; P8_WAIT_L(0); P8_MMA(1,0,At,B0); P8_MMA(1,1,At,B1); P8_BAR; }
;   if(wr==0)P8_BAR;
	s_waitcnt lgkmcnt(0)
	s_setprio 1
	s_waitcnt lgkmcnt(0)
	v_mfma_f32_16x16x32_bf16 v[28:31], v[16:19], v[0:3], v[124:127]
	v_mfma_f32_16x16x32_bf16 v[124:127], v[20:23], v[8:11], v[28:31]
	v_mfma_f32_16x16x32_bf16 v[28:31], v[16:19], v[196:199], v[120:123]
	v_mfma_f32_16x16x32_bf16 v[92:95], v[20:23], v[208:211], v[28:31]
	v_mfma_f32_16x16x32_bf16 v[28:31], v[24:27], v[0:3], v[116:119]
	v_mfma_f32_16x16x32_bf16 v[120:123], v[48:51], v[8:11], v[28:31]
	v_mfma_f32_16x16x32_bf16 v[28:31], v[24:27], v[196:199], v[112:115]
	v_mfma_f32_16x16x32_bf16 v[88:91], v[48:51], v[208:211], v[28:31]
	v_mfma_f32_16x16x32_bf16 v[28:31], v[212:215], v[0:3], v[108:111]
	v_mfma_f32_16x16x32_bf16 v[116:119], v[220:223], v[8:11], v[28:31]
	v_mfma_f32_16x16x32_bf16 v[28:31], v[212:215], v[196:199], v[104:107]
	v_mfma_f32_16x16x32_bf16 v[84:87], v[220:223], v[208:211], v[28:31]
	v_mfma_f32_16x16x32_bf16 v[28:31], v[224:227], v[0:3], v[100:103]
	v_mfma_f32_16x16x32_bf16 v[112:115], v[228:231], v[8:11], v[28:31]
	v_mfma_f32_16x16x32_bf16 v[28:31], v[224:227], v[196:199], v[96:99]
	v_mfma_f32_16x16x32_bf16 v[80:83], v[228:231], v[208:211], v[28:31]
	s_setprio 0
	s_barrier
	ds_read_b128 v[248:251], v148
	ds_read_b128 v[200:203], v148 offset:1024
	ds_read_b128 v[204:207], v148 offset:2048
	s_nop 1
	ds_read_b128 v[28:31], v148 offset:3072
	s_waitcnt vmcnt(0)
	s_barrier
	s_waitcnt lgkmcnt(0)
	s_setprio 1
	s_waitcnt lgkmcnt(0)
	v_mfma_f32_16x16x32_bf16 v[52:55], v[16:19], v[248:251], v[232:235]
	v_mfma_f32_16x16x32_bf16 v[16:19], v[16:19], v[204:207], v[178:181]
	v_mfma_f32_16x16x32_bf16 v[176:179], v[20:23], v[28:31], v[16:19]
	v_mfma_f32_16x16x32_bf16 v[16:19], v[24:27], v[248:251], v[182:185]
	v_mfma_f32_16x16x32_bf16 v[56:59], v[48:51], v[200:203], v[16:19]
	v_mfma_f32_16x16x32_bf16 v[16:19], v[24:27], v[204:207], v[186:189]
	v_mfma_f32_16x16x32_bf16 v[24:27], v[48:51], v[28:31], v[16:19]
	v_mfma_f32_16x16x32_bf16 v[16:19], v[212:215], v[248:251], v[76:79]
	v_mfma_f32_16x16x32_bf16 v[60:63], v[20:23], v[200:203], v[52:55]
	v_mfma_f32_16x16x32_bf16 v[52:55], v[220:223], v[200:203], v[16:19]
	v_mfma_f32_16x16x32_bf16 v[16:19], v[212:215], v[204:207], v[72:75]
	v_mfma_f32_16x16x32_bf16 v[20:23], v[220:223], v[28:31], v[16:19]
	v_mfma_f32_16x16x32_bf16 v[16:19], v[224:227], v[248:251], v[68:71]
	v_mfma_f32_16x16x32_bf16 v[48:51], v[228:231], v[200:203], v[16:19]
	v_mfma_f32_16x16x32_bf16 v[16:19], v[224:227], v[204:207], v[64:67]
	v_mfma_f32_16x16x32_bf16 v[16:19], v[228:231], v[28:31], v[16:19]
	s_setprio 0
	s_barrier
	ds_read_b128 v[180:183], v147 offset:49152
	ds_read_b128 v[184:187], v147 offset:50176
	ds_read_b128 v[212:215], v146 offset:49152
	ds_read_b128 v[146:149], v146 offset:50176
	ds_read_b128 v[220:223], v145 offset:49152
	ds_read_b128 v[224:227], v145 offset:50176
	ds_read_b128 v[228:231], v144 offset:49152
	ds_read_b128 v[232:235], v144 offset:50176
	s_barrier
	s_waitcnt lgkmcnt(0)
	s_setprio 1
	s_waitcnt lgkmcnt(0)
	v_mfma_f32_16x16x32_bf16 v[64:67], v[180:183], v[0:3], v[216:219]
	v_mfma_f32_16x16x32_bf16 v[104:107], v[184:187], v[8:11], v[64:67]
	v_mfma_f32_16x16x32_bf16 v[64:67], v[180:183], v[196:199], v[236:239]
	v_mfma_f32_16x16x32_bf16 v[72:75], v[184:187], v[208:211], v[64:67]
	v_mfma_f32_16x16x32_bf16 v[64:67], v[212:215], v[0:3], v[240:243]
	v_mfma_f32_16x16x32_bf16 v[44:47], v[220:223], v[0:3], v[44:47]
	v_mfma_f32_16x16x32_bf16 v[0:3], v[228:231], v[0:3], v[36:39]
	v_mfma_f32_16x16x32_bf16 v[96:99], v[146:149], v[8:11], v[64:67]
	v_mfma_f32_16x16x32_bf16 v[64:67], v[212:215], v[196:199], v[244:247]
	v_mfma_f32_16x16x32_bf16 v[40:43], v[220:223], v[196:199], v[40:43]
	v_mfma_f32_16x16x32_bf16 v[100:103], v[232:235], v[8:11], v[0:3]
	v_mfma_f32_16x16x32_bf16 v[0:3], v[228:231], v[196:199], v[32:35]
	v_mfma_f32_16x16x32_bf16 v[64:67], v[146:149], v[208:211], v[64:67]
	v_mfma_f32_16x16x32_bf16 v[108:111], v[224:227], v[8:11], v[44:47]
	v_mfma_f32_16x16x32_bf16 v[76:79], v[224:227], v[208:211], v[40:43]
	v_mfma_f32_16x16x32_bf16 v[68:71], v[232:235], v[208:211], v[0:3]
	s_setprio 0
	s_setprio 1
	v_mfma_f32_16x16x32_bf16 v[0:3], v[180:183], v[248:251], v[132:135]
	v_mfma_f32_16x16x32_bf16 v[40:43], v[184:187], v[200:203], v[0:3]
	v_mfma_f32_16x16x32_bf16 v[0:3], v[180:183], v[204:207], v[136:139]
	v_mfma_f32_16x16x32_bf16 v[8:11], v[184:187], v[28:31], v[0:3]
	v_mfma_f32_16x16x32_bf16 v[0:3], v[212:215], v[248:251], v[150:153]
	v_mfma_f32_16x16x32_bf16 v[12:15], v[220:223], v[248:251], v[12:15]
	v_mfma_f32_16x16x32_bf16 v[4:7], v[228:231], v[248:251], v[4:7]
	v_mfma_f32_16x16x32_bf16 v[32:35], v[146:149], v[200:203], v[0:3]
	v_mfma_f32_16x16x32_bf16 v[0:3], v[212:215], v[204:207], v[172:175]
	v_mfma_f32_16x16x32_bf16 v[44:47], v[224:227], v[200:203], v[12:15]
	v_mfma_f32_16x16x32_bf16 v[12:15], v[220:223], v[204:207], v[190:193]
	v_mfma_f32_16x16x32_bf16 v[36:39], v[232:235], v[200:203], v[4:7]
	v_mfma_f32_16x16x32_bf16 v[4:7], v[228:231], v[204:207], v[154:157]
	v_mfma_f32_16x16x32_bf16 v[0:3], v[146:149], v[28:31], v[0:3]
	v_mfma_f32_16x16x32_bf16 v[12:15], v[224:227], v[28:31], v[12:15]
	v_mfma_f32_16x16x32_bf16 v[4:7], v[232:235], v[28:31], v[4:7]
	s_setprio 0
	v_cmp_gt_u32_e32 vcc, s57, v142
	s_barrier
	s_and_saveexec_b64 s[0:1], vcc
	s_cbranch_execz .LBB0_144
	s_barrier

; #define P8_STAGE(P,BASE,br,kt) do{const bfr* _ub=(BASE)+((long)(br)*K+(long)(kt)*BK); \
;     __builtin_amdgcn_global_load_lds((const unsigned*)(_ub+so0),(unsigned*)((char*)(P)+wid*1024),16,0,0); \
;     __builtin_amdgcn_global_load_lds((const unsigned*)(_ub+so1),(unsigned*)((char*)(P)+wid*1024+8192),16,0,0);}while(0)
; #define P8_LDA(dst,b,h) _Pragma("unroll") for(int m=0;m<4;++m) _Pragma("unroll") for(int k=0;k<2;++k) \
;     dst[m][k]=*reinterpret_cast<const bf16x8*>((char*)P8_SA(b,h)+lds_byte(wr*64+m*16+fr,k*32+fq*8))
; #define P8_LDB(dst,b,h) _Pragma("unroll") for(int n=0;n<2;++n) _Pragma("unroll") for(int k=0;k<2;++k) \
;     dst[n][k]=*reinterpret_cast<const bf16x8*>((char*)P8_SB(b,h)+lds_byte(wc*32+n*16+fr,k*32+fq*8))
; #define P8_MMA(ai,bj,At,Bt) do{__builtin_amdgcn_s_setprio(1); \
;     _Pragma("unroll") for(int m=0;m<4;++m) _Pragma("unroll") for(int n=0;n<2;++n) _Pragma("unroll") for(int k=0;k<2;++k) \
;       acc[ai][bj][m][n]=__builtin_amdgcn_mfma_f32_16x16x32_bf16(At[m][k],Bt[n][k],acc[ai][bj][m][n],0,0,0); \
;     __builtin_amdgcn_s_setprio(0);}while(0)
; #define P8_WAIT_V(n) asm volatile("s_waitcnt vmcnt(" #n ")":::"memory")
; #define P8_WAIT_L(n) asm volatile("s_waitcnt lgkmcnt(" #n ")":::"memory")
; #define P8_BAR __builtin_amdgcn_s_barrier()
; #define P8_SCHED __builtin_amdgcn_sched_barrier(0)
; template <class EPI>
; DEVI void gemm8_tile(const bfr* __restrict__ A, const bfr* __restrict__ Bt, int K, int brow, int bcol, int nbrow, int nbcol, char* shmc, EPI epi) {
;     ...
;     P8_LDB(B0,0,0); P8_SCHED; P8_LDA(At,0,0); P8_STAGE(P8_SA(1,1),A,brow+128,t+1);
;     P8_WAIT_L(8); P8_BAR; P8_WAIT_L(0); P8_MMA(0,0,At,B0); P8_BAR; P8_SCHED;
;     P8_LDB(B1,0,1); P8_STAGE(P8_SB(0,0),Bt,bcol,t+2);
;     P8_BAR; P8_WAIT_L(0); P8_MMA(0,1,At,B1); P8_BAR;
;     P8_LDA(At,0,1); P8_STAGE(P8_SA(0,0),A,brow,t+2);
;     P8_BAR; P8_WAIT_L(0); P8_MMA(1,0,At,B0); P8_BAR; P8_SCHED;
;     P8_STAGE(P8_SB(0,1),Bt,bcol+128,t+2);
;     P8_WAIT_V(6); P8_BAR; P8_MMA(1,1,At,B1); P8_BAR;
.LBB0_175:
	ds_read_b128 v[174:177], v157
	ds_read_b128 v[178:181], v157 offset:1024
	ds_read_b128 v[182:185], v157 offset:2048
	ds_read_b128 v[186:189], v157 offset:3072
	v_add_u32_e32 v158, s54, v136
	s_add_i32 m0, s100, 0xc000
	ds_read_b128 v[160:163], v147
	ds_read_b128 v[190:193], v147 offset:1024
	ds_read_b128 v[196:199], v146
	ds_read_b128 v[200:203], v146 offset:1024
	ds_read_b128 v[204:207], v145
	ds_read_b128 v[208:211], v145 offset:1024
	ds_read_b128 v[212:215], v144
	ds_read_b128 v[216:219], v144 offset:1024
	global_load_lds_dwordx4 v158, s[86:87]
	v_add_u32_e32 v158, s54, v134
	s_add_i32 m0, s100, 0xe000
	s_nop 0
	global_load_lds_dwordx4 v158, s[86:87]
	s_waitcnt lgkmcnt(8)
	s_barrier
	s_waitcnt lgkmcnt(0)
	v_mfma_f32_16x16x32_bf16 v[124:127], v[160:163], v[174:177], v[124:127]
	v_mfma_f32_16x16x32_bf16 v[120:123], v[160:163], v[182:185], v[120:123]
	v_mfma_f32_16x16x32_bf16 v[116:119], v[196:199], v[174:177], v[116:119]
	v_mfma_f32_16x16x32_bf16 v[112:115], v[196:199], v[182:185], v[112:115]
	v_mfma_f32_16x16x32_bf16 v[108:111], v[204:207], v[174:177], v[108:111]
	v_mfma_f32_16x16x32_bf16 v[104:107], v[204:207], v[182:185], v[104:107]
	v_mfma_f32_16x16x32_bf16 v[100:103], v[212:215], v[174:177], v[100:103]
	v_mfma_f32_16x16x32_bf16 v[96:99], v[212:215], v[182:185], v[96:99]
	v_mfma_f32_16x16x32_bf16 v[124:127], v[190:193], v[178:181], v[124:127]
	v_mfma_f32_16x16x32_bf16 v[120:123], v[190:193], v[186:189], v[120:123]
	v_mfma_f32_16x16x32_bf16 v[116:119], v[200:203], v[178:181], v[116:119]
	v_mfma_f32_16x16x32_bf16 v[112:115], v[200:203], v[186:189], v[112:115]
	v_mfma_f32_16x16x32_bf16 v[108:111], v[208:211], v[178:181], v[108:111]
	v_mfma_f32_16x16x32_bf16 v[104:107], v[208:211], v[186:189], v[104:107]
	v_mfma_f32_16x16x32_bf16 v[100:103], v[216:219], v[178:181], v[100:103]
	v_mfma_f32_16x16x32_bf16 v[96:99], v[216:219], v[186:189], v[96:99]
	s_barrier
	v_add_u32_e32 v236, s60, v140
	s_add_i32 m0, s100, 0x10000
	ds_read_b128 v[220:223], v154
	ds_read_b128 v[224:227], v154 offset:1024
	ds_read_b128 v[228:231], v154 offset:2048
	ds_read_b128 v[232:235], v154 offset:3072
	global_load_lds_dwordx4 v236, s[86:87]
	v_add_u32_e32 v236, s60, v138
	s_add_i32 m0, s100, 0x12000
	s_nop 0
	global_load_lds_dwordx4 v236, s[86:87]
	s_barrier
	s_waitcnt lgkmcnt(0)
	v_mfma_f32_16x16x32_bf16 v[92:95], v[160:163], v[220:223], v[92:95]
	v_mfma_f32_16x16x32_bf16 v[88:91], v[160:163], v[228:231], v[88:91]
	v_mfma_f32_16x16x32_bf16 v[84:87], v[196:199], v[220:223], v[84:87]
	v_mfma_f32_16x16x32_bf16 v[80:83], v[196:199], v[228:231], v[80:83]
	v_mfma_f32_16x16x32_bf16 v[76:79], v[204:207], v[220:223], v[76:79]
	v_mfma_f32_16x16x32_bf16 v[72:75], v[204:207], v[228:231], v[72:75]
	v_mfma_f32_16x16x32_bf16 v[68:71], v[212:215], v[220:223], v[68:71]
	v_mfma_f32_16x16x32_bf16 v[64:67], v[212:215], v[228:231], v[64:67]
	v_mfma_f32_16x16x32_bf16 v[92:95], v[190:193], v[224:227], v[92:95]
	v_mfma_f32_16x16x32_bf16 v[88:91], v[190:193], v[232:235], v[88:91]
	v_mfma_f32_16x16x32_bf16 v[84:87], v[200:203], v[224:227], v[84:87]
	v_mfma_f32_16x16x32_bf16 v[80:83], v[200:203], v[232:235], v[80:83]
	v_mfma_f32_16x16x32_bf16 v[76:79], v[208:211], v[224:227], v[76:79]
	v_mfma_f32_16x16x32_bf16 v[72:75], v[208:211], v[232:235], v[72:75]
	v_mfma_f32_16x16x32_bf16 v[68:71], v[216:219], v[224:227], v[68:71]
	v_mfma_f32_16x16x32_bf16 v[64:67], v[216:219], v[232:235], v[64:67]
	v_add_u32_e32 v160, s72, v136
	s_mov_b32 m0, s100
	s_barrier
	ds_read_b128 v[190:193], v147 offset:16384
	ds_read_b128 v[196:199], v147 offset:17408
	ds_read_b128 v[200:203], v146 offset:16384
	ds_read_b128 v[204:207], v146 offset:17408
	ds_read_b128 v[208:211], v145 offset:16384
	ds_read_b128 v[212:215], v145 offset:17408
	ds_read_b128 v[216:219], v144 offset:16384
	ds_read_b128 v[236:239], v144 offset:17408
	global_load_lds_dwordx4 v160, s[86:87]
	v_add_u32_e32 v162, s72, v134
	s_add_i32 m0, s100, 0x2000
	s_nop 0
	global_load_lds_dwordx4 v162, s[86:87]
	s_barrier
	s_waitcnt lgkmcnt(0)
	v_mfma_f32_16x16x32_bf16 v[60:63], v[190:193], v[174:177], v[60:63]
	v_mfma_f32_16x16x32_bf16 v[56:59], v[190:193], v[182:185], v[56:59]
	v_mfma_f32_16x16x32_bf16 v[52:55], v[200:203], v[174:177], v[52:55]
	v_mfma_f32_16x16x32_bf16 v[48:51], v[200:203], v[182:185], v[48:51]
	v_mfma_f32_16x16x32_bf16 v[44:47], v[208:211], v[174:177], v[44:47]
	v_mfma_f32_16x16x32_bf16 v[40:43], v[208:211], v[182:185], v[40:43]
	v_mfma_f32_16x16x32_bf16 v[36:39], v[216:219], v[174:177], v[36:39]
	v_mfma_f32_16x16x32_bf16 v[32:35], v[216:219], v[182:185], v[32:35]
	v_mfma_f32_16x16x32_bf16 v[60:63], v[196:199], v[178:181], v[60:63]
	v_mfma_f32_16x16x32_bf16 v[56:59], v[196:199], v[186:189], v[56:59]
	v_mfma_f32_16x16x32_bf16 v[52:55], v[204:207], v[178:181], v[52:55]
	v_mfma_f32_16x16x32_bf16 v[48:51], v[204:207], v[186:189], v[48:51]
	v_mfma_f32_16x16x32_bf16 v[44:47], v[212:215], v[178:181], v[44:47]
	v_mfma_f32_16x16x32_bf16 v[40:43], v[212:215], v[186:189], v[40:43]
	v_mfma_f32_16x16x32_bf16 v[36:39], v[236:239], v[178:181], v[36:39]
	v_mfma_f32_16x16x32_bf16 v[32:35], v[236:239], v[186:189], v[32:35]
	s_barrier
	v_add_u32_e32 v162, s82, v140
	s_add_i32 m0, s100, 0x14000
	v_add_u32_e32 v174, s82, v138
	global_load_lds_dwordx4 v162, s[86:87]
	s_nop 0
	s_add_i32 m0, s100, 0x16000
	s_nop 0
	global_load_lds_dwordx4 v174, s[86:87]
	s_waitcnt vmcnt(6)
	s_barrier
; #define P8_STAGE(P,BASE,br,kt) do{const bfr* _ub=(BASE)+((long)(br)*K+(long)(kt)*BK); \
;     __builtin_amdgcn_global_load_lds((const unsigned*)(_ub+so0),(unsigned*)((char*)(P)+wid*1024),16,0,0); \
;     __builtin_amdgcn_global_load_lds((const unsigned*)(_ub+so1),(unsigned*)((char*)(P)+wid*1024+8192),16,0,0);}while(0)
; #define P8_LDA(dst,b,h) _Pragma("unroll") for(int m=0;m<4;++m) _Pragma("unroll") for(int k=0;k<2;++k) \
;     dst[m][k]=*reinterpret_cast<const bf16x8*>((char*)P8_SA(b,h)+lds_byte(wr*64+m*16+fr,k*32+fq*8))
; #define P8_LDB(dst,b,h) _Pragma("unroll") for(int n=0;n<2;++n) _Pragma("unroll") for(int k=0;k<2;++k) \
;     dst[n][k]=*reinterpret_cast<const bf16x8*>((char*)P8_SB(b,h)+lds_byte(wc*32+n*16+fr,k*32+fq*8))
; #define P8_MMA(ai,bj,At,Bt) do{__builtin_amdgcn_s_setprio(1); \
;     _Pragma("unroll") for(int m=0;m<4;++m) _Pragma("unroll") for(int n=0;n<2;++n) _Pragma("unroll") for(int k=0;k<2;++k) \
;       acc[ai][bj][m][n]=__builtin_amdgcn_mfma_f32_16x16x32_bf16(At[m][k],Bt[n][k],acc[ai][bj][m][n],0,0,0); \
;     __builtin_amdgcn_s_setprio(0);}while(0)
; #define P8_WAIT_V(n) asm volatile("s_waitcnt vmcnt(" #n ")":::"memory")
; #define P8_WAIT_L(n) asm volatile("s_waitcnt lgkmcnt(" #n ")":::"memory")
; #define P8_BAR __builtin_amdgcn_s_barrier()
; #define P8_SCHED __builtin_amdgcn_sched_barrier(0)
; template <class EPI>
; DEVI void gemm8_tile(const bfr* __restrict__ A, const bfr* __restrict__ Bt, int K, int brow, int bcol, int nbrow, int nbcol, char* shmc, EPI epi) {
;     ...
;     P8_WAIT_V(6); P8_BAR; P8_MMA(1,1,At,B1); P8_BAR;
;     P8_LDB(B0,1,0); P8_SCHED; P8_LDA(At,1,0); P8_STAGE(P8_SA(0,1),A,brow+128,t+2);
;     P8_WAIT_L(8); P8_BAR; P8_WAIT_L(0); P8_MMA(0,0,At,B0); P8_BAR; P8_SCHED;
;     P8_LDB(B1,1,1); P8_STAGE(P8_SB(1,0),Bt,bcol,t+3);
;     P8_BAR; P8_WAIT_L(0); P8_MMA(0,1,At,B1); P8_BAR;
;     P8_LDA(At,1,1); P8_STAGE(P8_SA(1,0),A,brow,t+3);
;     P8_BAR; P8_WAIT_L(0); P8_MMA(1,0,At,B0); P8_BAR; P8_SCHED;
	v_mfma_f32_16x16x32_bf16 v[28:31], v[190:193], v[220:223], v[28:31]
	v_mfma_f32_16x16x32_bf16 v[24:27], v[190:193], v[228:231], v[24:27]
	v_mfma_f32_16x16x32_bf16 v[20:23], v[200:203], v[220:223], v[20:23]
	v_mfma_f32_16x16x32_bf16 v[16:19], v[200:203], v[228:231], v[16:19]
	v_mfma_f32_16x16x32_bf16 v[12:15], v[208:211], v[220:223], v[12:15]
	v_mfma_f32_16x16x32_bf16 v[8:11], v[208:211], v[228:231], v[8:11]
	v_mfma_f32_16x16x32_bf16 v[4:7], v[216:219], v[220:223], v[4:7]
	v_mfma_f32_16x16x32_bf16 v[0:3], v[216:219], v[228:231], v[0:3]
	v_mfma_f32_16x16x32_bf16 v[28:31], v[196:199], v[224:227], v[28:31]
	v_mfma_f32_16x16x32_bf16 v[24:27], v[196:199], v[232:235], v[24:27]
	v_mfma_f32_16x16x32_bf16 v[20:23], v[204:207], v[224:227], v[20:23]
	v_mfma_f32_16x16x32_bf16 v[16:19], v[204:207], v[232:235], v[16:19]
	v_mfma_f32_16x16x32_bf16 v[12:15], v[212:215], v[224:227], v[12:15]
	v_mfma_f32_16x16x32_bf16 v[8:11], v[212:215], v[232:235], v[8:11]
	v_mfma_f32_16x16x32_bf16 v[4:7], v[236:239], v[224:227], v[4:7]
	v_mfma_f32_16x16x32_bf16 v[0:3], v[236:239], v[232:235], v[0:3]
	s_barrier
	ds_read_b128 v[174:177], v149
	ds_read_b128 v[178:181], v149 offset:1024
	ds_read_b128 v[182:185], v149 offset:2048
	ds_read_b128 v[186:189], v149 offset:3072
	v_add_u32_e32 v224, s92, v136
	s_add_i32 m0, s100, 0x4000
	ds_read_b128 v[190:193], v147 offset:32768
	ds_read_b128 v[196:199], v147 offset:33792
	ds_read_b128 v[200:203], v146 offset:32768
	ds_read_b128 v[204:207], v146 offset:33792
	ds_read_b128 v[208:211], v145 offset:32768
	ds_read_b128 v[212:215], v145 offset:33792
	ds_read_b128 v[216:219], v144 offset:32768
	ds_read_b128 v[220:223], v144 offset:33792
	global_load_lds_dwordx4 v224, s[86:87]
	v_add_u32_e32 v224, s92, v134
	s_add_i32 m0, s100, 0x6000
	s_nop 0
	global_load_lds_dwordx4 v224, s[86:87]
	s_waitcnt lgkmcnt(8)
	s_barrier
	s_waitcnt lgkmcnt(0)
	v_mfma_f32_16x16x32_bf16 v[124:127], v[190:193], v[174:177], v[124:127]
	v_mfma_f32_16x16x32_bf16 v[120:123], v[190:193], v[182:185], v[120:123]
	v_mfma_f32_16x16x32_bf16 v[116:119], v[200:203], v[174:177], v[116:119]
	v_mfma_f32_16x16x32_bf16 v[112:115], v[200:203], v[182:185], v[112:115]
	v_mfma_f32_16x16x32_bf16 v[108:111], v[208:211], v[174:177], v[108:111]
	v_mfma_f32_16x16x32_bf16 v[104:107], v[208:211], v[182:185], v[104:107]
	v_mfma_f32_16x16x32_bf16 v[100:103], v[216:219], v[174:177], v[100:103]
	v_mfma_f32_16x16x32_bf16 v[96:99], v[216:219], v[182:185], v[96:99]
	v_mfma_f32_16x16x32_bf16 v[124:127], v[196:199], v[178:181], v[124:127]
	v_mfma_f32_16x16x32_bf16 v[120:123], v[196:199], v[186:189], v[120:123]
	v_mfma_f32_16x16x32_bf16 v[116:119], v[204:207], v[178:181], v[116:119]
	v_mfma_f32_16x16x32_bf16 v[112:115], v[204:207], v[186:189], v[112:115]
	v_mfma_f32_16x16x32_bf16 v[108:111], v[212:215], v[178:181], v[108:111]
	v_mfma_f32_16x16x32_bf16 v[104:107], v[212:215], v[186:189], v[104:107]
	v_mfma_f32_16x16x32_bf16 v[100:103], v[220:223], v[178:181], v[100:103]
	v_mfma_f32_16x16x32_bf16 v[96:99], v[220:223], v[186:189], v[96:99]
	s_barrier
	v_add_u32_e32 v248, s94, v140
	s_add_i32 m0, s100, 0x18000
	ds_read_b128 v[224:227], v148
	ds_read_b128 v[228:231], v148 offset:1024
	ds_read_b128 v[232:235], v148 offset:2048
	ds_read_b128 v[236:239], v148 offset:3072
	global_load_lds_dwordx4 v248, s[86:87]
	v_add_u32_e32 v248, s94, v138
	s_add_i32 m0, s100, 0x1a000
	s_nop 0
	global_load_lds_dwordx4 v248, s[86:87]
	s_barrier
	s_waitcnt lgkmcnt(0)
	v_mfma_f32_16x16x32_bf16 v[92:95], v[190:193], v[224:227], v[92:95]
	v_mfma_f32_16x16x32_bf16 v[88:91], v[190:193], v[232:235], v[88:91]
	v_mfma_f32_16x16x32_bf16 v[84:87], v[200:203], v[224:227], v[84:87]
	v_mfma_f32_16x16x32_bf16 v[80:83], v[200:203], v[232:235], v[80:83]
	v_mfma_f32_16x16x32_bf16 v[76:79], v[208:211], v[224:227], v[76:79]
	v_mfma_f32_16x16x32_bf16 v[72:75], v[208:211], v[232:235], v[72:75]
	v_mfma_f32_16x16x32_bf16 v[68:71], v[216:219], v[224:227], v[68:71]
	v_mfma_f32_16x16x32_bf16 v[64:67], v[216:219], v[232:235], v[64:67]
	v_mfma_f32_16x16x32_bf16 v[92:95], v[196:199], v[228:231], v[92:95]
	v_mfma_f32_16x16x32_bf16 v[88:91], v[196:199], v[236:239], v[88:91]
	v_mfma_f32_16x16x32_bf16 v[84:87], v[204:207], v[228:231], v[84:87]
	v_mfma_f32_16x16x32_bf16 v[80:83], v[204:207], v[236:239], v[80:83]
	v_mfma_f32_16x16x32_bf16 v[76:79], v[212:215], v[228:231], v[76:79]
	v_mfma_f32_16x16x32_bf16 v[72:75], v[212:215], v[236:239], v[72:75]
	v_mfma_f32_16x16x32_bf16 v[68:71], v[220:223], v[228:231], v[68:71]
	v_mfma_f32_16x16x32_bf16 v[64:67], v[220:223], v[236:239], v[64:67]
	v_add_u32_e32 v240, vcc_lo, v136
	s_add_i32 m0, s100, 0x8000
	s_barrier
	ds_read_b128 v[190:193], v147 offset:49152
	ds_read_b128 v[196:199], v147 offset:50176
	ds_read_b128 v[200:203], v146 offset:49152
	ds_read_b128 v[204:207], v146 offset:50176
	ds_read_b128 v[208:211], v145 offset:49152
	ds_read_b128 v[212:215], v145 offset:50176
	ds_read_b128 v[216:219], v144 offset:49152
	ds_read_b128 v[220:223], v144 offset:50176
	global_load_lds_dwordx4 v240, s[86:87]
	v_add_u32_e32 v240, vcc_lo, v134
	s_add_i32 m0, s100, 0xa000
	s_nop 0
	global_load_lds_dwordx4 v240, s[86:87]
	s_barrier
; #define P8_STAGE(P,BASE,br,kt) do{const bfr* _ub=(BASE)+((long)(br)*K+(long)(kt)*BK); \
;     __builtin_amdgcn_global_load_lds((const unsigned*)(_ub+so0),(unsigned*)((char*)(P)+wid*1024),16,0,0); \
;     __builtin_amdgcn_global_load_lds((const unsigned*)(_ub+so1),(unsigned*)((char*)(P)+wid*1024+8192),16,0,0);}while(0)
; #define P8_LDA(dst,b,h) _Pragma("unroll") for(int m=0;m<4;++m) _Pragma("unroll") for(int k=0;k<2;++k) \
;     dst[m][k]=*reinterpret_cast<const bf16x8*>((char*)P8_SA(b,h)+lds_byte(wr*64+m*16+fr,k*32+fq*8))
; #define P8_LDB(dst,b,h) _Pragma("unroll") for(int n=0;n<2;++n) _Pragma("unroll") for(int k=0;k<2;++k) \
;     dst[n][k]=*reinterpret_cast<const bf16x8*>((char*)P8_SB(b,h)+lds_byte(wc*32+n*16+fr,k*32+fq*8))
; #define P8_MMA(ai,bj,At,Bt) do{__builtin_amdgcn_s_setprio(1); \
;     _Pragma("unroll") for(int m=0;m<4;++m) _Pragma("unroll") for(int n=0;n<2;++n) _Pragma("unroll") for(int k=0;k<2;++k) \
;       acc[ai][bj][m][n]=__builtin_amdgcn_mfma_f32_16x16x32_bf16(At[m][k],Bt[n][k],acc[ai][bj][m][n],0,0,0); \
;     __builtin_amdgcn_s_setprio(0);}while(0)
; #define P8_WAIT_V(n) asm volatile("s_waitcnt vmcnt(" #n ")":::"memory")
; #define P8_WAIT_L(n) asm volatile("s_waitcnt lgkmcnt(" #n ")":::"memory")
; #define P8_BAR __builtin_amdgcn_s_barrier()
; #define P8_SCHED __builtin_amdgcn_sched_barrier(0)
; template <class EPI>
; DEVI void gemm8_tile(const bfr* __restrict__ A, const bfr* __restrict__ Bt, int K, int brow, int bcol, int nbrow, int nbcol, char* shmc, EPI epi) {
;     ...
;     P8_BAR; P8_WAIT_L(0); P8_MMA(1,0,At,B0); P8_BAR; P8_SCHED;
;     P8_STAGE(P8_SB(1,1),Bt,bcol+128,t+3);
;     P8_WAIT_V(6); P8_BAR; P8_MMA(1,1,At,B1); P8_BAR;
;   }
;   { P8_LDB(B0,0,0); P8_LDA(At,0,0); P8_STAGE(P8_SA(1,1),A,brow+128,nt-1);
;     P8_BAR; P8_WAIT_L(0); P8_MMA(0,0,At,B0); P8_BAR;
	s_waitcnt lgkmcnt(0)
	v_mfma_f32_16x16x32_bf16 v[60:63], v[190:193], v[174:177], v[60:63]
	v_mfma_f32_16x16x32_bf16 v[56:59], v[190:193], v[182:185], v[56:59]
	v_mfma_f32_16x16x32_bf16 v[52:55], v[200:203], v[174:177], v[52:55]
	v_mfma_f32_16x16x32_bf16 v[48:51], v[200:203], v[182:185], v[48:51]
	v_mfma_f32_16x16x32_bf16 v[44:47], v[208:211], v[174:177], v[44:47]
	v_mfma_f32_16x16x32_bf16 v[40:43], v[208:211], v[182:185], v[40:43]
	v_mfma_f32_16x16x32_bf16 v[36:39], v[216:219], v[174:177], v[36:39]
	v_mfma_f32_16x16x32_bf16 v[32:35], v[216:219], v[182:185], v[32:35]
	v_mfma_f32_16x16x32_bf16 v[60:63], v[196:199], v[178:181], v[60:63]
	v_mfma_f32_16x16x32_bf16 v[56:59], v[196:199], v[186:189], v[56:59]
	v_mfma_f32_16x16x32_bf16 v[52:55], v[204:207], v[178:181], v[52:55]
	v_mfma_f32_16x16x32_bf16 v[48:51], v[204:207], v[186:189], v[48:51]
	v_mfma_f32_16x16x32_bf16 v[44:47], v[212:215], v[178:181], v[44:47]
	v_mfma_f32_16x16x32_bf16 v[40:43], v[212:215], v[186:189], v[40:43]
	v_mfma_f32_16x16x32_bf16 v[36:39], v[220:223], v[178:181], v[36:39]
	v_mfma_f32_16x16x32_bf16 v[32:35], v[220:223], v[186:189], v[32:35]
	s_barrier
	v_add_u32_e32 v174, s96, v140
	s_add_i32 m0, s100, 0x1c000
	s_nop 0
	global_load_lds_dwordx4 v174, s[86:87]
	v_add_u32_e32 v174, s96, v138
	s_add_i32 m0, s100, 0x1e000
	s_nop 0
	global_load_lds_dwordx4 v174, s[86:87]
	s_waitcnt vmcnt(6)
	s_barrier
	v_mfma_f32_16x16x32_bf16 v[28:31], v[190:193], v[224:227], v[28:31]
	v_mfma_f32_16x16x32_bf16 v[24:27], v[190:193], v[232:235], v[24:27]
	v_mfma_f32_16x16x32_bf16 v[20:23], v[200:203], v[224:227], v[20:23]
	v_mfma_f32_16x16x32_bf16 v[16:19], v[200:203], v[232:235], v[16:19]
	v_mfma_f32_16x16x32_bf16 v[12:15], v[208:211], v[224:227], v[12:15]
	v_mfma_f32_16x16x32_bf16 v[8:11], v[208:211], v[232:235], v[8:11]
	v_mfma_f32_16x16x32_bf16 v[4:7], v[216:219], v[224:227], v[4:7]
	v_mfma_f32_16x16x32_bf16 v[0:3], v[216:219], v[232:235], v[0:3]
	v_mfma_f32_16x16x32_bf16 v[28:31], v[196:199], v[228:231], v[28:31]
	v_mfma_f32_16x16x32_bf16 v[24:27], v[196:199], v[236:239], v[24:27]
	v_mfma_f32_16x16x32_bf16 v[20:23], v[204:207], v[228:231], v[20:23]
	v_mfma_f32_16x16x32_bf16 v[16:19], v[204:207], v[236:239], v[16:19]
	v_mfma_f32_16x16x32_bf16 v[12:15], v[212:215], v[228:231], v[12:15]
	v_mfma_f32_16x16x32_bf16 v[8:11], v[212:215], v[236:239], v[8:11]
	v_mfma_f32_16x16x32_bf16 v[4:7], v[220:223], v[228:231], v[4:7]
	v_mfma_f32_16x16x32_bf16 v[0:3], v[220:223], v[236:239], v[0:3]
	s_add_i32 s0, s0, 2
	v_lshl_add_u64 v[134:135], v[134:135], 0, s[80:81]
	v_lshl_add_u64 v[136:137], v[136:137], 0, s[80:81]
	v_lshl_add_u64 v[138:139], v[138:139], 0, s[80:81]
	s_cmp_lt_u32 s0, 4
	v_lshl_add_u64 v[140:141], v[140:141], 0, s[80:81]
	s_barrier
	s_cbranch_scc1 .LBB0_175
	v_add_u32_e32 v171, 0xc000, v143
	v_add_u32_e32 v172, 0xe000, v143
	v_add_u32_e32 v158, 0x10000, v143
	v_add_u32_e32 v159, 0x12000, v143
	v_add_u32_e32 v160, 0x2000, v143
	v_add_u32_e32 v161, 0x14000, v143
	v_add_u32_e32 v162, 0x16000, v143
	v_add_u32_e32 v163, 0x4000, v143
	v_add_u32_e32 v170, 0x6000, v143
	s_or_b32 s0, s34, 0x80
	s_ashr_i32 s1, s0, 31
	s_lshl_b64 s[0:1], s[0:1], 10
	s_add_u32 s0, s29, s0
	s_addc_u32 s1, s64, s1
	ds_read_b128 v[134:137], v157
	ds_read_b128 v[138:141], v157 offset:1024
	ds_read_b128 v[150:153], v157 offset:2048
	ds_read_b128 v[174:177], v157 offset:3072
	ds_read_b128 v[178:181], v147
	ds_read_b128 v[182:185], v147 offset:1024
	ds_read_b128 v[186:189], v146
	ds_read_b128 v[190:193], v146 offset:1024
	ds_read_b128 v[196:199], v145
	ds_read_b128 v[200:203], v145 offset:1024
	ds_read_b128 v[204:207], v144
	ds_read_b128 v[208:211], v144 offset:1024
	v_lshl_add_u64 v[156:157], v[166:167], 1, s[0:1]
	s_mov_b64 s[34:35], 0x380
	v_lshl_add_u64 v[156:157], v[156:157], 0, s[34:35]
	s_add_i32 m0, s100, 0xc000
	v_lshl_add_u64 v[132:133], v[132:133], 1, s[0:1]
	global_load_lds_dwordx4 v[156:157], off
	v_lshl_add_u64 v[132:133], v[132:133], 0, s[34:35]
	s_add_i32 m0, s100, 0xe000
	s_nop 0
	global_load_lds_dwordx4 v[132:133], off
	s_barrier
	s_waitcnt lgkmcnt(0)
	s_setprio 1
	s_waitcnt lgkmcnt(0)
	v_mfma_f32_16x16x32_bf16 v[124:127], v[178:181], v[134:137], v[124:127]
	v_mfma_f32_16x16x32_bf16 v[120:123], v[178:181], v[150:153], v[120:123]
	v_mfma_f32_16x16x32_bf16 v[116:119], v[186:189], v[134:137], v[116:119]
	v_mfma_f32_16x16x32_bf16 v[108:111], v[196:199], v[134:137], v[108:111]
	v_mfma_f32_16x16x32_bf16 v[124:127], v[182:185], v[138:141], v[124:127]
	v_mfma_f32_16x16x32_bf16 v[120:123], v[182:185], v[174:177], v[120:123]
	v_mfma_f32_16x16x32_bf16 v[116:119], v[190:193], v[138:141], v[116:119]
	v_mfma_f32_16x16x32_bf16 v[112:115], v[186:189], v[150:153], v[112:115]
	v_mfma_f32_16x16x32_bf16 v[108:111], v[200:203], v[138:141], v[108:111]
	v_mfma_f32_16x16x32_bf16 v[104:107], v[196:199], v[150:153], v[104:107]
	v_mfma_f32_16x16x32_bf16 v[100:103], v[204:207], v[134:137], v[100:103]
	v_mfma_f32_16x16x32_bf16 v[96:99], v[204:207], v[150:153], v[96:99]
	v_mfma_f32_16x16x32_bf16 v[212:215], v[190:193], v[174:177], v[112:115]
	v_mfma_f32_16x16x32_bf16 v[104:107], v[200:203], v[174:177], v[104:107]
	v_mfma_f32_16x16x32_bf16 v[216:219], v[208:211], v[138:141], v[100:103]
	v_mfma_f32_16x16x32_bf16 v[220:223], v[208:211], v[174:177], v[96:99]
	s_setprio 0
	s_barrier
	s_nop 1
	ds_read_b128 v[96:99], v154
	ds_read_b128 v[100:103], v154 offset:1024
	ds_read_b128 v[112:115], v154 offset:2048
	ds_read_b128 v[154:157], v154 offset:3072
	s_barrier
; #define P8_LDA(dst,b,h) _Pragma("unroll") for(int m=0;m<4;++m) _Pragma("unroll") for(int k=0;k<2;++k) \
;     dst[m][k]=*reinterpret_cast<const bf16x8*>((char*)P8_SA(b,h)+lds_byte(wr*64+m*16+fr,k*32+fq*8))
; #define P8_LDB(dst,b,h) _Pragma("unroll") for(int n=0;n<2;++n) _Pragma("unroll") for(int k=0;k<2;++k) \
;     dst[n][k]=*reinterpret_cast<const bf16x8*>((char*)P8_SB(b,h)+lds_byte(wc*32+n*16+fr,k*32+fq*8))
; #define P8_MMA(ai,bj,At,Bt) do{__builtin_amdgcn_s_setprio(1); \
;     _Pragma("unroll") for(int m=0;m<4;++m) _Pragma("unroll") for(int n=0;n<2;++n) _Pragma("unroll") for(int k=0;k<2;++k) \
;       acc[ai][bj][m][n]=__builtin_amdgcn_mfma_f32_16x16x32_bf16(At[m][k],Bt[n][k],acc[ai][bj][m][n],0,0,0); \
;     __builtin_amdgcn_s_setprio(0);}while(0)
; #define P8_WAIT_V(n) asm volatile("s_waitcnt vmcnt(" #n ")":::"memory")
; #define P8_WAIT_L(n) asm volatile("s_waitcnt lgkmcnt(" #n ")":::"memory")
; #define P8_BAR __builtin_amdgcn_s_barrier()
; template <class EPI>
; DEVI void gemm8_tile(const bfr* __restrict__ A, const bfr* __restrict__ Bt, int K, int brow, int bcol, int nbrow, int nbcol, char* shmc, EPI epi) {
;     ...
;     P8_LDB(B1,0,1); P8_BAR; P8_WAIT_L(0); P8_MMA(0,1,At,B1); P8_BAR;
;     P8_LDA(At,0,1); P8_WAIT_V(4); P8_BAR; P8_WAIT_L(0); P8_MMA(1,0,At,B0); P8_MMA(1,1,At,B1); P8_BAR; }
;   { P8_LDB(B0,1,0); P8_LDA(At,1,0); P8_WAIT_V(2); P8_BAR; P8_WAIT_L(0); P8_MMA(0,0,At,B0); P8_BAR;
	s_waitcnt lgkmcnt(0)
	s_setprio 1
	s_waitcnt lgkmcnt(0)
	v_mfma_f32_16x16x32_bf16 v[88:91], v[178:181], v[112:115], v[88:91]
	v_mfma_f32_16x16x32_bf16 v[84:87], v[186:189], v[96:99], v[84:87]
	v_mfma_f32_16x16x32_bf16 v[76:79], v[196:199], v[96:99], v[76:79]
	v_mfma_f32_16x16x32_bf16 v[72:75], v[196:199], v[112:115], v[72:75]
	v_mfma_f32_16x16x32_bf16 v[92:95], v[178:181], v[96:99], v[92:95]
	v_mfma_f32_16x16x32_bf16 v[88:91], v[182:185], v[154:157], v[88:91]
	v_mfma_f32_16x16x32_bf16 v[84:87], v[190:193], v[100:103], v[84:87]
	v_mfma_f32_16x16x32_bf16 v[80:83], v[186:189], v[112:115], v[80:83]
	v_mfma_f32_16x16x32_bf16 v[76:79], v[200:203], v[100:103], v[76:79]
	v_mfma_f32_16x16x32_bf16 v[72:75], v[200:203], v[154:157], v[72:75]
	v_mfma_f32_16x16x32_bf16 v[68:71], v[204:207], v[96:99], v[68:71]
	v_mfma_f32_16x16x32_bf16 v[64:67], v[204:207], v[112:115], v[64:67]
	v_mfma_f32_16x16x32_bf16 v[224:227], v[182:185], v[100:103], v[92:95]
	v_mfma_f32_16x16x32_bf16 v[178:181], v[190:193], v[154:157], v[80:83]
	v_mfma_f32_16x16x32_bf16 v[182:185], v[208:211], v[100:103], v[68:71]
	v_mfma_f32_16x16x32_bf16 v[186:189], v[208:211], v[154:157], v[64:67]
	s_setprio 0
	s_barrier
	s_nop 1
	ds_read_b128 v[64:67], v147 offset:16384
	ds_read_b128 v[68:71], v147 offset:17408
	ds_read_b128 v[80:83], v146 offset:16384
	ds_read_b128 v[92:95], v146 offset:17408
	ds_read_b128 v[190:193], v145 offset:16384
	ds_read_b128 v[196:199], v145 offset:17408
	ds_read_b128 v[200:203], v144 offset:16384
	ds_read_b128 v[204:207], v144 offset:17408
	s_waitcnt vmcnt(4)
	s_barrier
	s_waitcnt lgkmcnt(0)
	s_setprio 1
	s_waitcnt lgkmcnt(0)
	v_mfma_f32_16x16x32_bf16 v[60:63], v[64:67], v[134:137], v[60:63]
	v_mfma_f32_16x16x32_bf16 v[56:59], v[64:67], v[150:153], v[56:59]
	v_mfma_f32_16x16x32_bf16 v[52:55], v[80:83], v[134:137], v[52:55]
	v_mfma_f32_16x16x32_bf16 v[40:43], v[190:193], v[150:153], v[40:43]
	v_mfma_f32_16x16x32_bf16 v[36:39], v[200:203], v[134:137], v[36:39]
	v_mfma_f32_16x16x32_bf16 v[208:211], v[68:71], v[138:141], v[60:63]
	v_mfma_f32_16x16x32_bf16 v[56:59], v[68:71], v[174:177], v[56:59]
	v_mfma_f32_16x16x32_bf16 v[52:55], v[92:95], v[138:141], v[52:55]
	v_mfma_f32_16x16x32_bf16 v[48:51], v[80:83], v[150:153], v[48:51]
	v_mfma_f32_16x16x32_bf16 v[44:47], v[190:193], v[134:137], v[44:47]
	v_mfma_f32_16x16x32_bf16 v[40:43], v[196:199], v[174:177], v[40:43]
	v_mfma_f32_16x16x32_bf16 v[36:39], v[204:207], v[138:141], v[36:39]
	v_mfma_f32_16x16x32_bf16 v[32:35], v[200:203], v[150:153], v[32:35]
	v_mfma_f32_16x16x32_bf16 v[228:231], v[92:95], v[174:177], v[48:51]
	v_mfma_f32_16x16x32_bf16 v[232:235], v[196:199], v[138:141], v[44:47]
	v_mfma_f32_16x16x32_bf16 v[132:135], v[204:207], v[174:177], v[32:35]
	s_setprio 0
	s_setprio 1
	v_mfma_f32_16x16x32_bf16 v[24:27], v[64:67], v[112:115], v[24:27]
	v_mfma_f32_16x16x32_bf16 v[20:23], v[80:83], v[96:99], v[20:23]
	v_mfma_f32_16x16x32_bf16 v[8:11], v[190:193], v[112:115], v[8:11]
	v_mfma_f32_16x16x32_bf16 v[28:31], v[64:67], v[96:99], v[28:31]
	v_mfma_f32_16x16x32_bf16 v[24:27], v[68:71], v[154:157], v[24:27]
	v_mfma_f32_16x16x32_bf16 v[20:23], v[92:95], v[100:103], v[20:23]
	v_mfma_f32_16x16x32_bf16 v[16:19], v[80:83], v[112:115], v[16:19]
	v_mfma_f32_16x16x32_bf16 v[12:15], v[190:193], v[96:99], v[12:15]
	v_mfma_f32_16x16x32_bf16 v[8:11], v[196:199], v[154:157], v[8:11]
	v_mfma_f32_16x16x32_bf16 v[4:7], v[200:203], v[96:99], v[4:7]
	v_mfma_f32_16x16x32_bf16 v[0:3], v[200:203], v[112:115], v[0:3]
	v_mfma_f32_16x16x32_bf16 v[136:139], v[68:71], v[100:103], v[28:31]
	v_mfma_f32_16x16x32_bf16 v[150:153], v[92:95], v[154:157], v[16:19]
	v_mfma_f32_16x16x32_bf16 v[172:175], v[196:199], v[100:103], v[12:15]
	v_mfma_f32_16x16x32_bf16 v[190:193], v[204:207], v[100:103], v[4:7]
	v_mfma_f32_16x16x32_bf16 v[154:157], v[204:207], v[154:157], v[0:3]
	s_setprio 0
	s_barrier
	ds_read_b128 v[4:7], v149
	ds_read_b128 v[196:199], v149 offset:1024
	ds_read_b128 v[200:203], v149 offset:2048
	ds_read_b128 v[204:207], v149 offset:3072
	ds_read_b128 v[0:3], v147 offset:32768
	ds_read_b128 v[12:15], v147 offset:33792
	ds_read_b128 v[16:19], v146 offset:32768
	ds_read_b128 v[32:35], v146 offset:33792
	ds_read_b128 v[236:239], v145 offset:32768
	ds_read_b128 v[240:243], v145 offset:33792
	ds_read_b128 v[244:247], v144 offset:32768
	ds_read_b128 v[248:251], v144 offset:33792
	s_waitcnt vmcnt(2)
	s_barrier
; #define P8_LDA(dst,b,h) _Pragma("unroll") for(int m=0;m<4;++m) _Pragma("unroll") for(int k=0;k<2;++k) \
;     dst[m][k]=*reinterpret_cast<const bf16x8*>((char*)P8_SA(b,h)+lds_byte(wr*64+m*16+fr,k*32+fq*8))
; #define P8_LDB(dst,b,h) _Pragma("unroll") for(int n=0;n<2;++n) _Pragma("unroll") for(int k=0;k<2;++k) \
;     dst[n][k]=*reinterpret_cast<const bf16x8*>((char*)P8_SB(b,h)+lds_byte(wc*32+n*16+fr,k*32+fq*8))
; #define P8_MMA(ai,bj,At,Bt) do{__builtin_amdgcn_s_setprio(1); \
;     _Pragma("unroll") for(int m=0;m<4;++m) _Pragma("unroll") for(int n=0;n<2;++n) _Pragma("unroll") for(int k=0;k<2;++k) \
;       acc[ai][bj][m][n]=__builtin_amdgcn_mfma_f32_16x16x32_bf16(At[m][k],Bt[n][k],acc[ai][bj][m][n],0,0,0); \
;     __builtin_amdgcn_s_setprio(0);}while(0)
; #define P8_WAIT_V(n) asm volatile("s_waitcnt vmcnt(" #n ")":::"memory")
; #define P8_WAIT_L(n) asm volatile("s_waitcnt lgkmcnt(" #n ")":::"memory")
; #define P8_BAR __builtin_amdgcn_s_barrier()
; template <class EPI>
; DEVI void gemm8_tile(const bfr* __restrict__ A, const bfr* __restrict__ Bt, int K, int brow, int bcol, int nbrow, int nbcol, char* shmc, EPI epi) {
;     ...
;   { P8_LDB(B0,1,0); P8_LDA(At,1,0); P8_WAIT_V(2); P8_BAR; P8_WAIT_L(0); P8_MMA(0,0,At,B0); P8_BAR;
;     P8_LDB(B1,1,1); P8_WAIT_V(0); P8_BAR; P8_WAIT_L(0); P8_MMA(0,1,At,B1); P8_BAR;
;     P8_LDA(At,1,1); P8_BAR; P8_WAIT_L(0); P8_MMA(1,0,At,B0); P8_MMA(1,1,At,B1); P8_BAR; }
;   if(wr==0)P8_BAR;
	s_waitcnt lgkmcnt(0)
	s_setprio 1
	s_waitcnt lgkmcnt(0)
	v_mfma_f32_16x16x32_bf16 v[28:31], v[0:3], v[4:7], v[124:127]
	v_mfma_f32_16x16x32_bf16 v[124:127], v[12:15], v[196:199], v[28:31]
	v_mfma_f32_16x16x32_bf16 v[28:31], v[0:3], v[200:203], v[120:123]
	v_mfma_f32_16x16x32_bf16 v[92:95], v[12:15], v[204:207], v[28:31]
	v_mfma_f32_16x16x32_bf16 v[28:31], v[16:19], v[4:7], v[116:119]
	v_mfma_f32_16x16x32_bf16 v[112:115], v[32:35], v[196:199], v[28:31]
	v_mfma_f32_16x16x32_bf16 v[28:31], v[16:19], v[200:203], v[212:215]
	v_mfma_f32_16x16x32_bf16 v[80:83], v[32:35], v[204:207], v[28:31]
	v_mfma_f32_16x16x32_bf16 v[28:31], v[236:239], v[4:7], v[108:111]
	v_mfma_f32_16x16x32_bf16 v[100:103], v[240:243], v[196:199], v[28:31]
	v_mfma_f32_16x16x32_bf16 v[28:31], v[236:239], v[200:203], v[104:107]
	v_mfma_f32_16x16x32_bf16 v[68:71], v[240:243], v[204:207], v[28:31]
	v_mfma_f32_16x16x32_bf16 v[28:31], v[244:247], v[4:7], v[216:219]
	v_mfma_f32_16x16x32_bf16 v[96:99], v[248:251], v[196:199], v[28:31]
	v_mfma_f32_16x16x32_bf16 v[28:31], v[244:247], v[200:203], v[220:223]
	v_mfma_f32_16x16x32_bf16 v[64:67], v[248:251], v[204:207], v[28:31]
	s_setprio 0
	s_barrier
	ds_read_b128 v[212:215], v148
	ds_read_b128 v[216:219], v148 offset:1024
	ds_read_b128 v[220:223], v148 offset:2048
	ds_read_b128 v[104:107], v148 offset:3072
	s_waitcnt vmcnt(0)
	s_barrier
	s_waitcnt lgkmcnt(0)
	s_setprio 1
	s_waitcnt lgkmcnt(0)
	v_mfma_f32_16x16x32_bf16 v[28:31], v[0:3], v[212:215], v[224:227]
	v_mfma_f32_16x16x32_bf16 v[0:3], v[0:3], v[220:223], v[88:91]
	v_mfma_f32_16x16x32_bf16 v[60:63], v[12:15], v[216:219], v[28:31]
	v_mfma_f32_16x16x32_bf16 v[28:31], v[12:15], v[104:107], v[0:3]
	v_mfma_f32_16x16x32_bf16 v[0:3], v[16:19], v[212:215], v[84:87]
	v_mfma_f32_16x16x32_bf16 v[48:51], v[32:35], v[216:219], v[0:3]
	v_mfma_f32_16x16x32_bf16 v[0:3], v[16:19], v[220:223], v[178:181]
	v_mfma_f32_16x16x32_bf16 v[16:19], v[32:35], v[104:107], v[0:3]
	v_mfma_f32_16x16x32_bf16 v[0:3], v[236:239], v[212:215], v[76:79]
	v_mfma_f32_16x16x32_bf16 v[44:47], v[240:243], v[216:219], v[0:3]
	v_mfma_f32_16x16x32_bf16 v[0:3], v[236:239], v[220:223], v[72:75]
	v_mfma_f32_16x16x32_bf16 v[12:15], v[240:243], v[104:107], v[0:3]
	v_mfma_f32_16x16x32_bf16 v[0:3], v[244:247], v[212:215], v[182:185]
	v_mfma_f32_16x16x32_bf16 v[32:35], v[248:251], v[216:219], v[0:3]
	v_mfma_f32_16x16x32_bf16 v[0:3], v[244:247], v[220:223], v[186:189]
	v_mfma_f32_16x16x32_bf16 v[0:3], v[248:251], v[104:107], v[0:3]
	s_setprio 0
	s_barrier
	ds_read_b128 v[176:179], v147 offset:49152
	ds_read_b128 v[180:183], v147 offset:50176
	ds_read_b128 v[184:187], v146 offset:49152
	ds_read_b128 v[146:149], v146 offset:50176
	ds_read_b128 v[224:227], v145 offset:49152
	ds_read_b128 v[236:239], v145 offset:50176
	ds_read_b128 v[240:243], v144 offset:49152
	ds_read_b128 v[244:247], v144 offset:50176
	s_barrier
	s_waitcnt lgkmcnt(0)
	s_setprio 1
	s_waitcnt lgkmcnt(0)
	v_mfma_f32_16x16x32_bf16 v[52:55], v[184:187], v[4:7], v[52:55]
	v_mfma_f32_16x16x32_bf16 v[116:119], v[146:149], v[196:199], v[52:55]
	v_mfma_f32_16x16x32_bf16 v[52:55], v[184:187], v[200:203], v[228:231]
	v_mfma_f32_16x16x32_bf16 v[72:75], v[176:179], v[4:7], v[208:211]
	v_mfma_f32_16x16x32_bf16 v[84:87], v[146:149], v[204:207], v[52:55]
	v_mfma_f32_16x16x32_bf16 v[52:55], v[224:227], v[4:7], v[232:235]
	v_mfma_f32_16x16x32_bf16 v[4:7], v[240:243], v[4:7], v[36:39]
	v_mfma_f32_16x16x32_bf16 v[56:59], v[176:179], v[200:203], v[56:59]
	v_mfma_f32_16x16x32_bf16 v[40:43], v[224:227], v[200:203], v[40:43]
	v_mfma_f32_16x16x32_bf16 v[108:111], v[244:247], v[196:199], v[4:7]
	v_mfma_f32_16x16x32_bf16 v[4:7], v[240:243], v[200:203], v[132:135]
	v_mfma_f32_16x16x32_bf16 v[120:123], v[180:183], v[196:199], v[72:75]
	v_mfma_f32_16x16x32_bf16 v[88:91], v[180:183], v[204:207], v[56:59]
	v_mfma_f32_16x16x32_bf16 v[208:211], v[236:239], v[196:199], v[52:55]
	v_mfma_f32_16x16x32_bf16 v[72:75], v[236:239], v[204:207], v[40:43]
	v_mfma_f32_16x16x32_bf16 v[76:79], v[244:247], v[204:207], v[4:7]
	s_setprio 0
	s_setprio 1
	v_mfma_f32_16x16x32_bf16 v[4:7], v[176:179], v[212:215], v[136:139]
	v_mfma_f32_16x16x32_bf16 v[56:59], v[180:183], v[216:219], v[4:7]
	v_mfma_f32_16x16x32_bf16 v[4:7], v[176:179], v[220:223], v[24:27]
	v_mfma_f32_16x16x32_bf16 v[24:27], v[180:183], v[104:107], v[4:7]
	v_mfma_f32_16x16x32_bf16 v[4:7], v[184:187], v[212:215], v[20:23]
	v_mfma_f32_16x16x32_bf16 v[52:55], v[146:149], v[216:219], v[4:7]
	v_mfma_f32_16x16x32_bf16 v[4:7], v[184:187], v[220:223], v[150:153]
	v_mfma_f32_16x16x32_bf16 v[20:23], v[146:149], v[104:107], v[4:7]
	v_mfma_f32_16x16x32_bf16 v[4:7], v[224:227], v[212:215], v[172:175]
	v_mfma_f32_16x16x32_bf16 v[36:39], v[236:239], v[216:219], v[4:7]
	v_mfma_f32_16x16x32_bf16 v[4:7], v[224:227], v[220:223], v[8:11]
	v_mfma_f32_16x16x32_bf16 v[8:11], v[240:243], v[212:215], v[190:193]
	v_mfma_f32_16x16x32_bf16 v[40:43], v[244:247], v[216:219], v[8:11]
	v_mfma_f32_16x16x32_bf16 v[8:11], v[240:243], v[220:223], v[154:157]
	v_mfma_f32_16x16x32_bf16 v[4:7], v[236:239], v[104:107], v[4:7]
	v_mfma_f32_16x16x32_bf16 v[8:11], v[244:247], v[104:107], v[8:11]
	s_setprio 0
	v_cmp_gt_u32_e32 vcc, s57, v142
	s_barrier
	s_and_saveexec_b64 s[0:1], vcc
	s_cbranch_execz .LBB0_178
	s_barrier

; #define P8_STAGE(P,BASE,br,kt) do{const bfr* _ub=(BASE)+((long)(br)*K+(long)(kt)*BK); \
;     __builtin_amdgcn_global_load_lds((const unsigned*)(_ub+so0),(unsigned*)((char*)(P)+wid*1024),16,0,0); \
;     __builtin_amdgcn_global_load_lds((const unsigned*)(_ub+so1),(unsigned*)((char*)(P)+wid*1024+8192),16,0,0);}while(0)
; #define P8_LDA(dst,b,h) _Pragma("unroll") for(int m=0;m<4;++m) _Pragma("unroll") for(int k=0;k<2;++k) \
;     dst[m][k]=*reinterpret_cast<const bf16x8*>((char*)P8_SA(b,h)+lds_byte(wr*64+m*16+fr,k*32+fq*8))
; #define P8_LDB(dst,b,h) _Pragma("unroll") for(int n=0;n<2;++n) _Pragma("unroll") for(int k=0;k<2;++k) \
;     dst[n][k]=*reinterpret_cast<const bf16x8*>((char*)P8_SB(b,h)+lds_byte(wc*32+n*16+fr,k*32+fq*8))
; #define P8_MMA(ai,bj,At,Bt) do{__builtin_amdgcn_s_setprio(1); \
;     _Pragma("unroll") for(int m=0;m<4;++m) _Pragma("unroll") for(int n=0;n<2;++n) _Pragma("unroll") for(int k=0;k<2;++k) \
;       acc[ai][bj][m][n]=__builtin_amdgcn_mfma_f32_16x16x32_bf16(At[m][k],Bt[n][k],acc[ai][bj][m][n],0,0,0); \
;     __builtin_amdgcn_s_setprio(0);}while(0)
; #define P8_WAIT_V(n) asm volatile("s_waitcnt vmcnt(" #n ")":::"memory")
; #define P8_WAIT_L(n) asm volatile("s_waitcnt lgkmcnt(" #n ")":::"memory")
; #define P8_BAR __builtin_amdgcn_s_barrier()
; #define P8_SCHED __builtin_amdgcn_sched_barrier(0)
; template <class EPI>
; DEVI void gemm8_tile(const bfr* __restrict__ A, const bfr* __restrict__ Bt, int K, int brow, int bcol, int nbrow, int nbcol, char* shmc, EPI epi) {
;     ...
;     P8_LDB(B0,0,0); P8_SCHED; P8_LDA(At,0,0); P8_STAGE(P8_SA(1,1),A,brow+128,t+1);
;     P8_WAIT_L(8); P8_BAR; P8_WAIT_L(0); P8_MMA(0,0,At,B0); P8_BAR; P8_SCHED;
;     P8_LDB(B1,0,1); P8_STAGE(P8_SB(0,0),Bt,bcol,t+2);
;     P8_BAR; P8_WAIT_L(0); P8_MMA(0,1,At,B1); P8_BAR;
;     P8_LDA(At,0,1); P8_STAGE(P8_SA(0,0),A,brow,t+2);
;     P8_BAR; P8_WAIT_L(0); P8_MMA(1,0,At,B0); P8_BAR; P8_SCHED;
;     P8_STAGE(P8_SB(0,1),Bt,bcol+128,t+2);
;     P8_WAIT_V(6); P8_BAR; P8_MMA(1,1,At,B1); P8_BAR;
.LBB0_221:
	ds_read_b128 v[174:177], v157
	ds_read_b128 v[178:181], v157 offset:1024
	ds_read_b128 v[182:185], v157 offset:2048
	ds_read_b128 v[186:189], v157 offset:3072
	v_add_u32_e32 v158, s54, v136
	s_add_i32 m0, s100, 0xc000
	ds_read_b128 v[160:163], v147
	ds_read_b128 v[190:193], v147 offset:1024
	ds_read_b128 v[196:199], v146
	ds_read_b128 v[208:211], v146 offset:1024
	ds_read_b128 v[212:215], v145
	ds_read_b128 v[216:219], v145 offset:1024
	ds_read_b128 v[220:223], v144
	ds_read_b128 v[224:227], v144 offset:1024
	global_load_lds_dwordx4 v158, s[86:87]
	v_add_u32_e32 v158, s54, v134
	s_add_i32 m0, s100, 0xe000
	s_nop 0
	global_load_lds_dwordx4 v158, s[86:87]
	s_waitcnt lgkmcnt(8)
	s_barrier
	s_waitcnt lgkmcnt(0)
	v_mfma_f32_16x16x32_bf16 v[124:127], v[160:163], v[174:177], v[124:127]
	v_mfma_f32_16x16x32_bf16 v[120:123], v[160:163], v[182:185], v[120:123]
	v_mfma_f32_16x16x32_bf16 v[116:119], v[196:199], v[174:177], v[116:119]
	v_mfma_f32_16x16x32_bf16 v[112:115], v[196:199], v[182:185], v[112:115]
	v_mfma_f32_16x16x32_bf16 v[108:111], v[212:215], v[174:177], v[108:111]
	v_mfma_f32_16x16x32_bf16 v[104:107], v[212:215], v[182:185], v[104:107]
	v_mfma_f32_16x16x32_bf16 v[100:103], v[220:223], v[174:177], v[100:103]
	v_mfma_f32_16x16x32_bf16 v[96:99], v[220:223], v[182:185], v[96:99]
	v_mfma_f32_16x16x32_bf16 v[124:127], v[190:193], v[178:181], v[124:127]
	v_mfma_f32_16x16x32_bf16 v[120:123], v[190:193], v[186:189], v[120:123]
	v_mfma_f32_16x16x32_bf16 v[116:119], v[208:211], v[178:181], v[116:119]
	v_mfma_f32_16x16x32_bf16 v[112:115], v[208:211], v[186:189], v[112:115]
	v_mfma_f32_16x16x32_bf16 v[108:111], v[216:219], v[178:181], v[108:111]
	v_mfma_f32_16x16x32_bf16 v[104:107], v[216:219], v[186:189], v[104:107]
	v_mfma_f32_16x16x32_bf16 v[100:103], v[224:227], v[178:181], v[100:103]
	v_mfma_f32_16x16x32_bf16 v[96:99], v[224:227], v[186:189], v[96:99]
	s_barrier
	v_add_u32_e32 v206, s66, v140
	s_add_i32 m0, s100, 0x10000
	ds_read_b128 v[228:231], v155
	ds_read_b128 v[232:235], v155 offset:1024
	ds_read_b128 v[236:239], v155 offset:2048
	ds_read_b128 v[240:243], v155 offset:3072
	global_load_lds_dwordx4 v206, s[86:87]
	v_add_u32_e32 v244, s66, v138
	s_add_i32 m0, s100, 0x12000
	s_nop 0
	global_load_lds_dwordx4 v244, s[86:87]
	s_barrier
	s_waitcnt lgkmcnt(0)
	v_mfma_f32_16x16x32_bf16 v[92:95], v[160:163], v[228:231], v[92:95]
	v_mfma_f32_16x16x32_bf16 v[88:91], v[160:163], v[236:239], v[88:91]
	v_mfma_f32_16x16x32_bf16 v[84:87], v[196:199], v[228:231], v[84:87]
	v_mfma_f32_16x16x32_bf16 v[80:83], v[196:199], v[236:239], v[80:83]
	v_mfma_f32_16x16x32_bf16 v[76:79], v[212:215], v[228:231], v[76:79]
	v_mfma_f32_16x16x32_bf16 v[72:75], v[212:215], v[236:239], v[72:75]
	v_mfma_f32_16x16x32_bf16 v[68:71], v[220:223], v[228:231], v[68:71]
	v_mfma_f32_16x16x32_bf16 v[64:67], v[220:223], v[236:239], v[64:67]
	v_mfma_f32_16x16x32_bf16 v[92:95], v[190:193], v[232:235], v[92:95]
	v_mfma_f32_16x16x32_bf16 v[88:91], v[190:193], v[240:243], v[88:91]
	v_mfma_f32_16x16x32_bf16 v[84:87], v[208:211], v[232:235], v[84:87]
	v_mfma_f32_16x16x32_bf16 v[80:83], v[208:211], v[240:243], v[80:83]
	v_mfma_f32_16x16x32_bf16 v[76:79], v[216:219], v[232:235], v[76:79]
	v_mfma_f32_16x16x32_bf16 v[72:75], v[216:219], v[240:243], v[72:75]
	v_mfma_f32_16x16x32_bf16 v[68:71], v[224:227], v[232:235], v[68:71]
	v_mfma_f32_16x16x32_bf16 v[64:67], v[224:227], v[240:243], v[64:67]
	v_add_u32_e32 v160, s80, v136
	s_mov_b32 m0, s100
	s_barrier
	ds_read_b128 v[190:193], v147 offset:16384
	ds_read_b128 v[196:199], v147 offset:17408
	ds_read_b128 v[208:211], v146 offset:16384
	ds_read_b128 v[212:215], v146 offset:17408
	ds_read_b128 v[216:219], v145 offset:16384
	ds_read_b128 v[220:223], v145 offset:17408
	ds_read_b128 v[224:227], v144 offset:16384
	ds_read_b128 v[244:247], v144 offset:17408
	global_load_lds_dwordx4 v160, s[86:87]
	v_add_u32_e32 v162, s80, v134
	s_add_i32 m0, s100, 0x2000
	s_nop 0
	global_load_lds_dwordx4 v162, s[86:87]
	s_barrier
	s_waitcnt lgkmcnt(0)
	v_mfma_f32_16x16x32_bf16 v[60:63], v[190:193], v[174:177], v[60:63]
	v_mfma_f32_16x16x32_bf16 v[56:59], v[190:193], v[182:185], v[56:59]
	v_mfma_f32_16x16x32_bf16 v[52:55], v[208:211], v[174:177], v[52:55]
	v_mfma_f32_16x16x32_bf16 v[48:51], v[208:211], v[182:185], v[48:51]
	v_mfma_f32_16x16x32_bf16 v[44:47], v[216:219], v[174:177], v[44:47]
	v_mfma_f32_16x16x32_bf16 v[40:43], v[216:219], v[182:185], v[40:43]
	v_mfma_f32_16x16x32_bf16 v[36:39], v[224:227], v[174:177], v[36:39]
	v_mfma_f32_16x16x32_bf16 v[32:35], v[224:227], v[182:185], v[32:35]
	v_mfma_f32_16x16x32_bf16 v[60:63], v[196:199], v[178:181], v[60:63]
	v_mfma_f32_16x16x32_bf16 v[56:59], v[196:199], v[186:189], v[56:59]
	v_mfma_f32_16x16x32_bf16 v[52:55], v[212:215], v[178:181], v[52:55]
	v_mfma_f32_16x16x32_bf16 v[48:51], v[212:215], v[186:189], v[48:51]
	v_mfma_f32_16x16x32_bf16 v[44:47], v[220:223], v[178:181], v[44:47]
	v_mfma_f32_16x16x32_bf16 v[40:43], v[220:223], v[186:189], v[40:43]
	v_mfma_f32_16x16x32_bf16 v[36:39], v[244:247], v[178:181], v[36:39]
	v_mfma_f32_16x16x32_bf16 v[32:35], v[244:247], v[186:189], v[32:35]
	s_barrier
	v_add_u32_e32 v162, s70, v140
	s_add_i32 m0, s100, 0x14000
	v_add_u32_e32 v174, s70, v138
	global_load_lds_dwordx4 v162, s[86:87]
	s_nop 0
	s_add_i32 m0, s100, 0x16000
	s_nop 0
	global_load_lds_dwordx4 v174, s[86:87]
	s_waitcnt vmcnt(6)
	s_barrier
; #define P8_STAGE(P,BASE,br,kt) do{const bfr* _ub=(BASE)+((long)(br)*K+(long)(kt)*BK); \
;     __builtin_amdgcn_global_load_lds((const unsigned*)(_ub+so0),(unsigned*)((char*)(P)+wid*1024),16,0,0); \
;     __builtin_amdgcn_global_load_lds((const unsigned*)(_ub+so1),(unsigned*)((char*)(P)+wid*1024+8192),16,0,0);}while(0)
; #define P8_LDA(dst,b,h) _Pragma("unroll") for(int m=0;m<4;++m) _Pragma("unroll") for(int k=0;k<2;++k) \
;     dst[m][k]=*reinterpret_cast<const bf16x8*>((char*)P8_SA(b,h)+lds_byte(wr*64+m*16+fr,k*32+fq*8))
; #define P8_LDB(dst,b,h) _Pragma("unroll") for(int n=0;n<2;++n) _Pragma("unroll") for(int k=0;k<2;++k) \
;     dst[n][k]=*reinterpret_cast<const bf16x8*>((char*)P8_SB(b,h)+lds_byte(wc*32+n*16+fr,k*32+fq*8))
; #define P8_MMA(ai,bj,At,Bt) do{__builtin_amdgcn_s_setprio(1); \
;     _Pragma("unroll") for(int m=0;m<4;++m) _Pragma("unroll") for(int n=0;n<2;++n) _Pragma("unroll") for(int k=0;k<2;++k) \
;       acc[ai][bj][m][n]=__builtin_amdgcn_mfma_f32_16x16x32_bf16(At[m][k],Bt[n][k],acc[ai][bj][m][n],0,0,0); \
;     __builtin_amdgcn_s_setprio(0);}while(0)
; #define P8_WAIT_V(n) asm volatile("s_waitcnt vmcnt(" #n ")":::"memory")
; #define P8_WAIT_L(n) asm volatile("s_waitcnt lgkmcnt(" #n ")":::"memory")
; #define P8_BAR __builtin_amdgcn_s_barrier()
; #define P8_SCHED __builtin_amdgcn_sched_barrier(0)
; template <class EPI>
; DEVI void gemm8_tile(const bfr* __restrict__ A, const bfr* __restrict__ Bt, int K, int brow, int bcol, int nbrow, int nbcol, char* shmc, EPI epi) {
;     ...
;     P8_WAIT_V(6); P8_BAR; P8_MMA(1,1,At,B1); P8_BAR;
;     P8_LDB(B0,1,0); P8_SCHED; P8_LDA(At,1,0); P8_STAGE(P8_SA(0,1),A,brow+128,t+2);
;     P8_WAIT_L(8); P8_BAR; P8_WAIT_L(0); P8_MMA(0,0,At,B0); P8_BAR; P8_SCHED;
;     P8_LDB(B1,1,1); P8_STAGE(P8_SB(1,0),Bt,bcol,t+3);
;     P8_BAR; P8_WAIT_L(0); P8_MMA(0,1,At,B1); P8_BAR;
;     P8_LDA(At,1,1); P8_STAGE(P8_SA(1,0),A,brow,t+3);
;     P8_BAR; P8_WAIT_L(0); P8_MMA(1,0,At,B0); P8_BAR; P8_SCHED;
	v_mfma_f32_16x16x32_bf16 v[28:31], v[190:193], v[228:231], v[28:31]
	v_mfma_f32_16x16x32_bf16 v[24:27], v[190:193], v[236:239], v[24:27]
	v_mfma_f32_16x16x32_bf16 v[20:23], v[208:211], v[228:231], v[20:23]
	v_mfma_f32_16x16x32_bf16 v[16:19], v[208:211], v[236:239], v[16:19]
	v_mfma_f32_16x16x32_bf16 v[12:15], v[216:219], v[228:231], v[12:15]
	v_mfma_f32_16x16x32_bf16 v[8:11], v[216:219], v[236:239], v[8:11]
	v_mfma_f32_16x16x32_bf16 v[4:7], v[224:227], v[228:231], v[4:7]
	v_mfma_f32_16x16x32_bf16 v[0:3], v[224:227], v[236:239], v[0:3]
	v_mfma_f32_16x16x32_bf16 v[28:31], v[196:199], v[232:235], v[28:31]
	v_mfma_f32_16x16x32_bf16 v[24:27], v[196:199], v[240:243], v[24:27]
	v_mfma_f32_16x16x32_bf16 v[20:23], v[212:215], v[232:235], v[20:23]
	v_mfma_f32_16x16x32_bf16 v[16:19], v[212:215], v[240:243], v[16:19]
	v_mfma_f32_16x16x32_bf16 v[12:15], v[220:223], v[232:235], v[12:15]
	v_mfma_f32_16x16x32_bf16 v[8:11], v[220:223], v[240:243], v[8:11]
	v_mfma_f32_16x16x32_bf16 v[4:7], v[244:247], v[232:235], v[4:7]
	v_mfma_f32_16x16x32_bf16 v[0:3], v[244:247], v[240:243], v[0:3]
	s_barrier
	ds_read_b128 v[174:177], v149
	ds_read_b128 v[178:181], v149 offset:1024
	ds_read_b128 v[182:185], v149 offset:2048
	ds_read_b128 v[186:189], v149 offset:3072
	v_add_u32_e32 v232, s60, v136
	s_add_i32 m0, s100, 0x4000
	ds_read_b128 v[190:193], v147 offset:32768
	ds_read_b128 v[196:199], v147 offset:33792
	ds_read_b128 v[208:211], v146 offset:32768
	ds_read_b128 v[212:215], v146 offset:33792
	ds_read_b128 v[216:219], v145 offset:32768
	ds_read_b128 v[220:223], v145 offset:33792
	ds_read_b128 v[224:227], v144 offset:32768
	ds_read_b128 v[228:231], v144 offset:33792
	global_load_lds_dwordx4 v232, s[86:87]
	v_add_u32_e32 v232, s60, v134
	s_add_i32 m0, s100, 0x6000
	s_nop 0
	global_load_lds_dwordx4 v232, s[86:87]
	s_waitcnt lgkmcnt(8)
	s_barrier
	s_waitcnt lgkmcnt(0)
	v_mfma_f32_16x16x32_bf16 v[124:127], v[190:193], v[174:177], v[124:127]
	v_mfma_f32_16x16x32_bf16 v[120:123], v[190:193], v[182:185], v[120:123]
	v_mfma_f32_16x16x32_bf16 v[116:119], v[208:211], v[174:177], v[116:119]
	v_mfma_f32_16x16x32_bf16 v[112:115], v[208:211], v[182:185], v[112:115]
	v_mfma_f32_16x16x32_bf16 v[108:111], v[216:219], v[174:177], v[108:111]
	v_mfma_f32_16x16x32_bf16 v[104:107], v[216:219], v[182:185], v[104:107]
	v_mfma_f32_16x16x32_bf16 v[100:103], v[224:227], v[174:177], v[100:103]
	v_mfma_f32_16x16x32_bf16 v[96:99], v[224:227], v[182:185], v[96:99]
	v_mfma_f32_16x16x32_bf16 v[124:127], v[196:199], v[178:181], v[124:127]
	v_mfma_f32_16x16x32_bf16 v[120:123], v[196:199], v[186:189], v[120:123]
	v_mfma_f32_16x16x32_bf16 v[116:119], v[212:215], v[178:181], v[116:119]
	v_mfma_f32_16x16x32_bf16 v[112:115], v[212:215], v[186:189], v[112:115]
	v_mfma_f32_16x16x32_bf16 v[108:111], v[220:223], v[178:181], v[108:111]
	v_mfma_f32_16x16x32_bf16 v[104:107], v[220:223], v[186:189], v[104:107]
	v_mfma_f32_16x16x32_bf16 v[100:103], v[228:231], v[178:181], v[100:103]
	v_mfma_f32_16x16x32_bf16 v[96:99], v[228:231], v[186:189], v[96:99]
	s_barrier
	v_add_u32_e32 v248, s74, v140
	s_add_i32 m0, s100, 0x18000
	ds_read_b128 v[232:235], v148
	ds_read_b128 v[236:239], v148 offset:1024
	ds_read_b128 v[240:243], v148 offset:2048
	ds_read_b128 v[244:247], v148 offset:3072
	global_load_lds_dwordx4 v248, s[86:87]
	v_add_u32_e32 v248, s74, v138
	s_add_i32 m0, s100, 0x1a000
	s_nop 0
	global_load_lds_dwordx4 v248, s[86:87]
	s_barrier
	s_waitcnt lgkmcnt(0)
	v_mfma_f32_16x16x32_bf16 v[92:95], v[190:193], v[232:235], v[92:95]
	v_mfma_f32_16x16x32_bf16 v[88:91], v[190:193], v[240:243], v[88:91]
	v_mfma_f32_16x16x32_bf16 v[84:87], v[208:211], v[232:235], v[84:87]
	v_mfma_f32_16x16x32_bf16 v[80:83], v[208:211], v[240:243], v[80:83]
	v_mfma_f32_16x16x32_bf16 v[76:79], v[216:219], v[232:235], v[76:79]
	v_mfma_f32_16x16x32_bf16 v[72:75], v[216:219], v[240:243], v[72:75]
	v_mfma_f32_16x16x32_bf16 v[68:71], v[224:227], v[232:235], v[68:71]
	v_mfma_f32_16x16x32_bf16 v[64:67], v[224:227], v[240:243], v[64:67]
	v_mfma_f32_16x16x32_bf16 v[92:95], v[196:199], v[236:239], v[92:95]
	v_mfma_f32_16x16x32_bf16 v[88:91], v[196:199], v[244:247], v[88:91]
	v_mfma_f32_16x16x32_bf16 v[84:87], v[212:215], v[236:239], v[84:87]
	v_mfma_f32_16x16x32_bf16 v[80:83], v[212:215], v[244:247], v[80:83]
	v_mfma_f32_16x16x32_bf16 v[76:79], v[220:223], v[236:239], v[76:79]
	v_mfma_f32_16x16x32_bf16 v[72:75], v[220:223], v[244:247], v[72:75]
	v_mfma_f32_16x16x32_bf16 v[68:71], v[228:231], v[236:239], v[68:71]
	v_mfma_f32_16x16x32_bf16 v[64:67], v[228:231], v[244:247], v[64:67]
	v_add_u32_e32 v200, s72, v136
	s_add_i32 m0, s100, 0x8000
	s_barrier
	ds_read_b128 v[190:193], v147 offset:49152
	ds_read_b128 v[196:199], v147 offset:50176
	ds_read_b128 v[208:211], v146 offset:49152
	ds_read_b128 v[212:215], v146 offset:50176
	ds_read_b128 v[216:219], v145 offset:49152
	ds_read_b128 v[220:223], v145 offset:50176
	ds_read_b128 v[224:227], v144 offset:49152
	ds_read_b128 v[228:231], v144 offset:50176
	global_load_lds_dwordx4 v200, s[86:87]
	v_add_u32_e32 v200, s72, v134
	s_add_i32 m0, s100, 0xa000
	s_nop 0
	global_load_lds_dwordx4 v200, s[86:87]
	s_barrier
; #define P8_STAGE(P,BASE,br,kt) do{const bfr* _ub=(BASE)+((long)(br)*K+(long)(kt)*BK); \
;     __builtin_amdgcn_global_load_lds((const unsigned*)(_ub+so0),(unsigned*)((char*)(P)+wid*1024),16,0,0); \
;     __builtin_amdgcn_global_load_lds((const unsigned*)(_ub+so1),(unsigned*)((char*)(P)+wid*1024+8192),16,0,0);}while(0)
; #define P8_LDA(dst,b,h) _Pragma("unroll") for(int m=0;m<4;++m) _Pragma("unroll") for(int k=0;k<2;++k) \
;     dst[m][k]=*reinterpret_cast<const bf16x8*>((char*)P8_SA(b,h)+lds_byte(wr*64+m*16+fr,k*32+fq*8))
; #define P8_LDB(dst,b,h) _Pragma("unroll") for(int n=0;n<2;++n) _Pragma("unroll") for(int k=0;k<2;++k) \
;     dst[n][k]=*reinterpret_cast<const bf16x8*>((char*)P8_SB(b,h)+lds_byte(wc*32+n*16+fr,k*32+fq*8))
; #define P8_MMA(ai,bj,At,Bt) do{__builtin_amdgcn_s_setprio(1); \
;     _Pragma("unroll") for(int m=0;m<4;++m) _Pragma("unroll") for(int n=0;n<2;++n) _Pragma("unroll") for(int k=0;k<2;++k) \
;       acc[ai][bj][m][n]=__builtin_amdgcn_mfma_f32_16x16x32_bf16(At[m][k],Bt[n][k],acc[ai][bj][m][n],0,0,0); \
;     __builtin_amdgcn_s_setprio(0);}while(0)
; #define P8_WAIT_V(n) asm volatile("s_waitcnt vmcnt(" #n ")":::"memory")
; #define P8_WAIT_L(n) asm volatile("s_waitcnt lgkmcnt(" #n ")":::"memory")
; #define P8_BAR __builtin_amdgcn_s_barrier()
; #define P8_SCHED __builtin_amdgcn_sched_barrier(0)
; template <class EPI>
; DEVI void gemm8_tile(const bfr* __restrict__ A, const bfr* __restrict__ Bt, int K, int brow, int bcol, int nbrow, int nbcol, char* shmc, EPI epi) {
;     ...
;     P8_BAR; P8_WAIT_L(0); P8_MMA(1,0,At,B0); P8_BAR; P8_SCHED;
;     P8_STAGE(P8_SB(1,1),Bt,bcol+128,t+3);
;     P8_WAIT_V(6); P8_BAR; P8_MMA(1,1,At,B1); P8_BAR;
;   }
;   { P8_LDB(B0,0,0); P8_LDA(At,0,0); P8_STAGE(P8_SA(1,1),A,brow+128,nt-1);
;     P8_BAR; P8_WAIT_L(0); P8_MMA(0,0,At,B0); P8_BAR;
	s_waitcnt lgkmcnt(0)
	v_mfma_f32_16x16x32_bf16 v[60:63], v[190:193], v[174:177], v[60:63]
	v_mfma_f32_16x16x32_bf16 v[56:59], v[190:193], v[182:185], v[56:59]
	v_mfma_f32_16x16x32_bf16 v[52:55], v[208:211], v[174:177], v[52:55]
	v_mfma_f32_16x16x32_bf16 v[48:51], v[208:211], v[182:185], v[48:51]
	v_mfma_f32_16x16x32_bf16 v[44:47], v[216:219], v[174:177], v[44:47]
	v_mfma_f32_16x16x32_bf16 v[40:43], v[216:219], v[182:185], v[40:43]
	v_mfma_f32_16x16x32_bf16 v[36:39], v[224:227], v[174:177], v[36:39]
	v_mfma_f32_16x16x32_bf16 v[32:35], v[224:227], v[182:185], v[32:35]
	v_mfma_f32_16x16x32_bf16 v[60:63], v[196:199], v[178:181], v[60:63]
	v_mfma_f32_16x16x32_bf16 v[56:59], v[196:199], v[186:189], v[56:59]
	v_mfma_f32_16x16x32_bf16 v[52:55], v[212:215], v[178:181], v[52:55]
	v_mfma_f32_16x16x32_bf16 v[48:51], v[212:215], v[186:189], v[48:51]
	v_mfma_f32_16x16x32_bf16 v[44:47], v[220:223], v[178:181], v[44:47]
	v_mfma_f32_16x16x32_bf16 v[40:43], v[220:223], v[186:189], v[40:43]
	v_mfma_f32_16x16x32_bf16 v[36:39], v[228:231], v[178:181], v[36:39]
	v_mfma_f32_16x16x32_bf16 v[32:35], v[228:231], v[186:189], v[32:35]
	s_barrier
	v_add_u32_e32 v174, s78, v140
	s_add_i32 m0, s100, 0x1c000
	s_nop 0
	global_load_lds_dwordx4 v174, s[86:87]
	v_add_u32_e32 v174, s78, v138
	s_add_i32 m0, s100, 0x1e000
	s_nop 0
	global_load_lds_dwordx4 v174, s[86:87]
	s_waitcnt vmcnt(6)
	s_barrier
	v_mfma_f32_16x16x32_bf16 v[28:31], v[190:193], v[232:235], v[28:31]
	v_mfma_f32_16x16x32_bf16 v[24:27], v[190:193], v[240:243], v[24:27]
	v_mfma_f32_16x16x32_bf16 v[20:23], v[208:211], v[232:235], v[20:23]
	v_mfma_f32_16x16x32_bf16 v[16:19], v[208:211], v[240:243], v[16:19]
	v_mfma_f32_16x16x32_bf16 v[12:15], v[216:219], v[232:235], v[12:15]
	v_mfma_f32_16x16x32_bf16 v[8:11], v[216:219], v[240:243], v[8:11]
	v_mfma_f32_16x16x32_bf16 v[4:7], v[224:227], v[232:235], v[4:7]
	v_mfma_f32_16x16x32_bf16 v[0:3], v[224:227], v[240:243], v[0:3]
	v_mfma_f32_16x16x32_bf16 v[28:31], v[196:199], v[236:239], v[28:31]
	v_mfma_f32_16x16x32_bf16 v[24:27], v[196:199], v[244:247], v[24:27]
	v_mfma_f32_16x16x32_bf16 v[20:23], v[212:215], v[236:239], v[20:23]
	v_mfma_f32_16x16x32_bf16 v[16:19], v[212:215], v[244:247], v[16:19]
	v_mfma_f32_16x16x32_bf16 v[12:15], v[220:223], v[236:239], v[12:15]
	v_mfma_f32_16x16x32_bf16 v[8:11], v[220:223], v[244:247], v[8:11]
	v_mfma_f32_16x16x32_bf16 v[4:7], v[228:231], v[236:239], v[4:7]
	v_mfma_f32_16x16x32_bf16 v[0:3], v[228:231], v[244:247], v[0:3]
	s_add_i32 s0, s0, 2
	v_lshl_add_u64 v[134:135], v[134:135], 0, s[80:81]
	v_lshl_add_u64 v[136:137], v[136:137], 0, s[80:81]
	v_lshl_add_u64 v[138:139], v[138:139], 0, s[80:81]
	s_cmp_lt_u32 s0, 28
	v_lshl_add_u64 v[140:141], v[140:141], 0, s[80:81]
	s_barrier
	s_cbranch_scc1 .LBB0_221
	v_add_u32_e32 v171, 0xc000, v143
	v_add_u32_e32 v172, 0xe000, v143
	v_add_u32_e32 v158, 0x10000, v143
	v_add_u32_e32 v159, 0x12000, v143
	v_add_u32_e32 v160, 0x2000, v143
	v_add_u32_e32 v161, 0x14000, v143
	v_add_u32_e32 v162, 0x16000, v143
	v_add_u32_e32 v163, 0x4000, v143
	v_add_u32_e32 v170, 0x6000, v143
	s_or_b32 s0, s8, 0x80
	s_ashr_i32 s1, s0, 31
	s_lshl_b64 s[0:1], s[0:1], 12
	s_add_u32 s0, s34, s0
	s_addc_u32 s1, s35, s1
	ds_read_b128 v[134:137], v157
	ds_read_b128 v[138:141], v157 offset:1024
	ds_read_b128 v[150:153], v157 offset:2048
	ds_read_b128 v[174:177], v157 offset:3072
	ds_read_b128 v[178:181], v147
	ds_read_b128 v[182:185], v147 offset:1024
	ds_read_b128 v[186:189], v146
	ds_read_b128 v[190:193], v146 offset:1024
	ds_read_b128 v[196:199], v145
	ds_read_b128 v[208:211], v145 offset:1024
	ds_read_b128 v[212:215], v144
	ds_read_b128 v[216:219], v144 offset:1024
	v_lshl_add_u64 v[156:157], v[166:167], 1, s[0:1]
	s_mov_b64 s[54:55], 0xf80
	v_lshl_add_u64 v[156:157], v[156:157], 0, s[54:55]
	s_add_i32 m0, s100, 0xc000
	v_lshl_add_u64 v[132:133], v[132:133], 1, s[0:1]
	global_load_lds_dwordx4 v[156:157], off
	v_lshl_add_u64 v[132:133], v[132:133], 0, s[54:55]
	s_add_i32 m0, s100, 0xe000
	s_nop 0
	global_load_lds_dwordx4 v[132:133], off
	s_barrier
	s_waitcnt lgkmcnt(0)
	s_setprio 1
	s_waitcnt lgkmcnt(0)
	v_mfma_f32_16x16x32_bf16 v[124:127], v[178:181], v[134:137], v[124:127]
	v_mfma_f32_16x16x32_bf16 v[120:123], v[178:181], v[150:153], v[120:123]
	v_mfma_f32_16x16x32_bf16 v[116:119], v[186:189], v[134:137], v[116:119]
	v_mfma_f32_16x16x32_bf16 v[112:115], v[186:189], v[150:153], v[112:115]
	v_mfma_f32_16x16x32_bf16 v[96:99], v[212:215], v[150:153], v[96:99]
	v_mfma_f32_16x16x32_bf16 v[124:127], v[182:185], v[138:141], v[124:127]
	v_mfma_f32_16x16x32_bf16 v[120:123], v[182:185], v[174:177], v[120:123]
	v_mfma_f32_16x16x32_bf16 v[116:119], v[190:193], v[138:141], v[116:119]
	v_mfma_f32_16x16x32_bf16 v[112:115], v[190:193], v[174:177], v[112:115]
	v_mfma_f32_16x16x32_bf16 v[108:111], v[196:199], v[134:137], v[108:111]
	v_mfma_f32_16x16x32_bf16 v[104:107], v[196:199], v[150:153], v[104:107]
	v_mfma_f32_16x16x32_bf16 v[100:103], v[212:215], v[134:137], v[100:103]
	v_mfma_f32_16x16x32_bf16 v[96:99], v[216:219], v[174:177], v[96:99]
	v_mfma_f32_16x16x32_bf16 v[220:223], v[208:211], v[138:141], v[108:111]
	v_mfma_f32_16x16x32_bf16 v[224:227], v[208:211], v[174:177], v[104:107]
	v_mfma_f32_16x16x32_bf16 v[228:231], v[216:219], v[138:141], v[100:103]
	s_setprio 0
	s_barrier
	s_nop 1
	ds_read_b128 v[100:103], v155
	ds_read_b128 v[104:107], v155 offset:1024
	ds_read_b128 v[108:111], v155 offset:2048
	ds_read_b128 v[154:157], v155 offset:3072
	s_barrier
; #define P8_LDA(dst,b,h) _Pragma("unroll") for(int m=0;m<4;++m) _Pragma("unroll") for(int k=0;k<2;++k) \
;     dst[m][k]=*reinterpret_cast<const bf16x8*>((char*)P8_SA(b,h)+lds_byte(wr*64+m*16+fr,k*32+fq*8))
; #define P8_LDB(dst,b,h) _Pragma("unroll") for(int n=0;n<2;++n) _Pragma("unroll") for(int k=0;k<2;++k) \
;     dst[n][k]=*reinterpret_cast<const bf16x8*>((char*)P8_SB(b,h)+lds_byte(wc*32+n*16+fr,k*32+fq*8))
; #define P8_MMA(ai,bj,At,Bt) do{__builtin_amdgcn_s_setprio(1); \
;     _Pragma("unroll") for(int m=0;m<4;++m) _Pragma("unroll") for(int n=0;n<2;++n) _Pragma("unroll") for(int k=0;k<2;++k) \
;       acc[ai][bj][m][n]=__builtin_amdgcn_mfma_f32_16x16x32_bf16(At[m][k],Bt[n][k],acc[ai][bj][m][n],0,0,0); \
;     __builtin_amdgcn_s_setprio(0);}while(0)
; #define P8_WAIT_V(n) asm volatile("s_waitcnt vmcnt(" #n ")":::"memory")
; #define P8_WAIT_L(n) asm volatile("s_waitcnt lgkmcnt(" #n ")":::"memory")
; #define P8_BAR __builtin_amdgcn_s_barrier()
; template <class EPI>
; DEVI void gemm8_tile(const bfr* __restrict__ A, const bfr* __restrict__ Bt, int K, int brow, int bcol, int nbrow, int nbcol, char* shmc, EPI epi) {
;     ...
;     P8_LDB(B1,0,1); P8_BAR; P8_WAIT_L(0); P8_MMA(0,1,At,B1); P8_BAR;
;     P8_LDA(At,0,1); P8_WAIT_V(4); P8_BAR; P8_WAIT_L(0); P8_MMA(1,0,At,B0); P8_MMA(1,1,At,B1); P8_BAR; }
;   { P8_LDB(B0,1,0); P8_LDA(At,1,0); P8_WAIT_V(2); P8_BAR; P8_WAIT_L(0); P8_MMA(0,0,At,B0); P8_BAR;
	s_waitcnt lgkmcnt(0)
	s_setprio 1
	s_waitcnt lgkmcnt(0)
	v_mfma_f32_16x16x32_bf16 v[92:95], v[178:181], v[100:103], v[92:95]
	v_mfma_f32_16x16x32_bf16 v[88:91], v[178:181], v[108:111], v[88:91]
	v_mfma_f32_16x16x32_bf16 v[84:87], v[186:189], v[100:103], v[84:87]
	v_mfma_f32_16x16x32_bf16 v[80:83], v[186:189], v[108:111], v[80:83]
	v_mfma_f32_16x16x32_bf16 v[64:67], v[212:215], v[108:111], v[64:67]
	v_mfma_f32_16x16x32_bf16 v[92:95], v[182:185], v[104:107], v[92:95]
	v_mfma_f32_16x16x32_bf16 v[88:91], v[182:185], v[154:157], v[88:91]
	v_mfma_f32_16x16x32_bf16 v[84:87], v[190:193], v[104:107], v[84:87]
	v_mfma_f32_16x16x32_bf16 v[80:83], v[190:193], v[154:157], v[80:83]
	v_mfma_f32_16x16x32_bf16 v[76:79], v[196:199], v[100:103], v[76:79]
	v_mfma_f32_16x16x32_bf16 v[72:75], v[196:199], v[108:111], v[72:75]
	v_mfma_f32_16x16x32_bf16 v[68:71], v[212:215], v[100:103], v[68:71]
	v_mfma_f32_16x16x32_bf16 v[64:67], v[216:219], v[154:157], v[64:67]
	v_mfma_f32_16x16x32_bf16 v[178:181], v[208:211], v[104:107], v[76:79]
	v_mfma_f32_16x16x32_bf16 v[182:185], v[208:211], v[154:157], v[72:75]
	v_mfma_f32_16x16x32_bf16 v[186:189], v[216:219], v[104:107], v[68:71]
	s_setprio 0
	s_barrier
	s_nop 1
	ds_read_b128 v[68:71], v147 offset:16384
	ds_read_b128 v[72:75], v147 offset:17408
	ds_read_b128 v[76:79], v146 offset:16384
	ds_read_b128 v[190:193], v146 offset:17408
	ds_read_b128 v[196:199], v145 offset:16384
	ds_read_b128 v[208:211], v145 offset:17408
	ds_read_b128 v[212:215], v144 offset:16384
	ds_read_b128 v[216:219], v144 offset:17408
	s_waitcnt vmcnt(4)
	s_barrier
	s_waitcnt lgkmcnt(0)
	s_setprio 1
	s_waitcnt lgkmcnt(0)
	v_mfma_f32_16x16x32_bf16 v[60:63], v[68:71], v[134:137], v[60:63]
	v_mfma_f32_16x16x32_bf16 v[56:59], v[68:71], v[150:153], v[56:59]
	v_mfma_f32_16x16x32_bf16 v[52:55], v[76:79], v[134:137], v[52:55]
	v_mfma_f32_16x16x32_bf16 v[48:51], v[76:79], v[150:153], v[48:51]
	v_mfma_f32_16x16x32_bf16 v[32:35], v[212:215], v[150:153], v[32:35]
	v_mfma_f32_16x16x32_bf16 v[60:63], v[72:75], v[138:141], v[60:63]
	v_mfma_f32_16x16x32_bf16 v[56:59], v[72:75], v[174:177], v[56:59]
	v_mfma_f32_16x16x32_bf16 v[52:55], v[190:193], v[138:141], v[52:55]
	v_mfma_f32_16x16x32_bf16 v[48:51], v[190:193], v[174:177], v[48:51]
	v_mfma_f32_16x16x32_bf16 v[44:47], v[196:199], v[134:137], v[44:47]
	v_mfma_f32_16x16x32_bf16 v[40:43], v[196:199], v[150:153], v[40:43]
	v_mfma_f32_16x16x32_bf16 v[36:39], v[212:215], v[134:137], v[36:39]
	v_mfma_f32_16x16x32_bf16 v[32:35], v[216:219], v[174:177], v[32:35]
	v_mfma_f32_16x16x32_bf16 v[232:235], v[208:211], v[138:141], v[44:47]
	v_mfma_f32_16x16x32_bf16 v[236:239], v[208:211], v[174:177], v[40:43]
	v_mfma_f32_16x16x32_bf16 v[132:135], v[216:219], v[138:141], v[36:39]
	s_setprio 0
	s_setprio 1
	v_mfma_f32_16x16x32_bf16 v[28:31], v[68:71], v[100:103], v[28:31]
	v_mfma_f32_16x16x32_bf16 v[24:27], v[68:71], v[108:111], v[24:27]
	v_mfma_f32_16x16x32_bf16 v[20:23], v[76:79], v[100:103], v[20:23]
	v_mfma_f32_16x16x32_bf16 v[16:19], v[76:79], v[108:111], v[16:19]
	v_mfma_f32_16x16x32_bf16 v[0:3], v[212:215], v[108:111], v[0:3]
	v_mfma_f32_16x16x32_bf16 v[28:31], v[72:75], v[104:107], v[28:31]
	v_mfma_f32_16x16x32_bf16 v[24:27], v[72:75], v[154:157], v[24:27]
	v_mfma_f32_16x16x32_bf16 v[20:23], v[190:193], v[104:107], v[20:23]
	v_mfma_f32_16x16x32_bf16 v[16:19], v[190:193], v[154:157], v[16:19]
	v_mfma_f32_16x16x32_bf16 v[12:15], v[196:199], v[100:103], v[12:15]
	v_mfma_f32_16x16x32_bf16 v[8:11], v[196:199], v[108:111], v[8:11]
	v_mfma_f32_16x16x32_bf16 v[4:7], v[212:215], v[100:103], v[4:7]
	v_mfma_f32_16x16x32_bf16 v[0:3], v[216:219], v[154:157], v[0:3]
	v_mfma_f32_16x16x32_bf16 v[136:139], v[208:211], v[104:107], v[12:15]
	v_mfma_f32_16x16x32_bf16 v[150:153], v[208:211], v[154:157], v[8:11]
	v_mfma_f32_16x16x32_bf16 v[172:175], v[216:219], v[104:107], v[4:7]
	s_setprio 0
	s_barrier
	s_nop 1
	ds_read_b128 v[4:7], v149
	ds_read_b128 v[8:11], v149 offset:1024
	ds_read_b128 v[12:15], v149 offset:2048
	ds_read_b128 v[154:157], v149 offset:3072
	ds_read_b128 v[36:39], v147 offset:32768
	ds_read_b128 v[40:43], v147 offset:33792
	ds_read_b128 v[44:47], v146 offset:32768
	ds_read_b128 v[68:71], v146 offset:33792
	ds_read_b128 v[190:193], v145 offset:32768
	ds_read_b128 v[196:199], v145 offset:33792
	ds_read_b128 v[208:211], v144 offset:32768
	ds_read_b128 v[212:215], v144 offset:33792
	s_waitcnt vmcnt(2)
	s_barrier
; #define P8_LDA(dst,b,h) _Pragma("unroll") for(int m=0;m<4;++m) _Pragma("unroll") for(int k=0;k<2;++k) \
;     dst[m][k]=*reinterpret_cast<const bf16x8*>((char*)P8_SA(b,h)+lds_byte(wr*64+m*16+fr,k*32+fq*8))
; #define P8_LDB(dst,b,h) _Pragma("unroll") for(int n=0;n<2;++n) _Pragma("unroll") for(int k=0;k<2;++k) \
;     dst[n][k]=*reinterpret_cast<const bf16x8*>((char*)P8_SB(b,h)+lds_byte(wc*32+n*16+fr,k*32+fq*8))
; #define P8_MMA(ai,bj,At,Bt) do{__builtin_amdgcn_s_setprio(1); \
;     _Pragma("unroll") for(int m=0;m<4;++m) _Pragma("unroll") for(int n=0;n<2;++n) _Pragma("unroll") for(int k=0;k<2;++k) \
;       acc[ai][bj][m][n]=__builtin_amdgcn_mfma_f32_16x16x32_bf16(At[m][k],Bt[n][k],acc[ai][bj][m][n],0,0,0); \
;     __builtin_amdgcn_s_setprio(0);}while(0)
; #define P8_WAIT_V(n) asm volatile("s_waitcnt vmcnt(" #n ")":::"memory")
; #define P8_WAIT_L(n) asm volatile("s_waitcnt lgkmcnt(" #n ")":::"memory")
; #define P8_BAR __builtin_amdgcn_s_barrier()
; template <class EPI>
; DEVI void gemm8_tile(const bfr* __restrict__ A, const bfr* __restrict__ Bt, int K, int brow, int bcol, int nbrow, int nbcol, char* shmc, EPI epi) {
;     ...
;   { P8_LDB(B0,1,0); P8_LDA(At,1,0); P8_WAIT_V(2); P8_BAR; P8_WAIT_L(0); P8_MMA(0,0,At,B0); P8_BAR;
;     P8_LDB(B1,1,1); P8_WAIT_V(0); P8_BAR; P8_WAIT_L(0); P8_MMA(0,1,At,B1); P8_BAR;
;     P8_LDA(At,1,1); P8_BAR; P8_WAIT_L(0); P8_MMA(1,0,At,B0); P8_MMA(1,1,At,B1); P8_BAR; }
;   if(wr==0)P8_BAR;
	s_waitcnt lgkmcnt(0)
	s_setprio 1
	s_waitcnt lgkmcnt(0)
	v_mfma_f32_16x16x32_bf16 v[72:75], v[36:39], v[4:7], v[124:127]
	v_mfma_f32_16x16x32_bf16 v[124:127], v[40:43], v[8:11], v[72:75]
	v_mfma_f32_16x16x32_bf16 v[72:75], v[36:39], v[12:15], v[120:123]
	v_mfma_f32_16x16x32_bf16 v[108:111], v[40:43], v[154:157], v[72:75]
	v_mfma_f32_16x16x32_bf16 v[72:75], v[44:47], v[4:7], v[116:119]
	v_mfma_f32_16x16x32_bf16 v[120:123], v[68:71], v[8:11], v[72:75]
	v_mfma_f32_16x16x32_bf16 v[72:75], v[44:47], v[12:15], v[112:115]
	v_mfma_f32_16x16x32_bf16 v[104:107], v[68:71], v[154:157], v[72:75]
	v_mfma_f32_16x16x32_bf16 v[72:75], v[190:193], v[4:7], v[220:223]
	v_mfma_f32_16x16x32_bf16 v[116:119], v[196:199], v[8:11], v[72:75]
	v_mfma_f32_16x16x32_bf16 v[72:75], v[190:193], v[12:15], v[224:227]
	v_mfma_f32_16x16x32_bf16 v[100:103], v[196:199], v[154:157], v[72:75]
	v_mfma_f32_16x16x32_bf16 v[72:75], v[208:211], v[4:7], v[228:231]
	v_mfma_f32_16x16x32_bf16 v[112:115], v[212:215], v[8:11], v[72:75]
	v_mfma_f32_16x16x32_bf16 v[72:75], v[208:211], v[12:15], v[96:99]
	v_mfma_f32_16x16x32_bf16 v[96:99], v[212:215], v[154:157], v[72:75]
	s_setprio 0
	s_barrier
	ds_read_b128 v[216:219], v148
	ds_read_b128 v[220:223], v148 offset:1024
	ds_read_b128 v[224:227], v148 offset:2048
	ds_read_b128 v[228:231], v148 offset:3072
	s_waitcnt vmcnt(0)
	s_barrier
	s_waitcnt lgkmcnt(0)
	s_setprio 1
	s_waitcnt lgkmcnt(0)
	v_mfma_f32_16x16x32_bf16 v[72:75], v[36:39], v[216:219], v[92:95]
	v_mfma_f32_16x16x32_bf16 v[36:39], v[36:39], v[224:227], v[88:91]
	v_mfma_f32_16x16x32_bf16 v[76:79], v[40:43], v[228:231], v[36:39]
	v_mfma_f32_16x16x32_bf16 v[36:39], v[44:47], v[216:219], v[84:87]
	v_mfma_f32_16x16x32_bf16 v[88:91], v[68:71], v[220:223], v[36:39]
	v_mfma_f32_16x16x32_bf16 v[36:39], v[44:47], v[224:227], v[80:83]
	v_mfma_f32_16x16x32_bf16 v[92:95], v[40:43], v[220:223], v[72:75]
	v_mfma_f32_16x16x32_bf16 v[72:75], v[68:71], v[228:231], v[36:39]
	v_mfma_f32_16x16x32_bf16 v[36:39], v[190:193], v[216:219], v[178:181]
	v_mfma_f32_16x16x32_bf16 v[84:87], v[196:199], v[220:223], v[36:39]
	v_mfma_f32_16x16x32_bf16 v[36:39], v[190:193], v[224:227], v[182:185]
	v_mfma_f32_16x16x32_bf16 v[68:71], v[196:199], v[228:231], v[36:39]
	v_mfma_f32_16x16x32_bf16 v[36:39], v[208:211], v[216:219], v[186:189]
	v_mfma_f32_16x16x32_bf16 v[80:83], v[212:215], v[220:223], v[36:39]
	v_mfma_f32_16x16x32_bf16 v[36:39], v[208:211], v[224:227], v[64:67]
	v_mfma_f32_16x16x32_bf16 v[64:67], v[212:215], v[228:231], v[36:39]
	s_setprio 0
	s_barrier
	ds_read_b128 v[176:179], v147 offset:49152
	ds_read_b128 v[180:183], v147 offset:50176
	ds_read_b128 v[184:187], v146 offset:49152
	ds_read_b128 v[146:149], v146 offset:50176
	ds_read_b128 v[188:191], v145 offset:49152
	ds_read_b128 v[196:199], v145 offset:50176
	ds_read_b128 v[208:211], v144 offset:49152
	ds_read_b128 v[212:215], v144 offset:50176
	s_barrier
	s_waitcnt lgkmcnt(0)
	s_setprio 1
	s_waitcnt lgkmcnt(0)
	v_mfma_f32_16x16x32_bf16 v[36:39], v[176:179], v[4:7], v[60:63]
	v_mfma_f32_16x16x32_bf16 v[60:63], v[180:183], v[8:11], v[36:39]
	v_mfma_f32_16x16x32_bf16 v[36:39], v[176:179], v[12:15], v[56:59]
	v_mfma_f32_16x16x32_bf16 v[44:47], v[180:183], v[154:157], v[36:39]
	v_mfma_f32_16x16x32_bf16 v[36:39], v[184:187], v[4:7], v[52:55]
	v_mfma_f32_16x16x32_bf16 v[56:59], v[146:149], v[8:11], v[36:39]
	v_mfma_f32_16x16x32_bf16 v[36:39], v[184:187], v[12:15], v[48:51]
	v_mfma_f32_16x16x32_bf16 v[40:43], v[146:149], v[154:157], v[36:39]
	v_mfma_f32_16x16x32_bf16 v[36:39], v[188:191], v[4:7], v[232:235]
	v_mfma_f32_16x16x32_bf16 v[4:7], v[208:211], v[4:7], v[132:135]
	v_mfma_f32_16x16x32_bf16 v[52:55], v[196:199], v[8:11], v[36:39]
	v_mfma_f32_16x16x32_bf16 v[36:39], v[188:191], v[12:15], v[236:239]
	v_mfma_f32_16x16x32_bf16 v[48:51], v[212:215], v[8:11], v[4:7]
	v_mfma_f32_16x16x32_bf16 v[4:7], v[208:211], v[12:15], v[32:35]
	v_mfma_f32_16x16x32_bf16 v[36:39], v[196:199], v[154:157], v[36:39]
	v_mfma_f32_16x16x32_bf16 v[32:35], v[212:215], v[154:157], v[4:7]
	s_setprio 0
	s_setprio 1
	v_mfma_f32_16x16x32_bf16 v[4:7], v[176:179], v[216:219], v[28:31]
	v_mfma_f32_16x16x32_bf16 v[28:31], v[180:183], v[220:223], v[4:7]
	v_mfma_f32_16x16x32_bf16 v[4:7], v[176:179], v[224:227], v[24:27]
	v_mfma_f32_16x16x32_bf16 v[12:15], v[180:183], v[228:231], v[4:7]
	v_mfma_f32_16x16x32_bf16 v[4:7], v[184:187], v[216:219], v[20:23]
	v_mfma_f32_16x16x32_bf16 v[24:27], v[146:149], v[220:223], v[4:7]
	v_mfma_f32_16x16x32_bf16 v[4:7], v[184:187], v[224:227], v[16:19]
	v_mfma_f32_16x16x32_bf16 v[8:11], v[146:149], v[228:231], v[4:7]
	v_mfma_f32_16x16x32_bf16 v[4:7], v[188:191], v[216:219], v[136:139]
	v_mfma_f32_16x16x32_bf16 v[20:23], v[196:199], v[220:223], v[4:7]
	v_mfma_f32_16x16x32_bf16 v[4:7], v[188:191], v[224:227], v[150:153]
	v_mfma_f32_16x16x32_bf16 v[16:19], v[208:211], v[216:219], v[172:175]
	v_mfma_f32_16x16x32_bf16 v[0:3], v[208:211], v[224:227], v[0:3]
	v_mfma_f32_16x16x32_bf16 v[4:7], v[196:199], v[228:231], v[4:7]
	v_mfma_f32_16x16x32_bf16 v[16:19], v[212:215], v[220:223], v[16:19]
	v_mfma_f32_16x16x32_bf16 v[0:3], v[212:215], v[228:231], v[0:3]
	s_setprio 0
	v_cmp_gt_u32_e32 vcc, s57, v142
	s_barrier
	s_and_saveexec_b64 s[0:1], vcc
	s_cbranch_execz .LBB0_224
	s_barrier

; #define P8_STAGE(P,BASE,br,kt) do{const bfr* _ub=(BASE)+((long)(br)*K+(long)(kt)*BK); \
;     __builtin_amdgcn_global_load_lds((const unsigned*)(_ub+so0),(unsigned*)((char*)(P)+wid*1024),16,0,0); \
;     __builtin_amdgcn_global_load_lds((const unsigned*)(_ub+so1),(unsigned*)((char*)(P)+wid*1024+8192),16,0,0);}while(0)
; #define P8_LDA(dst,b,h) _Pragma("unroll") for(int m=0;m<4;++m) _Pragma("unroll") for(int k=0;k<2;++k) \
;     dst[m][k]=*reinterpret_cast<const bf16x8*>((char*)P8_SA(b,h)+lds_byte(wr*64+m*16+fr,k*32+fq*8))
; #define P8_LDB(dst,b,h) _Pragma("unroll") for(int n=0;n<2;++n) _Pragma("unroll") for(int k=0;k<2;++k) \
;     dst[n][k]=*reinterpret_cast<const bf16x8*>((char*)P8_SB(b,h)+lds_byte(wc*32+n*16+fr,k*32+fq*8))
; #define P8_MMA(ai,bj,At,Bt) do{__builtin_amdgcn_s_setprio(1); \
;     _Pragma("unroll") for(int m=0;m<4;++m) _Pragma("unroll") for(int n=0;n<2;++n) _Pragma("unroll") for(int k=0;k<2;++k) \
;       acc[ai][bj][m][n]=__builtin_amdgcn_mfma_f32_16x16x32_bf16(At[m][k],Bt[n][k],acc[ai][bj][m][n],0,0,0); \
;     __builtin_amdgcn_s_setprio(0);}while(0)
; #define P8_WAIT_V(n) asm volatile("s_waitcnt vmcnt(" #n ")":::"memory")
; #define P8_WAIT_L(n) asm volatile("s_waitcnt lgkmcnt(" #n ")":::"memory")
; #define P8_BAR __builtin_amdgcn_s_barrier()
; #define P8_SCHED __builtin_amdgcn_sched_barrier(0)
; template <class EPI>
; DEVI void gemm8_tile(const bfr* __restrict__ A, const bfr* __restrict__ Bt, int K, int brow, int bcol, int nbrow, int nbcol, char* shmc, EPI epi) {
;     ...
;     P8_LDB(B0,0,0); P8_SCHED; P8_LDA(At,0,0); P8_STAGE(P8_SA(1,1),A,brow+128,t+1);
;     P8_WAIT_L(8); P8_BAR; P8_WAIT_L(0); P8_MMA(0,0,At,B0); P8_BAR; P8_SCHED;
;     P8_LDB(B1,0,1); P8_STAGE(P8_SB(0,0),Bt,bcol,t+2);
;     P8_BAR; P8_WAIT_L(0); P8_MMA(0,1,At,B1); P8_BAR;
;     P8_LDA(At,0,1); P8_STAGE(P8_SA(0,0),A,brow,t+2);
;     P8_BAR; P8_WAIT_L(0); P8_MMA(1,0,At,B0); P8_BAR; P8_SCHED;
;     P8_STAGE(P8_SB(0,1),Bt,bcol+128,t+2);
;     P8_WAIT_V(6); P8_BAR; P8_MMA(1,1,At,B1); P8_BAR;
.LBB0_286:
	ds_read_b128 v[174:177], v157
	ds_read_b128 v[178:181], v157 offset:1024
	ds_read_b128 v[182:185], v157 offset:2048
	ds_read_b128 v[186:189], v157 offset:3072
	v_add_u32_e32 v158, s54, v140
	s_add_i32 m0, s100, 0xc000
	ds_read_b128 v[160:163], v147
	ds_read_b128 v[190:193], v147 offset:1024
	ds_read_b128 v[196:199], v146
	ds_read_b128 v[200:203], v146 offset:1024
	ds_read_b128 v[204:207], v145
	ds_read_b128 v[208:211], v145 offset:1024
	ds_read_b128 v[212:215], v144
	ds_read_b128 v[216:219], v144 offset:1024
	global_load_lds_dwordx4 v158, s[86:87]
	v_add_u32_e32 v158, s54, v138
	s_add_i32 m0, s100, 0xe000
	s_nop 0
	global_load_lds_dwordx4 v158, s[86:87]
	s_waitcnt lgkmcnt(8)
	s_barrier
	s_waitcnt lgkmcnt(0)
	v_mfma_f32_16x16x32_bf16 v[124:127], v[160:163], v[174:177], v[124:127]
	v_mfma_f32_16x16x32_bf16 v[120:123], v[160:163], v[182:185], v[120:123]
	v_mfma_f32_16x16x32_bf16 v[116:119], v[196:199], v[174:177], v[116:119]
	v_mfma_f32_16x16x32_bf16 v[112:115], v[196:199], v[182:185], v[112:115]
	v_mfma_f32_16x16x32_bf16 v[108:111], v[204:207], v[174:177], v[108:111]
	v_mfma_f32_16x16x32_bf16 v[104:107], v[204:207], v[182:185], v[104:107]
	v_mfma_f32_16x16x32_bf16 v[100:103], v[212:215], v[174:177], v[100:103]
	v_mfma_f32_16x16x32_bf16 v[96:99], v[212:215], v[182:185], v[96:99]
	v_mfma_f32_16x16x32_bf16 v[124:127], v[190:193], v[178:181], v[124:127]
	v_mfma_f32_16x16x32_bf16 v[120:123], v[190:193], v[186:189], v[120:123]
	v_mfma_f32_16x16x32_bf16 v[116:119], v[200:203], v[178:181], v[116:119]
	v_mfma_f32_16x16x32_bf16 v[112:115], v[200:203], v[186:189], v[112:115]
	v_mfma_f32_16x16x32_bf16 v[108:111], v[208:211], v[178:181], v[108:111]
	v_mfma_f32_16x16x32_bf16 v[104:107], v[208:211], v[186:189], v[104:107]
	v_mfma_f32_16x16x32_bf16 v[100:103], v[216:219], v[178:181], v[100:103]
	v_mfma_f32_16x16x32_bf16 v[96:99], v[216:219], v[186:189], v[96:99]
	s_barrier
	v_add_u32_e32 v236, s66, v136
	s_add_i32 m0, s100, 0x10000
	ds_read_b128 v[220:223], v155
	ds_read_b128 v[224:227], v155 offset:1024
	ds_read_b128 v[228:231], v155 offset:2048
	ds_read_b128 v[232:235], v155 offset:3072
	global_load_lds_dwordx4 v236, s[86:87]
	v_add_u32_e32 v236, s66, v134
	s_add_i32 m0, s100, 0x12000
	s_nop 0
	global_load_lds_dwordx4 v236, s[86:87]
	s_barrier
	s_waitcnt lgkmcnt(0)
	v_mfma_f32_16x16x32_bf16 v[92:95], v[160:163], v[220:223], v[92:95]
	v_mfma_f32_16x16x32_bf16 v[88:91], v[160:163], v[228:231], v[88:91]
	v_mfma_f32_16x16x32_bf16 v[84:87], v[196:199], v[220:223], v[84:87]
	v_mfma_f32_16x16x32_bf16 v[80:83], v[196:199], v[228:231], v[80:83]
	v_mfma_f32_16x16x32_bf16 v[76:79], v[204:207], v[220:223], v[76:79]
	v_mfma_f32_16x16x32_bf16 v[72:75], v[204:207], v[228:231], v[72:75]
	v_mfma_f32_16x16x32_bf16 v[68:71], v[212:215], v[220:223], v[68:71]
	v_mfma_f32_16x16x32_bf16 v[64:67], v[212:215], v[228:231], v[64:67]
	v_mfma_f32_16x16x32_bf16 v[92:95], v[190:193], v[224:227], v[92:95]
	v_mfma_f32_16x16x32_bf16 v[88:91], v[190:193], v[232:235], v[88:91]
	v_mfma_f32_16x16x32_bf16 v[84:87], v[200:203], v[224:227], v[84:87]
	v_mfma_f32_16x16x32_bf16 v[80:83], v[200:203], v[232:235], v[80:83]
	v_mfma_f32_16x16x32_bf16 v[76:79], v[208:211], v[224:227], v[76:79]
	v_mfma_f32_16x16x32_bf16 v[72:75], v[208:211], v[232:235], v[72:75]
	v_mfma_f32_16x16x32_bf16 v[68:71], v[216:219], v[224:227], v[68:71]
	v_mfma_f32_16x16x32_bf16 v[64:67], v[216:219], v[232:235], v[64:67]
	v_add_u32_e32 v160, s60, v140
	s_mov_b32 m0, s100
	s_barrier
	ds_read_b128 v[190:193], v147 offset:16384
	ds_read_b128 v[196:199], v147 offset:17408
	ds_read_b128 v[200:203], v146 offset:16384
	ds_read_b128 v[204:207], v146 offset:17408
	ds_read_b128 v[208:211], v145 offset:16384
	ds_read_b128 v[212:215], v145 offset:17408
	ds_read_b128 v[216:219], v144 offset:16384
	ds_read_b128 v[236:239], v144 offset:17408
	global_load_lds_dwordx4 v160, s[86:87]
	v_add_u32_e32 v162, s60, v138
	s_add_i32 m0, s100, 0x2000
	s_nop 0
	global_load_lds_dwordx4 v162, s[86:87]
	s_barrier
	s_waitcnt lgkmcnt(0)
	v_mfma_f32_16x16x32_bf16 v[60:63], v[190:193], v[174:177], v[60:63]
	v_mfma_f32_16x16x32_bf16 v[56:59], v[190:193], v[182:185], v[56:59]
	v_mfma_f32_16x16x32_bf16 v[52:55], v[200:203], v[174:177], v[52:55]
	v_mfma_f32_16x16x32_bf16 v[48:51], v[200:203], v[182:185], v[48:51]
	v_mfma_f32_16x16x32_bf16 v[44:47], v[208:211], v[174:177], v[44:47]
	v_mfma_f32_16x16x32_bf16 v[40:43], v[208:211], v[182:185], v[40:43]
	v_mfma_f32_16x16x32_bf16 v[36:39], v[216:219], v[174:177], v[36:39]
	v_mfma_f32_16x16x32_bf16 v[32:35], v[216:219], v[182:185], v[32:35]
	v_mfma_f32_16x16x32_bf16 v[60:63], v[196:199], v[178:181], v[60:63]
	v_mfma_f32_16x16x32_bf16 v[56:59], v[196:199], v[186:189], v[56:59]
	v_mfma_f32_16x16x32_bf16 v[52:55], v[204:207], v[178:181], v[52:55]
	v_mfma_f32_16x16x32_bf16 v[48:51], v[204:207], v[186:189], v[48:51]
	v_mfma_f32_16x16x32_bf16 v[44:47], v[212:215], v[178:181], v[44:47]
	v_mfma_f32_16x16x32_bf16 v[40:43], v[212:215], v[186:189], v[40:43]
	v_mfma_f32_16x16x32_bf16 v[36:39], v[236:239], v[178:181], v[36:39]
	v_mfma_f32_16x16x32_bf16 v[32:35], v[236:239], v[186:189], v[32:35]
	s_barrier
	v_add_u32_e32 v162, s70, v136
	s_add_i32 m0, s100, 0x14000
	v_add_u32_e32 v174, s70, v134
	global_load_lds_dwordx4 v162, s[86:87]
	s_nop 0
	s_add_i32 m0, s100, 0x16000
	s_nop 0
	global_load_lds_dwordx4 v174, s[86:87]
	s_waitcnt vmcnt(6)
	s_barrier
; #define P8_STAGE(P,BASE,br,kt) do{const bfr* _ub=(BASE)+((long)(br)*K+(long)(kt)*BK); \
;     __builtin_amdgcn_global_load_lds((const unsigned*)(_ub+so0),(unsigned*)((char*)(P)+wid*1024),16,0,0); \
;     __builtin_amdgcn_global_load_lds((const unsigned*)(_ub+so1),(unsigned*)((char*)(P)+wid*1024+8192),16,0,0);}while(0)
; #define P8_LDA(dst,b,h) _Pragma("unroll") for(int m=0;m<4;++m) _Pragma("unroll") for(int k=0;k<2;++k) \
;     dst[m][k]=*reinterpret_cast<const bf16x8*>((char*)P8_SA(b,h)+lds_byte(wr*64+m*16+fr,k*32+fq*8))
; #define P8_LDB(dst,b,h) _Pragma("unroll") for(int n=0;n<2;++n) _Pragma("unroll") for(int k=0;k<2;++k) \
;     dst[n][k]=*reinterpret_cast<const bf16x8*>((char*)P8_SB(b,h)+lds_byte(wc*32+n*16+fr,k*32+fq*8))
; #define P8_MMA(ai,bj,At,Bt) do{__builtin_amdgcn_s_setprio(1); \
;     _Pragma("unroll") for(int m=0;m<4;++m) _Pragma("unroll") for(int n=0;n<2;++n) _Pragma("unroll") for(int k=0;k<2;++k) \
;       acc[ai][bj][m][n]=__builtin_amdgcn_mfma_f32_16x16x32_bf16(At[m][k],Bt[n][k],acc[ai][bj][m][n],0,0,0); \
;     __builtin_amdgcn_s_setprio(0);}while(0)
; #define P8_WAIT_V(n) asm volatile("s_waitcnt vmcnt(" #n ")":::"memory")
; #define P8_WAIT_L(n) asm volatile("s_waitcnt lgkmcnt(" #n ")":::"memory")
; #define P8_BAR __builtin_amdgcn_s_barrier()
; #define P8_SCHED __builtin_amdgcn_sched_barrier(0)
; template <class EPI>
; DEVI void gemm8_tile(const bfr* __restrict__ A, const bfr* __restrict__ Bt, int K, int brow, int bcol, int nbrow, int nbcol, char* shmc, EPI epi) {
;     ...
;     P8_WAIT_V(6); P8_BAR; P8_MMA(1,1,At,B1); P8_BAR;
;     P8_LDB(B0,1,0); P8_SCHED; P8_LDA(At,1,0); P8_STAGE(P8_SA(0,1),A,brow+128,t+2);
;     P8_WAIT_L(8); P8_BAR; P8_WAIT_L(0); P8_MMA(0,0,At,B0); P8_BAR; P8_SCHED;
;     P8_LDB(B1,1,1); P8_STAGE(P8_SB(1,0),Bt,bcol,t+3);
;     P8_BAR; P8_WAIT_L(0); P8_MMA(0,1,At,B1); P8_BAR;
;     P8_LDA(At,1,1); P8_STAGE(P8_SA(1,0),A,brow,t+3);
;     P8_BAR; P8_WAIT_L(0); P8_MMA(1,0,At,B0); P8_BAR; P8_SCHED;
	v_mfma_f32_16x16x32_bf16 v[28:31], v[190:193], v[220:223], v[28:31]
	v_mfma_f32_16x16x32_bf16 v[24:27], v[190:193], v[228:231], v[24:27]
	v_mfma_f32_16x16x32_bf16 v[20:23], v[200:203], v[220:223], v[20:23]
	v_mfma_f32_16x16x32_bf16 v[16:19], v[200:203], v[228:231], v[16:19]
	v_mfma_f32_16x16x32_bf16 v[12:15], v[208:211], v[220:223], v[12:15]
	v_mfma_f32_16x16x32_bf16 v[8:11], v[208:211], v[228:231], v[8:11]
	v_mfma_f32_16x16x32_bf16 v[4:7], v[216:219], v[220:223], v[4:7]
	v_mfma_f32_16x16x32_bf16 v[0:3], v[216:219], v[228:231], v[0:3]
	v_mfma_f32_16x16x32_bf16 v[28:31], v[196:199], v[224:227], v[28:31]
	v_mfma_f32_16x16x32_bf16 v[24:27], v[196:199], v[232:235], v[24:27]
	v_mfma_f32_16x16x32_bf16 v[20:23], v[204:207], v[224:227], v[20:23]
	v_mfma_f32_16x16x32_bf16 v[16:19], v[204:207], v[232:235], v[16:19]
	v_mfma_f32_16x16x32_bf16 v[12:15], v[212:215], v[224:227], v[12:15]
	v_mfma_f32_16x16x32_bf16 v[8:11], v[212:215], v[232:235], v[8:11]
	v_mfma_f32_16x16x32_bf16 v[4:7], v[236:239], v[224:227], v[4:7]
	v_mfma_f32_16x16x32_bf16 v[0:3], v[236:239], v[232:235], v[0:3]
	s_barrier
	ds_read_b128 v[174:177], v149
	ds_read_b128 v[178:181], v149 offset:1024
	ds_read_b128 v[182:185], v149 offset:2048
	ds_read_b128 v[186:189], v149 offset:3072
	v_add_u32_e32 v224, s82, v140
	s_add_i32 m0, s100, 0x4000
	ds_read_b128 v[190:193], v147 offset:32768
	ds_read_b128 v[196:199], v147 offset:33792
	ds_read_b128 v[200:203], v146 offset:32768
	ds_read_b128 v[204:207], v146 offset:33792
	ds_read_b128 v[208:211], v145 offset:32768
	ds_read_b128 v[212:215], v145 offset:33792
	ds_read_b128 v[216:219], v144 offset:32768
	ds_read_b128 v[220:223], v144 offset:33792
	global_load_lds_dwordx4 v224, s[86:87]
	v_add_u32_e32 v224, s82, v138
	s_add_i32 m0, s100, 0x6000
	s_nop 0
	global_load_lds_dwordx4 v224, s[86:87]
	s_waitcnt lgkmcnt(8)
	s_barrier
	s_waitcnt lgkmcnt(0)
	v_mfma_f32_16x16x32_bf16 v[124:127], v[190:193], v[174:177], v[124:127]
	v_mfma_f32_16x16x32_bf16 v[120:123], v[190:193], v[182:185], v[120:123]
	v_mfma_f32_16x16x32_bf16 v[116:119], v[200:203], v[174:177], v[116:119]
	v_mfma_f32_16x16x32_bf16 v[112:115], v[200:203], v[182:185], v[112:115]
	v_mfma_f32_16x16x32_bf16 v[108:111], v[208:211], v[174:177], v[108:111]
	v_mfma_f32_16x16x32_bf16 v[104:107], v[208:211], v[182:185], v[104:107]
	v_mfma_f32_16x16x32_bf16 v[100:103], v[216:219], v[174:177], v[100:103]
	v_mfma_f32_16x16x32_bf16 v[96:99], v[216:219], v[182:185], v[96:99]
	v_mfma_f32_16x16x32_bf16 v[124:127], v[196:199], v[178:181], v[124:127]
	v_mfma_f32_16x16x32_bf16 v[120:123], v[196:199], v[186:189], v[120:123]
	v_mfma_f32_16x16x32_bf16 v[116:119], v[204:207], v[178:181], v[116:119]
	v_mfma_f32_16x16x32_bf16 v[112:115], v[204:207], v[186:189], v[112:115]
	v_mfma_f32_16x16x32_bf16 v[108:111], v[212:215], v[178:181], v[108:111]
	v_mfma_f32_16x16x32_bf16 v[104:107], v[212:215], v[186:189], v[104:107]
	v_mfma_f32_16x16x32_bf16 v[100:103], v[220:223], v[178:181], v[100:103]
	v_mfma_f32_16x16x32_bf16 v[96:99], v[220:223], v[186:189], v[96:99]
	s_barrier
	v_add_u32_e32 v248, s74, v136
	s_add_i32 m0, s100, 0x18000
	ds_read_b128 v[224:227], v148
	ds_read_b128 v[228:231], v148 offset:1024
	ds_read_b128 v[232:235], v148 offset:2048
	ds_read_b128 v[236:239], v148 offset:3072
	global_load_lds_dwordx4 v248, s[86:87]
	v_add_u32_e32 v248, s74, v134
	s_add_i32 m0, s100, 0x1a000
	s_nop 0
	global_load_lds_dwordx4 v248, s[86:87]
	s_barrier
	s_waitcnt lgkmcnt(0)
	v_mfma_f32_16x16x32_bf16 v[92:95], v[190:193], v[224:227], v[92:95]
	v_mfma_f32_16x16x32_bf16 v[88:91], v[190:193], v[232:235], v[88:91]
	v_mfma_f32_16x16x32_bf16 v[84:87], v[200:203], v[224:227], v[84:87]
	v_mfma_f32_16x16x32_bf16 v[80:83], v[200:203], v[232:235], v[80:83]
	v_mfma_f32_16x16x32_bf16 v[76:79], v[208:211], v[224:227], v[76:79]
	v_mfma_f32_16x16x32_bf16 v[72:75], v[208:211], v[232:235], v[72:75]
	v_mfma_f32_16x16x32_bf16 v[68:71], v[216:219], v[224:227], v[68:71]
	v_mfma_f32_16x16x32_bf16 v[64:67], v[216:219], v[232:235], v[64:67]
	v_mfma_f32_16x16x32_bf16 v[92:95], v[196:199], v[228:231], v[92:95]
	v_mfma_f32_16x16x32_bf16 v[88:91], v[196:199], v[236:239], v[88:91]
	v_mfma_f32_16x16x32_bf16 v[84:87], v[204:207], v[228:231], v[84:87]
	v_mfma_f32_16x16x32_bf16 v[80:83], v[204:207], v[236:239], v[80:83]
	v_mfma_f32_16x16x32_bf16 v[76:79], v[212:215], v[228:231], v[76:79]
	v_mfma_f32_16x16x32_bf16 v[72:75], v[212:215], v[236:239], v[72:75]
	v_mfma_f32_16x16x32_bf16 v[68:71], v[220:223], v[228:231], v[68:71]
	v_mfma_f32_16x16x32_bf16 v[64:67], v[220:223], v[236:239], v[64:67]
	v_add_u32_e32 v240, s92, v140
	s_add_i32 m0, s100, 0x8000
	s_barrier
	ds_read_b128 v[190:193], v147 offset:49152
	ds_read_b128 v[196:199], v147 offset:50176
	ds_read_b128 v[200:203], v146 offset:49152
	ds_read_b128 v[204:207], v146 offset:50176
	ds_read_b128 v[208:211], v145 offset:49152
	ds_read_b128 v[212:215], v145 offset:50176
	ds_read_b128 v[216:219], v144 offset:49152
	ds_read_b128 v[220:223], v144 offset:50176
	global_load_lds_dwordx4 v240, s[86:87]
	v_add_u32_e32 v240, s92, v138
	s_add_i32 m0, s100, 0xa000
	s_nop 0
	global_load_lds_dwordx4 v240, s[86:87]
	s_barrier
; #define P8_STAGE(P,BASE,br,kt) do{const bfr* _ub=(BASE)+((long)(br)*K+(long)(kt)*BK); \
;     __builtin_amdgcn_global_load_lds((const unsigned*)(_ub+so0),(unsigned*)((char*)(P)+wid*1024),16,0,0); \
;     __builtin_amdgcn_global_load_lds((const unsigned*)(_ub+so1),(unsigned*)((char*)(P)+wid*1024+8192),16,0,0);}while(0)
; #define P8_LDA(dst,b,h) _Pragma("unroll") for(int m=0;m<4;++m) _Pragma("unroll") for(int k=0;k<2;++k) \
;     dst[m][k]=*reinterpret_cast<const bf16x8*>((char*)P8_SA(b,h)+lds_byte(wr*64+m*16+fr,k*32+fq*8))
; #define P8_LDB(dst,b,h) _Pragma("unroll") for(int n=0;n<2;++n) _Pragma("unroll") for(int k=0;k<2;++k) \
;     dst[n][k]=*reinterpret_cast<const bf16x8*>((char*)P8_SB(b,h)+lds_byte(wc*32+n*16+fr,k*32+fq*8))
; #define P8_MMA(ai,bj,At,Bt) do{__builtin_amdgcn_s_setprio(1); \
;     _Pragma("unroll") for(int m=0;m<4;++m) _Pragma("unroll") for(int n=0;n<2;++n) _Pragma("unroll") for(int k=0;k<2;++k) \
;       acc[ai][bj][m][n]=__builtin_amdgcn_mfma_f32_16x16x32_bf16(At[m][k],Bt[n][k],acc[ai][bj][m][n],0,0,0); \
;     __builtin_amdgcn_s_setprio(0);}while(0)
; #define P8_WAIT_V(n) asm volatile("s_waitcnt vmcnt(" #n ")":::"memory")
; #define P8_WAIT_L(n) asm volatile("s_waitcnt lgkmcnt(" #n ")":::"memory")
; #define P8_BAR __builtin_amdgcn_s_barrier()
; #define P8_SCHED __builtin_amdgcn_sched_barrier(0)
; template <class EPI>
; DEVI void gemm8_tile(const bfr* __restrict__ A, const bfr* __restrict__ Bt, int K, int brow, int bcol, int nbrow, int nbcol, char* shmc, EPI epi) {
;     ...
;     P8_BAR; P8_WAIT_L(0); P8_MMA(1,0,At,B0); P8_BAR; P8_SCHED;
;     P8_STAGE(P8_SB(1,1),Bt,bcol+128,t+3);
;     P8_WAIT_V(6); P8_BAR; P8_MMA(1,1,At,B1); P8_BAR;
;   }
;   { P8_LDB(B0,0,0); P8_LDA(At,0,0); P8_STAGE(P8_SA(1,1),A,brow+128,nt-1);
;     P8_BAR; P8_WAIT_L(0); P8_MMA(0,0,At,B0); P8_BAR;
	s_waitcnt lgkmcnt(0)
	v_mfma_f32_16x16x32_bf16 v[60:63], v[190:193], v[174:177], v[60:63]
	v_mfma_f32_16x16x32_bf16 v[56:59], v[190:193], v[182:185], v[56:59]
	v_mfma_f32_16x16x32_bf16 v[52:55], v[200:203], v[174:177], v[52:55]
	v_mfma_f32_16x16x32_bf16 v[48:51], v[200:203], v[182:185], v[48:51]
	v_mfma_f32_16x16x32_bf16 v[44:47], v[208:211], v[174:177], v[44:47]
	v_mfma_f32_16x16x32_bf16 v[40:43], v[208:211], v[182:185], v[40:43]
	v_mfma_f32_16x16x32_bf16 v[36:39], v[216:219], v[174:177], v[36:39]
	v_mfma_f32_16x16x32_bf16 v[32:35], v[216:219], v[182:185], v[32:35]
	v_mfma_f32_16x16x32_bf16 v[60:63], v[196:199], v[178:181], v[60:63]
	v_mfma_f32_16x16x32_bf16 v[56:59], v[196:199], v[186:189], v[56:59]
	v_mfma_f32_16x16x32_bf16 v[52:55], v[204:207], v[178:181], v[52:55]
	v_mfma_f32_16x16x32_bf16 v[48:51], v[204:207], v[186:189], v[48:51]
	v_mfma_f32_16x16x32_bf16 v[44:47], v[212:215], v[178:181], v[44:47]
	v_mfma_f32_16x16x32_bf16 v[40:43], v[212:215], v[186:189], v[40:43]
	v_mfma_f32_16x16x32_bf16 v[36:39], v[220:223], v[178:181], v[36:39]
	v_mfma_f32_16x16x32_bf16 v[32:35], v[220:223], v[186:189], v[32:35]
	s_barrier
	v_add_u32_e32 v174, s78, v136
	s_add_i32 m0, s100, 0x1c000
	s_nop 0
	global_load_lds_dwordx4 v174, s[86:87]
	v_add_u32_e32 v174, s78, v134
	s_add_i32 m0, s100, 0x1e000
	s_nop 0
	global_load_lds_dwordx4 v174, s[86:87]
	s_waitcnt vmcnt(6)
	s_barrier
	v_mfma_f32_16x16x32_bf16 v[28:31], v[190:193], v[224:227], v[28:31]
	v_mfma_f32_16x16x32_bf16 v[24:27], v[190:193], v[232:235], v[24:27]
	v_mfma_f32_16x16x32_bf16 v[20:23], v[200:203], v[224:227], v[20:23]
	v_mfma_f32_16x16x32_bf16 v[16:19], v[200:203], v[232:235], v[16:19]
	v_mfma_f32_16x16x32_bf16 v[12:15], v[208:211], v[224:227], v[12:15]
	v_mfma_f32_16x16x32_bf16 v[8:11], v[208:211], v[232:235], v[8:11]
	v_mfma_f32_16x16x32_bf16 v[4:7], v[216:219], v[224:227], v[4:7]
	v_mfma_f32_16x16x32_bf16 v[0:3], v[216:219], v[232:235], v[0:3]
	v_mfma_f32_16x16x32_bf16 v[28:31], v[196:199], v[228:231], v[28:31]
	v_mfma_f32_16x16x32_bf16 v[24:27], v[196:199], v[236:239], v[24:27]
	v_mfma_f32_16x16x32_bf16 v[20:23], v[204:207], v[228:231], v[20:23]
	v_mfma_f32_16x16x32_bf16 v[16:19], v[204:207], v[236:239], v[16:19]
	v_mfma_f32_16x16x32_bf16 v[12:15], v[212:215], v[228:231], v[12:15]
	v_mfma_f32_16x16x32_bf16 v[8:11], v[212:215], v[236:239], v[8:11]
	v_mfma_f32_16x16x32_bf16 v[4:7], v[220:223], v[228:231], v[4:7]
	v_mfma_f32_16x16x32_bf16 v[0:3], v[220:223], v[236:239], v[0:3]
	s_add_i32 s0, s0, 2
	v_lshl_add_u64 v[134:135], v[134:135], 0, s[80:81]
	v_lshl_add_u64 v[136:137], v[136:137], 0, s[80:81]
	v_lshl_add_u64 v[138:139], v[138:139], 0, s[80:81]
	s_cmp_lt_u32 s0, 28
	v_lshl_add_u64 v[140:141], v[140:141], 0, s[80:81]
	s_barrier
	s_cbranch_scc1 .LBB0_286
	v_add_u32_e32 v171, 0xc000, v143
	v_add_u32_e32 v172, 0xe000, v143
	v_add_u32_e32 v158, 0x10000, v143
	v_add_u32_e32 v159, 0x12000, v143
	v_add_u32_e32 v160, 0x2000, v143
	v_add_u32_e32 v161, 0x14000, v143
	v_add_u32_e32 v162, 0x16000, v143
	v_add_u32_e32 v163, 0x4000, v143
	v_add_u32_e32 v170, 0x6000, v143
	s_or_b32 s0, s8, 0x80
	s_ashr_i32 s1, s0, 31
	s_lshl_b64 s[0:1], s[0:1], 12
	s_add_u32 s0, s29, s0
	s_addc_u32 s1, s68, s1
	ds_read_b128 v[134:137], v157
	ds_read_b128 v[138:141], v157 offset:1024
	ds_read_b128 v[150:153], v157 offset:2048
	ds_read_b128 v[174:177], v157 offset:3072
	ds_read_b128 v[178:181], v147
	ds_read_b128 v[182:185], v147 offset:1024
	ds_read_b128 v[186:189], v146
	ds_read_b128 v[190:193], v146 offset:1024
	ds_read_b128 v[196:199], v145
	ds_read_b128 v[200:203], v145 offset:1024
	ds_read_b128 v[204:207], v144
	ds_read_b128 v[208:211], v144 offset:1024
	v_lshl_add_u64 v[156:157], v[166:167], 1, s[0:1]
	s_mov_b64 s[54:55], 0xf80
	v_lshl_add_u64 v[156:157], v[156:157], 0, s[54:55]
	s_add_i32 m0, s100, 0xc000
	v_lshl_add_u64 v[132:133], v[132:133], 1, s[0:1]
	global_load_lds_dwordx4 v[156:157], off
	v_lshl_add_u64 v[132:133], v[132:133], 0, s[54:55]
	s_add_i32 m0, s100, 0xe000
	s_nop 0
	global_load_lds_dwordx4 v[132:133], off
	s_barrier
	s_waitcnt lgkmcnt(0)
	s_setprio 1
	s_waitcnt lgkmcnt(0)
	v_mfma_f32_16x16x32_bf16 v[124:127], v[178:181], v[134:137], v[124:127]
	v_mfma_f32_16x16x32_bf16 v[116:119], v[186:189], v[134:137], v[116:119]
	v_mfma_f32_16x16x32_bf16 v[112:115], v[186:189], v[150:153], v[112:115]
	v_mfma_f32_16x16x32_bf16 v[96:99], v[204:207], v[150:153], v[96:99]
	v_mfma_f32_16x16x32_bf16 v[124:127], v[182:185], v[138:141], v[124:127]
	v_mfma_f32_16x16x32_bf16 v[120:123], v[178:181], v[150:153], v[120:123]
	v_mfma_f32_16x16x32_bf16 v[116:119], v[190:193], v[138:141], v[116:119]
	v_mfma_f32_16x16x32_bf16 v[112:115], v[190:193], v[174:177], v[112:115]
	v_mfma_f32_16x16x32_bf16 v[108:111], v[196:199], v[134:137], v[108:111]
	v_mfma_f32_16x16x32_bf16 v[104:107], v[196:199], v[150:153], v[104:107]
	v_mfma_f32_16x16x32_bf16 v[100:103], v[204:207], v[134:137], v[100:103]
	v_mfma_f32_16x16x32_bf16 v[96:99], v[208:211], v[174:177], v[96:99]
	v_mfma_f32_16x16x32_bf16 v[212:215], v[182:185], v[174:177], v[120:123]
	v_mfma_f32_16x16x32_bf16 v[216:219], v[200:203], v[138:141], v[108:111]
	v_mfma_f32_16x16x32_bf16 v[220:223], v[200:203], v[174:177], v[104:107]
	v_mfma_f32_16x16x32_bf16 v[224:227], v[208:211], v[138:141], v[100:103]
	s_setprio 0
	s_barrier
	s_nop 0
	ds_read_b128 v[100:103], v155
	ds_read_b128 v[104:107], v155 offset:1024
	ds_read_b128 v[108:111], v155 offset:2048
	ds_read_b128 v[120:123], v155 offset:3072
	s_barrier
; #define P8_LDA(dst,b,h) _Pragma("unroll") for(int m=0;m<4;++m) _Pragma("unroll") for(int k=0;k<2;++k) \
;     dst[m][k]=*reinterpret_cast<const bf16x8*>((char*)P8_SA(b,h)+lds_byte(wr*64+m*16+fr,k*32+fq*8))
; #define P8_LDB(dst,b,h) _Pragma("unroll") for(int n=0;n<2;++n) _Pragma("unroll") for(int k=0;k<2;++k) \
;     dst[n][k]=*reinterpret_cast<const bf16x8*>((char*)P8_SB(b,h)+lds_byte(wc*32+n*16+fr,k*32+fq*8))
; #define P8_MMA(ai,bj,At,Bt) do{__builtin_amdgcn_s_setprio(1); \
;     _Pragma("unroll") for(int m=0;m<4;++m) _Pragma("unroll") for(int n=0;n<2;++n) _Pragma("unroll") for(int k=0;k<2;++k) \
;       acc[ai][bj][m][n]=__builtin_amdgcn_mfma_f32_16x16x32_bf16(At[m][k],Bt[n][k],acc[ai][bj][m][n],0,0,0); \
;     __builtin_amdgcn_s_setprio(0);}while(0)
; #define P8_WAIT_V(n) asm volatile("s_waitcnt vmcnt(" #n ")":::"memory")
; #define P8_WAIT_L(n) asm volatile("s_waitcnt lgkmcnt(" #n ")":::"memory")
; #define P8_BAR __builtin_amdgcn_s_barrier()
; template <class EPI>
; DEVI void gemm8_tile(const bfr* __restrict__ A, const bfr* __restrict__ Bt, int K, int brow, int bcol, int nbrow, int nbcol, char* shmc, EPI epi) {
;     ...
;     P8_LDB(B1,0,1); P8_BAR; P8_WAIT_L(0); P8_MMA(0,1,At,B1); P8_BAR;
;     P8_LDA(At,0,1); P8_WAIT_V(4); P8_BAR; P8_WAIT_L(0); P8_MMA(1,0,At,B0); P8_MMA(1,1,At,B1); P8_BAR; }
;   { P8_LDB(B0,1,0); P8_LDA(At,1,0); P8_WAIT_V(2); P8_BAR; P8_WAIT_L(0); P8_MMA(0,0,At,B0); P8_BAR;
	s_waitcnt lgkmcnt(0)
	s_setprio 1
	s_waitcnt lgkmcnt(0)
	v_mfma_f32_16x16x32_bf16 v[92:95], v[178:181], v[100:103], v[92:95]
	v_mfma_f32_16x16x32_bf16 v[84:87], v[186:189], v[100:103], v[84:87]
	v_mfma_f32_16x16x32_bf16 v[80:83], v[186:189], v[108:111], v[80:83]
	v_mfma_f32_16x16x32_bf16 v[64:67], v[204:207], v[108:111], v[64:67]
	v_mfma_f32_16x16x32_bf16 v[92:95], v[182:185], v[104:107], v[92:95]
	v_mfma_f32_16x16x32_bf16 v[88:91], v[178:181], v[108:111], v[88:91]
	v_mfma_f32_16x16x32_bf16 v[84:87], v[190:193], v[104:107], v[84:87]
	v_mfma_f32_16x16x32_bf16 v[80:83], v[190:193], v[120:123], v[80:83]
	v_mfma_f32_16x16x32_bf16 v[76:79], v[196:199], v[100:103], v[76:79]
	v_mfma_f32_16x16x32_bf16 v[72:75], v[196:199], v[108:111], v[72:75]
	v_mfma_f32_16x16x32_bf16 v[68:71], v[204:207], v[100:103], v[68:71]
	v_mfma_f32_16x16x32_bf16 v[64:67], v[208:211], v[120:123], v[64:67]
	v_mfma_f32_16x16x32_bf16 v[154:157], v[182:185], v[120:123], v[88:91]
	v_mfma_f32_16x16x32_bf16 v[178:181], v[200:203], v[104:107], v[76:79]
	v_mfma_f32_16x16x32_bf16 v[182:185], v[200:203], v[120:123], v[72:75]
	v_mfma_f32_16x16x32_bf16 v[186:189], v[208:211], v[104:107], v[68:71]
	s_setprio 0
	s_barrier
	s_nop 0
	ds_read_b128 v[68:71], v147 offset:16384
	ds_read_b128 v[72:75], v147 offset:17408
	ds_read_b128 v[76:79], v146 offset:16384
	ds_read_b128 v[88:91], v146 offset:17408
	ds_read_b128 v[190:193], v145 offset:16384
	ds_read_b128 v[196:199], v145 offset:17408
	ds_read_b128 v[200:203], v144 offset:16384
	ds_read_b128 v[204:207], v144 offset:17408
	s_waitcnt vmcnt(4)
	s_barrier
	s_waitcnt lgkmcnt(0)
	s_setprio 1
	s_waitcnt lgkmcnt(0)
	v_mfma_f32_16x16x32_bf16 v[60:63], v[68:71], v[134:137], v[60:63]
	v_mfma_f32_16x16x32_bf16 v[52:55], v[76:79], v[134:137], v[52:55]
	v_mfma_f32_16x16x32_bf16 v[48:51], v[76:79], v[150:153], v[48:51]
	v_mfma_f32_16x16x32_bf16 v[32:35], v[200:203], v[150:153], v[32:35]
	v_mfma_f32_16x16x32_bf16 v[60:63], v[72:75], v[138:141], v[60:63]
	v_mfma_f32_16x16x32_bf16 v[56:59], v[68:71], v[150:153], v[56:59]
	v_mfma_f32_16x16x32_bf16 v[52:55], v[88:91], v[138:141], v[52:55]
	v_mfma_f32_16x16x32_bf16 v[48:51], v[88:91], v[174:177], v[48:51]
	v_mfma_f32_16x16x32_bf16 v[44:47], v[190:193], v[134:137], v[44:47]
	v_mfma_f32_16x16x32_bf16 v[40:43], v[190:193], v[150:153], v[40:43]
	v_mfma_f32_16x16x32_bf16 v[36:39], v[200:203], v[134:137], v[36:39]
	v_mfma_f32_16x16x32_bf16 v[32:35], v[204:207], v[174:177], v[32:35]
	v_mfma_f32_16x16x32_bf16 v[208:211], v[72:75], v[174:177], v[56:59]
	v_mfma_f32_16x16x32_bf16 v[228:231], v[196:199], v[138:141], v[44:47]
	v_mfma_f32_16x16x32_bf16 v[232:235], v[196:199], v[174:177], v[40:43]
	v_mfma_f32_16x16x32_bf16 v[132:135], v[204:207], v[138:141], v[36:39]
	s_setprio 0
	s_setprio 1
	v_mfma_f32_16x16x32_bf16 v[28:31], v[68:71], v[100:103], v[28:31]
	v_mfma_f32_16x16x32_bf16 v[20:23], v[76:79], v[100:103], v[20:23]
	v_mfma_f32_16x16x32_bf16 v[16:19], v[76:79], v[108:111], v[16:19]
	v_mfma_f32_16x16x32_bf16 v[0:3], v[200:203], v[108:111], v[0:3]
	v_mfma_f32_16x16x32_bf16 v[28:31], v[72:75], v[104:107], v[28:31]
	v_mfma_f32_16x16x32_bf16 v[24:27], v[68:71], v[108:111], v[24:27]
	v_mfma_f32_16x16x32_bf16 v[20:23], v[88:91], v[104:107], v[20:23]
	v_mfma_f32_16x16x32_bf16 v[16:19], v[88:91], v[120:123], v[16:19]
	v_mfma_f32_16x16x32_bf16 v[12:15], v[190:193], v[100:103], v[12:15]
	v_mfma_f32_16x16x32_bf16 v[8:11], v[190:193], v[108:111], v[8:11]
	v_mfma_f32_16x16x32_bf16 v[4:7], v[200:203], v[100:103], v[4:7]
	v_mfma_f32_16x16x32_bf16 v[0:3], v[204:207], v[120:123], v[0:3]
	v_mfma_f32_16x16x32_bf16 v[136:139], v[72:75], v[120:123], v[24:27]
	v_mfma_f32_16x16x32_bf16 v[150:153], v[196:199], v[104:107], v[12:15]
	v_mfma_f32_16x16x32_bf16 v[172:175], v[196:199], v[120:123], v[8:11]
	v_mfma_f32_16x16x32_bf16 v[190:193], v[204:207], v[104:107], v[4:7]
	s_setprio 0
	s_barrier
	s_nop 0
	ds_read_b128 v[4:7], v149
	ds_read_b128 v[8:11], v149 offset:1024
	ds_read_b128 v[12:15], v149 offset:2048
	ds_read_b128 v[24:27], v149 offset:3072
	ds_read_b128 v[36:39], v147 offset:32768
	ds_read_b128 v[40:43], v147 offset:33792
	ds_read_b128 v[44:47], v146 offset:32768
	ds_read_b128 v[56:59], v146 offset:33792
	ds_read_b128 v[68:71], v145 offset:32768
	ds_read_b128 v[196:199], v145 offset:33792
	ds_read_b128 v[200:203], v144 offset:32768
	ds_read_b128 v[204:207], v144 offset:33792
	s_waitcnt vmcnt(2)
	s_barrier
; #define P8_LDA(dst,b,h) _Pragma("unroll") for(int m=0;m<4;++m) _Pragma("unroll") for(int k=0;k<2;++k) \
;     dst[m][k]=*reinterpret_cast<const bf16x8*>((char*)P8_SA(b,h)+lds_byte(wr*64+m*16+fr,k*32+fq*8))
; #define P8_LDB(dst,b,h) _Pragma("unroll") for(int n=0;n<2;++n) _Pragma("unroll") for(int k=0;k<2;++k) \
;     dst[n][k]=*reinterpret_cast<const bf16x8*>((char*)P8_SB(b,h)+lds_byte(wc*32+n*16+fr,k*32+fq*8))
; #define P8_MMA(ai,bj,At,Bt) do{__builtin_amdgcn_s_setprio(1); \
;     _Pragma("unroll") for(int m=0;m<4;++m) _Pragma("unroll") for(int n=0;n<2;++n) _Pragma("unroll") for(int k=0;k<2;++k) \
;       acc[ai][bj][m][n]=__builtin_amdgcn_mfma_f32_16x16x32_bf16(At[m][k],Bt[n][k],acc[ai][bj][m][n],0,0,0); \
;     __builtin_amdgcn_s_setprio(0);}while(0)
; #define P8_WAIT_V(n) asm volatile("s_waitcnt vmcnt(" #n ")":::"memory")
; #define P8_WAIT_L(n) asm volatile("s_waitcnt lgkmcnt(" #n ")":::"memory")
; #define P8_BAR __builtin_amdgcn_s_barrier()
; template <class EPI>
; DEVI void gemm8_tile(const bfr* __restrict__ A, const bfr* __restrict__ Bt, int K, int brow, int bcol, int nbrow, int nbcol, char* shmc, EPI epi) {
;     ...
;   { P8_LDB(B0,1,0); P8_LDA(At,1,0); P8_WAIT_V(2); P8_BAR; P8_WAIT_L(0); P8_MMA(0,0,At,B0); P8_BAR;
;     P8_LDB(B1,1,1); P8_WAIT_V(0); P8_BAR; P8_WAIT_L(0); P8_MMA(0,1,At,B1); P8_BAR;
;     P8_LDA(At,1,1); P8_BAR; P8_WAIT_L(0); P8_MMA(1,0,At,B0); P8_MMA(1,1,At,B1); P8_BAR; }
;   if(wr==0)P8_BAR;
	s_waitcnt lgkmcnt(0)
	s_setprio 1
	s_waitcnt lgkmcnt(0)
	v_mfma_f32_16x16x32_bf16 v[72:75], v[36:39], v[4:7], v[124:127]
	v_mfma_f32_16x16x32_bf16 v[120:123], v[40:43], v[8:11], v[72:75]
	v_mfma_f32_16x16x32_bf16 v[72:75], v[36:39], v[12:15], v[212:215]
	v_mfma_f32_16x16x32_bf16 v[104:107], v[40:43], v[24:27], v[72:75]
	v_mfma_f32_16x16x32_bf16 v[72:75], v[44:47], v[4:7], v[116:119]
	v_mfma_f32_16x16x32_bf16 v[124:127], v[56:59], v[8:11], v[72:75]
	v_mfma_f32_16x16x32_bf16 v[72:75], v[44:47], v[12:15], v[112:115]
	v_mfma_f32_16x16x32_bf16 v[108:111], v[56:59], v[24:27], v[72:75]
	v_mfma_f32_16x16x32_bf16 v[72:75], v[68:71], v[4:7], v[216:219]
	v_mfma_f32_16x16x32_bf16 v[112:115], v[196:199], v[8:11], v[72:75]
	v_mfma_f32_16x16x32_bf16 v[72:75], v[68:71], v[12:15], v[220:223]
	v_mfma_f32_16x16x32_bf16 v[100:103], v[196:199], v[24:27], v[72:75]
	v_mfma_f32_16x16x32_bf16 v[72:75], v[200:203], v[4:7], v[224:227]
	v_mfma_f32_16x16x32_bf16 v[116:119], v[204:207], v[8:11], v[72:75]
	v_mfma_f32_16x16x32_bf16 v[72:75], v[200:203], v[12:15], v[96:99]
	v_mfma_f32_16x16x32_bf16 v[96:99], v[204:207], v[24:27], v[72:75]
	s_setprio 0
	s_barrier
	ds_read_b128 v[212:215], v148
	ds_read_b128 v[216:219], v148 offset:1024
	ds_read_b128 v[220:223], v148 offset:2048
	ds_read_b128 v[224:227], v148 offset:3072
	s_waitcnt vmcnt(0)
	s_barrier
	s_waitcnt lgkmcnt(0)
	s_setprio 1
	s_waitcnt lgkmcnt(0)
	v_mfma_f32_16x16x32_bf16 v[72:75], v[36:39], v[212:215], v[92:95]
	v_mfma_f32_16x16x32_bf16 v[36:39], v[36:39], v[220:223], v[154:157]
	v_mfma_f32_16x16x32_bf16 v[88:91], v[40:43], v[216:219], v[72:75]
	v_mfma_f32_16x16x32_bf16 v[72:75], v[40:43], v[224:227], v[36:39]
	v_mfma_f32_16x16x32_bf16 v[36:39], v[44:47], v[212:215], v[84:87]
	v_mfma_f32_16x16x32_bf16 v[92:95], v[56:59], v[216:219], v[36:39]
	v_mfma_f32_16x16x32_bf16 v[36:39], v[44:47], v[220:223], v[80:83]
	v_mfma_f32_16x16x32_bf16 v[76:79], v[56:59], v[224:227], v[36:39]
	v_mfma_f32_16x16x32_bf16 v[36:39], v[68:71], v[212:215], v[178:181]
	v_mfma_f32_16x16x32_bf16 v[80:83], v[196:199], v[216:219], v[36:39]
	v_mfma_f32_16x16x32_bf16 v[36:39], v[68:71], v[220:223], v[182:185]
	v_mfma_f32_16x16x32_bf16 v[68:71], v[196:199], v[224:227], v[36:39]
	v_mfma_f32_16x16x32_bf16 v[36:39], v[200:203], v[212:215], v[186:189]
	v_mfma_f32_16x16x32_bf16 v[84:87], v[204:207], v[216:219], v[36:39]
	v_mfma_f32_16x16x32_bf16 v[36:39], v[200:203], v[220:223], v[64:67]
	v_mfma_f32_16x16x32_bf16 v[64:67], v[204:207], v[224:227], v[36:39]
	s_setprio 0
	s_barrier
	ds_read_b128 v[154:157], v147 offset:49152
	ds_read_b128 v[176:179], v147 offset:50176
	ds_read_b128 v[180:183], v146 offset:49152
	ds_read_b128 v[146:149], v146 offset:50176
	ds_read_b128 v[184:187], v145 offset:49152
	ds_read_b128 v[196:199], v145 offset:50176
	ds_read_b128 v[200:203], v144 offset:49152
	ds_read_b128 v[204:207], v144 offset:50176
	s_barrier
	s_waitcnt lgkmcnt(0)
	s_setprio 1
	s_waitcnt lgkmcnt(0)
	v_mfma_f32_16x16x32_bf16 v[36:39], v[154:157], v[4:7], v[60:63]
	v_mfma_f32_16x16x32_bf16 v[56:59], v[176:179], v[8:11], v[36:39]
	v_mfma_f32_16x16x32_bf16 v[36:39], v[154:157], v[12:15], v[208:211]
	v_mfma_f32_16x16x32_bf16 v[40:43], v[176:179], v[24:27], v[36:39]
	v_mfma_f32_16x16x32_bf16 v[36:39], v[180:183], v[4:7], v[52:55]
	v_mfma_f32_16x16x32_bf16 v[60:63], v[146:149], v[8:11], v[36:39]
	v_mfma_f32_16x16x32_bf16 v[36:39], v[180:183], v[12:15], v[48:51]
	v_mfma_f32_16x16x32_bf16 v[44:47], v[146:149], v[24:27], v[36:39]
	v_mfma_f32_16x16x32_bf16 v[36:39], v[184:187], v[4:7], v[228:231]
	v_mfma_f32_16x16x32_bf16 v[4:7], v[200:203], v[4:7], v[132:135]
	v_mfma_f32_16x16x32_bf16 v[48:51], v[196:199], v[8:11], v[36:39]
	v_mfma_f32_16x16x32_bf16 v[36:39], v[184:187], v[12:15], v[232:235]
	v_mfma_f32_16x16x32_bf16 v[52:55], v[204:207], v[8:11], v[4:7]
	v_mfma_f32_16x16x32_bf16 v[4:7], v[200:203], v[12:15], v[32:35]
	v_mfma_f32_16x16x32_bf16 v[36:39], v[196:199], v[24:27], v[36:39]
	v_mfma_f32_16x16x32_bf16 v[32:35], v[204:207], v[24:27], v[4:7]
	s_setprio 0
	s_setprio 1
	v_mfma_f32_16x16x32_bf16 v[4:7], v[154:157], v[212:215], v[28:31]
	v_mfma_f32_16x16x32_bf16 v[24:27], v[176:179], v[216:219], v[4:7]
	v_mfma_f32_16x16x32_bf16 v[4:7], v[154:157], v[220:223], v[136:139]
	v_mfma_f32_16x16x32_bf16 v[8:11], v[176:179], v[224:227], v[4:7]
	v_mfma_f32_16x16x32_bf16 v[4:7], v[180:183], v[212:215], v[20:23]
	v_mfma_f32_16x16x32_bf16 v[28:31], v[146:149], v[216:219], v[4:7]
	v_mfma_f32_16x16x32_bf16 v[4:7], v[180:183], v[220:223], v[16:19]
	v_mfma_f32_16x16x32_bf16 v[12:15], v[146:149], v[224:227], v[4:7]
	v_mfma_f32_16x16x32_bf16 v[4:7], v[184:187], v[212:215], v[150:153]
	v_mfma_f32_16x16x32_bf16 v[16:19], v[196:199], v[216:219], v[4:7]
	v_mfma_f32_16x16x32_bf16 v[4:7], v[184:187], v[220:223], v[172:175]
	v_mfma_f32_16x16x32_bf16 v[20:23], v[200:203], v[212:215], v[190:193]
	v_mfma_f32_16x16x32_bf16 v[0:3], v[200:203], v[220:223], v[0:3]
	v_mfma_f32_16x16x32_bf16 v[4:7], v[196:199], v[224:227], v[4:7]
	v_mfma_f32_16x16x32_bf16 v[20:23], v[204:207], v[216:219], v[20:23]
	v_mfma_f32_16x16x32_bf16 v[0:3], v[204:207], v[224:227], v[0:3]
	s_setprio 0
	v_cmp_gt_u32_e32 vcc, s57, v142
	s_barrier
	s_and_saveexec_b64 s[0:1], vcc
	s_cbranch_execz .LBB0_289
	s_barrier

; #define P8_STAGE(P,BASE,br,kt) do{const bfr* _ub=(BASE)+((long)(br)*K+(long)(kt)*BK); \
;     __builtin_amdgcn_global_load_lds((const unsigned*)(_ub+so0),(unsigned*)((char*)(P)+wid*1024),16,0,0); \
;     __builtin_amdgcn_global_load_lds((const unsigned*)(_ub+so1),(unsigned*)((char*)(P)+wid*1024+8192),16,0,0);}while(0)
; #define P8_LDA(dst,b,h) _Pragma("unroll") for(int m=0;m<4;++m) _Pragma("unroll") for(int k=0;k<2;++k) \
;     dst[m][k]=*reinterpret_cast<const bf16x8*>((char*)P8_SA(b,h)+lds_byte(wr*64+m*16+fr,k*32+fq*8))
; #define P8_LDB(dst,b,h) _Pragma("unroll") for(int n=0;n<2;++n) _Pragma("unroll") for(int k=0;k<2;++k) \
;     dst[n][k]=*reinterpret_cast<const bf16x8*>((char*)P8_SB(b,h)+lds_byte(wc*32+n*16+fr,k*32+fq*8))
; #define P8_MMA(ai,bj,At,Bt) do{__builtin_amdgcn_s_setprio(1); \
;     _Pragma("unroll") for(int m=0;m<4;++m) _Pragma("unroll") for(int n=0;n<2;++n) _Pragma("unroll") for(int k=0;k<2;++k) \
;       acc[ai][bj][m][n]=__builtin_amdgcn_mfma_f32_16x16x32_bf16(At[m][k],Bt[n][k],acc[ai][bj][m][n],0,0,0); \
;     __builtin_amdgcn_s_setprio(0);}while(0)
; #define P8_WAIT_V(n) asm volatile("s_waitcnt vmcnt(" #n ")":::"memory")
; #define P8_WAIT_L(n) asm volatile("s_waitcnt lgkmcnt(" #n ")":::"memory")
; #define P8_BAR __builtin_amdgcn_s_barrier()
; #define P8_SCHED __builtin_amdgcn_sched_barrier(0)
; template <class EPI>
; DEVI void gemm8_tile(const bfr* __restrict__ A, const bfr* __restrict__ Bt, int K, int brow, int bcol, int nbrow, int nbcol, char* shmc, EPI epi) {
;     ...
;     P8_LDB(B0,0,0); P8_SCHED; P8_LDA(At,0,0); P8_STAGE(P8_SA(1,1),A,brow+128,t+1);
;     P8_WAIT_L(8); P8_BAR; P8_WAIT_L(0); P8_MMA(0,0,At,B0); P8_BAR; P8_SCHED;
;     P8_LDB(B1,0,1); P8_STAGE(P8_SB(0,0),Bt,bcol,t+2);
;     P8_BAR; P8_WAIT_L(0); P8_MMA(0,1,At,B1); P8_BAR;
;     P8_LDA(At,0,1); P8_STAGE(P8_SA(0,0),A,brow,t+2);
;     P8_BAR; P8_WAIT_L(0); P8_MMA(1,0,At,B0); P8_BAR; P8_SCHED;
;     P8_STAGE(P8_SB(0,1),Bt,bcol+128,t+2);
;     P8_WAIT_V(6); P8_BAR; P8_MMA(1,1,At,B1); P8_BAR;
.LBB0_382:
	ds_read_b128 v[174:177], v157
	ds_read_b128 v[178:181], v157 offset:1024
	ds_read_b128 v[182:185], v157 offset:2048
	ds_read_b128 v[186:189], v157 offset:3072
	v_add_u32_e32 v158, s54, v140
	s_add_i32 m0, s100, 0xc000
	ds_read_b128 v[160:163], v147
	ds_read_b128 v[190:193], v147 offset:1024
	ds_read_b128 v[196:199], v146
	ds_read_b128 v[208:211], v146 offset:1024
	ds_read_b128 v[212:215], v145
	ds_read_b128 v[216:219], v145 offset:1024
	ds_read_b128 v[220:223], v144
	ds_read_b128 v[224:227], v144 offset:1024
	global_load_lds_dwordx4 v158, s[86:87]
	v_add_u32_e32 v158, s54, v138
	s_add_i32 m0, s100, 0xe000
	s_nop 0
	global_load_lds_dwordx4 v158, s[86:87]
	s_waitcnt lgkmcnt(8)
	s_barrier
	s_waitcnt lgkmcnt(0)
	v_mfma_f32_16x16x32_bf16 v[124:127], v[160:163], v[174:177], v[124:127]
	v_mfma_f32_16x16x32_bf16 v[120:123], v[160:163], v[182:185], v[120:123]
	v_mfma_f32_16x16x32_bf16 v[116:119], v[196:199], v[174:177], v[116:119]
	v_mfma_f32_16x16x32_bf16 v[112:115], v[196:199], v[182:185], v[112:115]
	v_mfma_f32_16x16x32_bf16 v[108:111], v[212:215], v[174:177], v[108:111]
	v_mfma_f32_16x16x32_bf16 v[104:107], v[212:215], v[182:185], v[104:107]
	v_mfma_f32_16x16x32_bf16 v[100:103], v[220:223], v[174:177], v[100:103]
	v_mfma_f32_16x16x32_bf16 v[96:99], v[220:223], v[182:185], v[96:99]
	v_mfma_f32_16x16x32_bf16 v[124:127], v[190:193], v[178:181], v[124:127]
	v_mfma_f32_16x16x32_bf16 v[120:123], v[190:193], v[186:189], v[120:123]
	v_mfma_f32_16x16x32_bf16 v[116:119], v[208:211], v[178:181], v[116:119]
	v_mfma_f32_16x16x32_bf16 v[112:115], v[208:211], v[186:189], v[112:115]
	v_mfma_f32_16x16x32_bf16 v[108:111], v[216:219], v[178:181], v[108:111]
	v_mfma_f32_16x16x32_bf16 v[104:107], v[216:219], v[186:189], v[104:107]
	v_mfma_f32_16x16x32_bf16 v[100:103], v[224:227], v[178:181], v[100:103]
	v_mfma_f32_16x16x32_bf16 v[96:99], v[224:227], v[186:189], v[96:99]
	s_barrier
	v_add_u32_e32 v206, s60, v136
	s_add_i32 m0, s100, 0x10000
	ds_read_b128 v[228:231], v154
	ds_read_b128 v[232:235], v154 offset:1024
	ds_read_b128 v[236:239], v154 offset:2048
	ds_read_b128 v[240:243], v154 offset:3072
	global_load_lds_dwordx4 v206, s[86:87]
	v_add_u32_e32 v244, s60, v134
	s_add_i32 m0, s100, 0x12000
	s_nop 0
	global_load_lds_dwordx4 v244, s[86:87]
	s_barrier
	s_waitcnt lgkmcnt(0)
	v_mfma_f32_16x16x32_bf16 v[92:95], v[160:163], v[228:231], v[92:95]
	v_mfma_f32_16x16x32_bf16 v[88:91], v[160:163], v[236:239], v[88:91]
	v_mfma_f32_16x16x32_bf16 v[84:87], v[196:199], v[228:231], v[84:87]
	v_mfma_f32_16x16x32_bf16 v[80:83], v[196:199], v[236:239], v[80:83]
	v_mfma_f32_16x16x32_bf16 v[76:79], v[212:215], v[228:231], v[76:79]
	v_mfma_f32_16x16x32_bf16 v[72:75], v[212:215], v[236:239], v[72:75]
	v_mfma_f32_16x16x32_bf16 v[68:71], v[220:223], v[228:231], v[68:71]
	v_mfma_f32_16x16x32_bf16 v[64:67], v[220:223], v[236:239], v[64:67]
	v_mfma_f32_16x16x32_bf16 v[92:95], v[190:193], v[232:235], v[92:95]
	v_mfma_f32_16x16x32_bf16 v[88:91], v[190:193], v[240:243], v[88:91]
	v_mfma_f32_16x16x32_bf16 v[84:87], v[208:211], v[232:235], v[84:87]
	v_mfma_f32_16x16x32_bf16 v[80:83], v[208:211], v[240:243], v[80:83]
	v_mfma_f32_16x16x32_bf16 v[76:79], v[216:219], v[232:235], v[76:79]
	v_mfma_f32_16x16x32_bf16 v[72:75], v[216:219], v[240:243], v[72:75]
	v_mfma_f32_16x16x32_bf16 v[68:71], v[224:227], v[232:235], v[68:71]
	v_mfma_f32_16x16x32_bf16 v[64:67], v[224:227], v[240:243], v[64:67]
	v_add_u32_e32 v160, s82, v140
	s_mov_b32 m0, s100
	s_barrier
	ds_read_b128 v[190:193], v147 offset:16384
	ds_read_b128 v[196:199], v147 offset:17408
	ds_read_b128 v[208:211], v146 offset:16384
	ds_read_b128 v[212:215], v146 offset:17408
	ds_read_b128 v[216:219], v145 offset:16384
	ds_read_b128 v[220:223], v145 offset:17408
	ds_read_b128 v[224:227], v144 offset:16384
	ds_read_b128 v[244:247], v144 offset:17408
	global_load_lds_dwordx4 v160, s[86:87]
	v_add_u32_e32 v162, s82, v138
	s_add_i32 m0, s100, 0x2000
	s_nop 0
	global_load_lds_dwordx4 v162, s[86:87]
	s_barrier
	s_waitcnt lgkmcnt(0)
	v_mfma_f32_16x16x32_bf16 v[60:63], v[190:193], v[174:177], v[60:63]
	v_mfma_f32_16x16x32_bf16 v[56:59], v[190:193], v[182:185], v[56:59]
	v_mfma_f32_16x16x32_bf16 v[52:55], v[208:211], v[174:177], v[52:55]
	v_mfma_f32_16x16x32_bf16 v[48:51], v[208:211], v[182:185], v[48:51]
	v_mfma_f32_16x16x32_bf16 v[44:47], v[216:219], v[174:177], v[44:47]
	v_mfma_f32_16x16x32_bf16 v[40:43], v[216:219], v[182:185], v[40:43]
	v_mfma_f32_16x16x32_bf16 v[36:39], v[224:227], v[174:177], v[36:39]
	v_mfma_f32_16x16x32_bf16 v[32:35], v[224:227], v[182:185], v[32:35]
	v_mfma_f32_16x16x32_bf16 v[60:63], v[196:199], v[178:181], v[60:63]
	v_mfma_f32_16x16x32_bf16 v[56:59], v[196:199], v[186:189], v[56:59]
	v_mfma_f32_16x16x32_bf16 v[52:55], v[212:215], v[178:181], v[52:55]
	v_mfma_f32_16x16x32_bf16 v[48:51], v[212:215], v[186:189], v[48:51]
	v_mfma_f32_16x16x32_bf16 v[44:47], v[220:223], v[178:181], v[44:47]
	v_mfma_f32_16x16x32_bf16 v[40:43], v[220:223], v[186:189], v[40:43]
	v_mfma_f32_16x16x32_bf16 v[36:39], v[244:247], v[178:181], v[36:39]
	v_mfma_f32_16x16x32_bf16 v[32:35], v[244:247], v[186:189], v[32:35]
	s_barrier
	v_add_u32_e32 v162, s92, v136
	s_add_i32 m0, s100, 0x14000
	v_add_u32_e32 v174, s92, v134
	global_load_lds_dwordx4 v162, s[86:87]
	s_nop 0
	s_add_i32 m0, s100, 0x16000
	s_nop 0
	global_load_lds_dwordx4 v174, s[86:87]
	s_waitcnt vmcnt(6)
	s_barrier
; #define P8_STAGE(P,BASE,br,kt) do{const bfr* _ub=(BASE)+((long)(br)*K+(long)(kt)*BK); \
;     __builtin_amdgcn_global_load_lds((const unsigned*)(_ub+so0),(unsigned*)((char*)(P)+wid*1024),16,0,0); \
;     __builtin_amdgcn_global_load_lds((const unsigned*)(_ub+so1),(unsigned*)((char*)(P)+wid*1024+8192),16,0,0);}while(0)
; #define P8_LDA(dst,b,h) _Pragma("unroll") for(int m=0;m<4;++m) _Pragma("unroll") for(int k=0;k<2;++k) \
;     dst[m][k]=*reinterpret_cast<const bf16x8*>((char*)P8_SA(b,h)+lds_byte(wr*64+m*16+fr,k*32+fq*8))
; #define P8_LDB(dst,b,h) _Pragma("unroll") for(int n=0;n<2;++n) _Pragma("unroll") for(int k=0;k<2;++k) \
;     dst[n][k]=*reinterpret_cast<const bf16x8*>((char*)P8_SB(b,h)+lds_byte(wc*32+n*16+fr,k*32+fq*8))
; #define P8_MMA(ai,bj,At,Bt) do{__builtin_amdgcn_s_setprio(1); \
;     _Pragma("unroll") for(int m=0;m<4;++m) _Pragma("unroll") for(int n=0;n<2;++n) _Pragma("unroll") for(int k=0;k<2;++k) \
;       acc[ai][bj][m][n]=__builtin_amdgcn_mfma_f32_16x16x32_bf16(At[m][k],Bt[n][k],acc[ai][bj][m][n],0,0,0); \
;     __builtin_amdgcn_s_setprio(0);}while(0)
; #define P8_WAIT_V(n) asm volatile("s_waitcnt vmcnt(" #n ")":::"memory")
; #define P8_WAIT_L(n) asm volatile("s_waitcnt lgkmcnt(" #n ")":::"memory")
; #define P8_BAR __builtin_amdgcn_s_barrier()
; #define P8_SCHED __builtin_amdgcn_sched_barrier(0)
; template <class EPI>
; DEVI void gemm8_tile(const bfr* __restrict__ A, const bfr* __restrict__ Bt, int K, int brow, int bcol, int nbrow, int nbcol, char* shmc, EPI epi) {
;     ...
;     P8_WAIT_V(6); P8_BAR; P8_MMA(1,1,At,B1); P8_BAR;
;     P8_LDB(B0,1,0); P8_SCHED; P8_LDA(At,1,0); P8_STAGE(P8_SA(0,1),A,brow+128,t+2);
;     P8_WAIT_L(8); P8_BAR; P8_WAIT_L(0); P8_MMA(0,0,At,B0); P8_BAR; P8_SCHED;
;     P8_LDB(B1,1,1); P8_STAGE(P8_SB(1,0),Bt,bcol,t+3);
;     P8_BAR; P8_WAIT_L(0); P8_MMA(0,1,At,B1); P8_BAR;
;     P8_LDA(At,1,1); P8_STAGE(P8_SA(1,0),A,brow,t+3);
;     P8_BAR; P8_WAIT_L(0); P8_MMA(1,0,At,B0); P8_BAR; P8_SCHED;
	v_mfma_f32_16x16x32_bf16 v[28:31], v[190:193], v[228:231], v[28:31]
	v_mfma_f32_16x16x32_bf16 v[24:27], v[190:193], v[236:239], v[24:27]
	v_mfma_f32_16x16x32_bf16 v[20:23], v[208:211], v[228:231], v[20:23]
	v_mfma_f32_16x16x32_bf16 v[16:19], v[208:211], v[236:239], v[16:19]
	v_mfma_f32_16x16x32_bf16 v[12:15], v[216:219], v[228:231], v[12:15]
	v_mfma_f32_16x16x32_bf16 v[8:11], v[216:219], v[236:239], v[8:11]
	v_mfma_f32_16x16x32_bf16 v[4:7], v[224:227], v[228:231], v[4:7]
	v_mfma_f32_16x16x32_bf16 v[0:3], v[224:227], v[236:239], v[0:3]
	v_mfma_f32_16x16x32_bf16 v[28:31], v[196:199], v[232:235], v[28:31]
	v_mfma_f32_16x16x32_bf16 v[24:27], v[196:199], v[240:243], v[24:27]
	v_mfma_f32_16x16x32_bf16 v[20:23], v[212:215], v[232:235], v[20:23]
	v_mfma_f32_16x16x32_bf16 v[16:19], v[212:215], v[240:243], v[16:19]
	v_mfma_f32_16x16x32_bf16 v[12:15], v[220:223], v[232:235], v[12:15]
	v_mfma_f32_16x16x32_bf16 v[8:11], v[220:223], v[240:243], v[8:11]
	v_mfma_f32_16x16x32_bf16 v[4:7], v[244:247], v[232:235], v[4:7]
	v_mfma_f32_16x16x32_bf16 v[0:3], v[244:247], v[240:243], v[0:3]
	s_barrier
	ds_read_b128 v[174:177], v149
	ds_read_b128 v[178:181], v149 offset:1024
	ds_read_b128 v[182:185], v149 offset:2048
	ds_read_b128 v[186:189], v149 offset:3072
	v_add_u32_e32 v232, s94, v140
	s_add_i32 m0, s100, 0x4000
	ds_read_b128 v[190:193], v147 offset:32768
	ds_read_b128 v[196:199], v147 offset:33792
	ds_read_b128 v[208:211], v146 offset:32768
	ds_read_b128 v[212:215], v146 offset:33792
	ds_read_b128 v[216:219], v145 offset:32768
	ds_read_b128 v[220:223], v145 offset:33792
	ds_read_b128 v[224:227], v144 offset:32768
	ds_read_b128 v[228:231], v144 offset:33792
	global_load_lds_dwordx4 v232, s[86:87]
	v_add_u32_e32 v232, s94, v138
	s_add_i32 m0, s100, 0x6000
	s_nop 0
	global_load_lds_dwordx4 v232, s[86:87]
	s_waitcnt lgkmcnt(8)
	s_barrier
	s_waitcnt lgkmcnt(0)
	v_mfma_f32_16x16x32_bf16 v[124:127], v[190:193], v[174:177], v[124:127]
	v_mfma_f32_16x16x32_bf16 v[120:123], v[190:193], v[182:185], v[120:123]
	v_mfma_f32_16x16x32_bf16 v[116:119], v[208:211], v[174:177], v[116:119]
	v_mfma_f32_16x16x32_bf16 v[112:115], v[208:211], v[182:185], v[112:115]
	v_mfma_f32_16x16x32_bf16 v[108:111], v[216:219], v[174:177], v[108:111]
	v_mfma_f32_16x16x32_bf16 v[104:107], v[216:219], v[182:185], v[104:107]
	v_mfma_f32_16x16x32_bf16 v[100:103], v[224:227], v[174:177], v[100:103]
	v_mfma_f32_16x16x32_bf16 v[96:99], v[224:227], v[182:185], v[96:99]
	v_mfma_f32_16x16x32_bf16 v[124:127], v[196:199], v[178:181], v[124:127]
	v_mfma_f32_16x16x32_bf16 v[120:123], v[196:199], v[186:189], v[120:123]
	v_mfma_f32_16x16x32_bf16 v[116:119], v[212:215], v[178:181], v[116:119]
	v_mfma_f32_16x16x32_bf16 v[112:115], v[212:215], v[186:189], v[112:115]
	v_mfma_f32_16x16x32_bf16 v[108:111], v[220:223], v[178:181], v[108:111]
	v_mfma_f32_16x16x32_bf16 v[104:107], v[220:223], v[186:189], v[104:107]
	v_mfma_f32_16x16x32_bf16 v[100:103], v[228:231], v[178:181], v[100:103]
	v_mfma_f32_16x16x32_bf16 v[96:99], v[228:231], v[186:189], v[96:99]
	s_barrier
	v_add_u32_e32 v248, s96, v136
	s_add_i32 m0, s100, 0x18000
	ds_read_b128 v[232:235], v148
	ds_read_b128 v[236:239], v148 offset:1024
	ds_read_b128 v[240:243], v148 offset:2048
	ds_read_b128 v[244:247], v148 offset:3072
	global_load_lds_dwordx4 v248, s[86:87]
	v_add_u32_e32 v248, s96, v134
	s_add_i32 m0, s100, 0x1a000
	s_nop 0
	global_load_lds_dwordx4 v248, s[86:87]
	s_barrier
	s_waitcnt lgkmcnt(0)
	v_mfma_f32_16x16x32_bf16 v[92:95], v[190:193], v[232:235], v[92:95]
	v_mfma_f32_16x16x32_bf16 v[88:91], v[190:193], v[240:243], v[88:91]
	v_mfma_f32_16x16x32_bf16 v[84:87], v[208:211], v[232:235], v[84:87]
	v_mfma_f32_16x16x32_bf16 v[80:83], v[208:211], v[240:243], v[80:83]
	v_mfma_f32_16x16x32_bf16 v[76:79], v[216:219], v[232:235], v[76:79]
	v_mfma_f32_16x16x32_bf16 v[72:75], v[216:219], v[240:243], v[72:75]
	v_mfma_f32_16x16x32_bf16 v[68:71], v[224:227], v[232:235], v[68:71]
	v_mfma_f32_16x16x32_bf16 v[64:67], v[224:227], v[240:243], v[64:67]
	v_mfma_f32_16x16x32_bf16 v[92:95], v[196:199], v[236:239], v[92:95]
	v_mfma_f32_16x16x32_bf16 v[88:91], v[196:199], v[244:247], v[88:91]
	v_mfma_f32_16x16x32_bf16 v[84:87], v[212:215], v[236:239], v[84:87]
	v_mfma_f32_16x16x32_bf16 v[80:83], v[212:215], v[244:247], v[80:83]
	v_mfma_f32_16x16x32_bf16 v[76:79], v[220:223], v[236:239], v[76:79]
	v_mfma_f32_16x16x32_bf16 v[72:75], v[220:223], v[244:247], v[72:75]
	v_mfma_f32_16x16x32_bf16 v[68:71], v[228:231], v[236:239], v[68:71]
	v_mfma_f32_16x16x32_bf16 v[64:67], v[228:231], v[244:247], v[64:67]
	v_add_u32_e32 v200, vcc_lo, v140
	s_add_i32 m0, s100, 0x8000
	s_barrier
	ds_read_b128 v[190:193], v147 offset:49152
	ds_read_b128 v[196:199], v147 offset:50176
	ds_read_b128 v[208:211], v146 offset:49152
	ds_read_b128 v[212:215], v146 offset:50176
	ds_read_b128 v[216:219], v145 offset:49152
	ds_read_b128 v[220:223], v145 offset:50176
	ds_read_b128 v[224:227], v144 offset:49152
	ds_read_b128 v[228:231], v144 offset:50176
	global_load_lds_dwordx4 v200, s[86:87]
	v_add_u32_e32 v200, vcc_lo, v138
	s_add_i32 m0, s100, 0xa000
	s_nop 0
	global_load_lds_dwordx4 v200, s[86:87]
	s_barrier
; #define P8_STAGE(P,BASE,br,kt) do{const bfr* _ub=(BASE)+((long)(br)*K+(long)(kt)*BK); \
;     __builtin_amdgcn_global_load_lds((const unsigned*)(_ub+so0),(unsigned*)((char*)(P)+wid*1024),16,0,0); \
;     __builtin_amdgcn_global_load_lds((const unsigned*)(_ub+so1),(unsigned*)((char*)(P)+wid*1024+8192),16,0,0);}while(0)
; #define P8_LDA(dst,b,h) _Pragma("unroll") for(int m=0;m<4;++m) _Pragma("unroll") for(int k=0;k<2;++k) \
;     dst[m][k]=*reinterpret_cast<const bf16x8*>((char*)P8_SA(b,h)+lds_byte(wr*64+m*16+fr,k*32+fq*8))
; #define P8_LDB(dst,b,h) _Pragma("unroll") for(int n=0;n<2;++n) _Pragma("unroll") for(int k=0;k<2;++k) \
;     dst[n][k]=*reinterpret_cast<const bf16x8*>((char*)P8_SB(b,h)+lds_byte(wc*32+n*16+fr,k*32+fq*8))
; #define P8_WAIT_V(n) asm volatile("s_waitcnt vmcnt(" #n ")":::"memory")
; #define P8_WAIT_L(n) asm volatile("s_waitcnt lgkmcnt(" #n ")":::"memory")
; template <class EPI>
; DEVI void gemm8_tile(const bfr* __restrict__ A, const bfr* __restrict__ Bt, int K, int brow, int bcol, int nbrow, int nbcol, char* shmc, EPI epi) {
;     ...
;   for(int t=0;t<nt-2;t+=2){
;     P8_LDB(B0,0,0); P8_SCHED; P8_LDA(At,0,0); P8_STAGE(P8_SA(1,1),A,brow+128,t+1);
;     P8_WAIT_L(8); P8_BAR; P8_WAIT_L(0); P8_MMA(0,0,At,B0); P8_BAR; P8_SCHED;
;     P8_LDB(B1,0,1); P8_STAGE(P8_SB(0,0),Bt,bcol,t+2);
;     P8_BAR; P8_WAIT_L(0); P8_MMA(0,1,At,B1); P8_BAR;
;     P8_LDA(At,0,1); P8_STAGE(P8_SA(0,0),A,brow,t+2);
;     P8_BAR; P8_WAIT_L(0); P8_MMA(1,0,At,B0); P8_BAR; P8_SCHED;
;     P8_STAGE(P8_SB(0,1),Bt,bcol+128,t+2);
;     P8_WAIT_V(6); P8_BAR; P8_MMA(1,1,At,B1); P8_BAR;
;     P8_LDB(B0,1,0); P8_SCHED; P8_LDA(At,1,0); P8_STAGE(P8_SA(0,1),A,brow+128,t+2);
;     P8_WAIT_L(8); P8_BAR; P8_WAIT_L(0); P8_MMA(0,0,At,B0); P8_BAR; P8_SCHED;
;     P8_LDB(B1,1,1); P8_STAGE(P8_SB(1,0),Bt,bcol,t+3);
;     P8_BAR; P8_WAIT_L(0); P8_MMA(0,1,At,B1); P8_BAR;
;     P8_LDA(At,1,1); P8_STAGE(P8_SA(1,0),A,brow,t+3);
;     P8_BAR; P8_WAIT_L(0); P8_MMA(1,0,At,B0); P8_BAR; P8_SCHED;
;     P8_STAGE(P8_SB(1,1),Bt,bcol+128,t+3);
;     P8_WAIT_V(6); P8_BAR; P8_MMA(1,1,At,B1); P8_BAR;
;   }
;   { P8_LDB(B0,0,0); P8_LDA(At,0,0); P8_STAGE(P8_SA(1,1),A,brow+128,nt-1);
;     P8_BAR; P8_WAIT_L(0); P8_MMA(0,0,At,B0); P8_BAR;
;     P8_LDB(B1,0,1); P8_BAR; P8_WAIT_L(0); P8_MMA(0,1,At,B1); P8_BAR;
;     P8_LDA(At,0,1); P8_WAIT_V(4); P8_BAR; P8_WAIT_L(0); P8_MMA(1,0,At,B0); P8_MMA(1,1,At,B1); P8_BAR; }
	s_waitcnt lgkmcnt(0)
	v_mfma_f32_16x16x32_bf16 v[60:63], v[190:193], v[174:177], v[60:63]
	v_mfma_f32_16x16x32_bf16 v[56:59], v[190:193], v[182:185], v[56:59]
	v_mfma_f32_16x16x32_bf16 v[52:55], v[208:211], v[174:177], v[52:55]
	v_mfma_f32_16x16x32_bf16 v[48:51], v[208:211], v[182:185], v[48:51]
	v_mfma_f32_16x16x32_bf16 v[44:47], v[216:219], v[174:177], v[44:47]
	v_mfma_f32_16x16x32_bf16 v[40:43], v[216:219], v[182:185], v[40:43]
	v_mfma_f32_16x16x32_bf16 v[36:39], v[224:227], v[174:177], v[36:39]
	v_mfma_f32_16x16x32_bf16 v[32:35], v[224:227], v[182:185], v[32:35]
	v_mfma_f32_16x16x32_bf16 v[60:63], v[196:199], v[178:181], v[60:63]
	v_mfma_f32_16x16x32_bf16 v[56:59], v[196:199], v[186:189], v[56:59]
	v_mfma_f32_16x16x32_bf16 v[52:55], v[212:215], v[178:181], v[52:55]
	v_mfma_f32_16x16x32_bf16 v[48:51], v[212:215], v[186:189], v[48:51]
	v_mfma_f32_16x16x32_bf16 v[44:47], v[220:223], v[178:181], v[44:47]
	v_mfma_f32_16x16x32_bf16 v[40:43], v[220:223], v[186:189], v[40:43]
	v_mfma_f32_16x16x32_bf16 v[36:39], v[228:231], v[178:181], v[36:39]
	v_mfma_f32_16x16x32_bf16 v[32:35], v[228:231], v[186:189], v[32:35]
	s_barrier
	v_add_u32_e32 v174, s28, v136
	s_add_i32 m0, s100, 0x1c000
	s_nop 0
	global_load_lds_dwordx4 v174, s[86:87]
	v_add_u32_e32 v174, s28, v134
	s_add_i32 m0, s100, 0x1e000
	s_nop 0
	global_load_lds_dwordx4 v174, s[86:87]
	s_waitcnt vmcnt(6)
	s_barrier
	v_mfma_f32_16x16x32_bf16 v[28:31], v[190:193], v[232:235], v[28:31]
	v_mfma_f32_16x16x32_bf16 v[24:27], v[190:193], v[240:243], v[24:27]
	v_mfma_f32_16x16x32_bf16 v[20:23], v[208:211], v[232:235], v[20:23]
	v_mfma_f32_16x16x32_bf16 v[16:19], v[208:211], v[240:243], v[16:19]
	v_mfma_f32_16x16x32_bf16 v[12:15], v[216:219], v[232:235], v[12:15]
	v_mfma_f32_16x16x32_bf16 v[8:11], v[216:219], v[240:243], v[8:11]
	v_mfma_f32_16x16x32_bf16 v[4:7], v[224:227], v[232:235], v[4:7]
	v_mfma_f32_16x16x32_bf16 v[0:3], v[224:227], v[240:243], v[0:3]
	v_mfma_f32_16x16x32_bf16 v[28:31], v[196:199], v[236:239], v[28:31]
	v_mfma_f32_16x16x32_bf16 v[24:27], v[196:199], v[244:247], v[24:27]
	v_mfma_f32_16x16x32_bf16 v[20:23], v[212:215], v[236:239], v[20:23]
	v_mfma_f32_16x16x32_bf16 v[16:19], v[212:215], v[244:247], v[16:19]
	v_mfma_f32_16x16x32_bf16 v[12:15], v[220:223], v[236:239], v[12:15]
	v_mfma_f32_16x16x32_bf16 v[8:11], v[220:223], v[244:247], v[8:11]
	v_mfma_f32_16x16x32_bf16 v[4:7], v[228:231], v[236:239], v[4:7]
	v_mfma_f32_16x16x32_bf16 v[0:3], v[228:231], v[244:247], v[0:3]
	s_add_i32 s0, s0, 2
	v_lshl_add_u64 v[134:135], v[134:135], 0, s[80:81]
	v_lshl_add_u64 v[136:137], v[136:137], 0, s[80:81]
	v_lshl_add_u64 v[138:139], v[138:139], 0, s[80:81]
	s_cmpk_lt_u32 s0, 0x7c
	v_lshl_add_u64 v[140:141], v[140:141], 0, s[80:81]
	s_barrier
	s_cbranch_scc1 .LBB0_382
	v_add_u32_e32 v171, 0xc000, v143
	v_add_u32_e32 v172, 0xe000, v143
	v_add_u32_e32 v158, 0x10000, v143
	v_add_u32_e32 v159, 0x12000, v143
	v_add_u32_e32 v160, 0x2000, v143
	v_add_u32_e32 v161, 0x14000, v143
	v_add_u32_e32 v162, 0x16000, v143
	v_add_u32_e32 v163, 0x4000, v143
	v_add_u32_e32 v170, 0x6000, v143
	s_or_b32 s0, s10, 0x80
	s_ashr_i32 s1, s0, 31
	s_lshl_b64 s[0:1], s[0:1], 14
	s_add_u32 s0, s31, s0
	s_addc_u32 s1, s64, s1
	s_add_u32 s0, s0, 0x3f80
	s_addc_u32 s1, s1, 0
	ds_read_b128 v[134:137], v157
	ds_read_b128 v[138:141], v157 offset:1024
	ds_read_b128 v[150:153], v157 offset:2048
	ds_read_b128 v[174:177], v157 offset:3072
	ds_read_b128 v[178:181], v147
	ds_read_b128 v[182:185], v147 offset:1024
	ds_read_b128 v[186:189], v146
	ds_read_b128 v[190:193], v146 offset:1024
	ds_read_b128 v[196:199], v145
	ds_read_b128 v[208:211], v145 offset:1024
	ds_read_b128 v[212:215], v144
	ds_read_b128 v[216:219], v144 offset:1024
	v_lshl_add_u64 v[156:157], v[166:167], 1, s[0:1]
	s_add_i32 m0, s100, 0xc000
	v_lshl_add_u64 v[132:133], v[132:133], 1, s[0:1]
	global_load_lds_dwordx4 v[156:157], off
	s_add_i32 m0, s100, 0xe000
	s_nop 0
	global_load_lds_dwordx4 v[132:133], off
	s_barrier
	s_waitcnt lgkmcnt(0)
	s_setprio 1
	s_waitcnt lgkmcnt(0)
	v_mfma_f32_16x16x32_bf16 v[124:127], v[178:181], v[134:137], v[124:127]
	v_mfma_f32_16x16x32_bf16 v[116:119], v[186:189], v[134:137], v[116:119]
	v_mfma_f32_16x16x32_bf16 v[112:115], v[186:189], v[150:153], v[112:115]
	v_mfma_f32_16x16x32_bf16 v[96:99], v[212:215], v[150:153], v[96:99]
	v_mfma_f32_16x16x32_bf16 v[124:127], v[182:185], v[138:141], v[124:127]
	v_mfma_f32_16x16x32_bf16 v[120:123], v[178:181], v[150:153], v[120:123]
	v_mfma_f32_16x16x32_bf16 v[116:119], v[190:193], v[138:141], v[116:119]
	v_mfma_f32_16x16x32_bf16 v[112:115], v[190:193], v[174:177], v[112:115]
	v_mfma_f32_16x16x32_bf16 v[108:111], v[196:199], v[134:137], v[108:111]
	v_mfma_f32_16x16x32_bf16 v[104:107], v[196:199], v[150:153], v[104:107]
	v_mfma_f32_16x16x32_bf16 v[100:103], v[212:215], v[134:137], v[100:103]
	v_mfma_f32_16x16x32_bf16 v[96:99], v[216:219], v[174:177], v[96:99]
	v_mfma_f32_16x16x32_bf16 v[220:223], v[182:185], v[174:177], v[120:123]
	v_mfma_f32_16x16x32_bf16 v[224:227], v[208:211], v[138:141], v[108:111]
	v_mfma_f32_16x16x32_bf16 v[228:231], v[208:211], v[174:177], v[104:107]
	v_mfma_f32_16x16x32_bf16 v[232:235], v[216:219], v[138:141], v[100:103]
	s_setprio 0
	s_barrier
	s_nop 0
	ds_read_b128 v[100:103], v154
	ds_read_b128 v[104:107], v154 offset:1024
	ds_read_b128 v[108:111], v154 offset:2048
	ds_read_b128 v[120:123], v154 offset:3072
	s_barrier
; #define P8_LDA(dst,b,h) _Pragma("unroll") for(int m=0;m<4;++m) _Pragma("unroll") for(int k=0;k<2;++k) \
;     dst[m][k]=*reinterpret_cast<const bf16x8*>((char*)P8_SA(b,h)+lds_byte(wr*64+m*16+fr,k*32+fq*8))
; #define P8_LDB(dst,b,h) _Pragma("unroll") for(int n=0;n<2;++n) _Pragma("unroll") for(int k=0;k<2;++k) \
;     dst[n][k]=*reinterpret_cast<const bf16x8*>((char*)P8_SB(b,h)+lds_byte(wc*32+n*16+fr,k*32+fq*8))
; #define P8_MMA(ai,bj,At,Bt) do{__builtin_amdgcn_s_setprio(1); \
;     _Pragma("unroll") for(int m=0;m<4;++m) _Pragma("unroll") for(int n=0;n<2;++n) _Pragma("unroll") for(int k=0;k<2;++k) \
;       acc[ai][bj][m][n]=__builtin_amdgcn_mfma_f32_16x16x32_bf16(At[m][k],Bt[n][k],acc[ai][bj][m][n],0,0,0); \
;     __builtin_amdgcn_s_setprio(0);}while(0)
; #define P8_WAIT_V(n) asm volatile("s_waitcnt vmcnt(" #n ")":::"memory")
; #define P8_WAIT_L(n) asm volatile("s_waitcnt lgkmcnt(" #n ")":::"memory")
; #define P8_BAR __builtin_amdgcn_s_barrier()
; template <class EPI>
; DEVI void gemm8_tile(const bfr* __restrict__ A, const bfr* __restrict__ Bt, int K, int brow, int bcol, int nbrow, int nbcol, char* shmc, EPI epi) {
;     ...
;     P8_LDA(At,0,1); P8_WAIT_V(4); P8_BAR; P8_WAIT_L(0); P8_MMA(1,0,At,B0); P8_MMA(1,1,At,B1); P8_BAR; }
;   { P8_LDB(B0,1,0); P8_LDA(At,1,0); P8_WAIT_V(2); P8_BAR; P8_WAIT_L(0); P8_MMA(0,0,At,B0); P8_BAR;
	s_waitcnt lgkmcnt(0)
	s_setprio 1
	s_waitcnt lgkmcnt(0)
	v_mfma_f32_16x16x32_bf16 v[92:95], v[178:181], v[100:103], v[92:95]
	v_mfma_f32_16x16x32_bf16 v[84:87], v[186:189], v[100:103], v[84:87]
	v_mfma_f32_16x16x32_bf16 v[80:83], v[186:189], v[108:111], v[80:83]
	v_mfma_f32_16x16x32_bf16 v[64:67], v[212:215], v[108:111], v[64:67]
	v_mfma_f32_16x16x32_bf16 v[92:95], v[182:185], v[104:107], v[92:95]
	v_mfma_f32_16x16x32_bf16 v[88:91], v[178:181], v[108:111], v[88:91]
	v_mfma_f32_16x16x32_bf16 v[84:87], v[190:193], v[104:107], v[84:87]
	v_mfma_f32_16x16x32_bf16 v[80:83], v[190:193], v[120:123], v[80:83]
	v_mfma_f32_16x16x32_bf16 v[76:79], v[196:199], v[100:103], v[76:79]
	v_mfma_f32_16x16x32_bf16 v[72:75], v[196:199], v[108:111], v[72:75]
	v_mfma_f32_16x16x32_bf16 v[68:71], v[212:215], v[100:103], v[68:71]
	v_mfma_f32_16x16x32_bf16 v[64:67], v[216:219], v[120:123], v[64:67]
	v_mfma_f32_16x16x32_bf16 v[154:157], v[182:185], v[120:123], v[88:91]
	v_mfma_f32_16x16x32_bf16 v[178:181], v[208:211], v[104:107], v[76:79]
	v_mfma_f32_16x16x32_bf16 v[182:185], v[208:211], v[120:123], v[72:75]
	v_mfma_f32_16x16x32_bf16 v[186:189], v[216:219], v[104:107], v[68:71]
	s_setprio 0
	s_barrier
	s_nop 0
	ds_read_b128 v[68:71], v147 offset:16384
	ds_read_b128 v[72:75], v147 offset:17408
	ds_read_b128 v[76:79], v146 offset:16384
	ds_read_b128 v[88:91], v146 offset:17408
	ds_read_b128 v[190:193], v145 offset:16384
	ds_read_b128 v[196:199], v145 offset:17408
	ds_read_b128 v[208:211], v144 offset:16384
	ds_read_b128 v[212:215], v144 offset:17408
	s_waitcnt vmcnt(4)
	s_barrier
	s_waitcnt lgkmcnt(0)
	s_setprio 1
	s_waitcnt lgkmcnt(0)
	v_mfma_f32_16x16x32_bf16 v[60:63], v[68:71], v[134:137], v[60:63]
	v_mfma_f32_16x16x32_bf16 v[52:55], v[76:79], v[134:137], v[52:55]
	v_mfma_f32_16x16x32_bf16 v[48:51], v[76:79], v[150:153], v[48:51]
	v_mfma_f32_16x16x32_bf16 v[32:35], v[208:211], v[150:153], v[32:35]
	v_mfma_f32_16x16x32_bf16 v[60:63], v[72:75], v[138:141], v[60:63]
	v_mfma_f32_16x16x32_bf16 v[56:59], v[68:71], v[150:153], v[56:59]
	v_mfma_f32_16x16x32_bf16 v[52:55], v[88:91], v[138:141], v[52:55]
	v_mfma_f32_16x16x32_bf16 v[48:51], v[88:91], v[174:177], v[48:51]
	v_mfma_f32_16x16x32_bf16 v[44:47], v[190:193], v[134:137], v[44:47]
	v_mfma_f32_16x16x32_bf16 v[40:43], v[190:193], v[150:153], v[40:43]
	v_mfma_f32_16x16x32_bf16 v[36:39], v[208:211], v[134:137], v[36:39]
	v_mfma_f32_16x16x32_bf16 v[32:35], v[212:215], v[174:177], v[32:35]
	v_mfma_f32_16x16x32_bf16 v[216:219], v[72:75], v[174:177], v[56:59]
	v_mfma_f32_16x16x32_bf16 v[236:239], v[196:199], v[138:141], v[44:47]
	v_mfma_f32_16x16x32_bf16 v[240:243], v[196:199], v[174:177], v[40:43]
	v_mfma_f32_16x16x32_bf16 v[132:135], v[212:215], v[138:141], v[36:39]
	s_setprio 0
	s_setprio 1
	v_mfma_f32_16x16x32_bf16 v[28:31], v[68:71], v[100:103], v[28:31]
	v_mfma_f32_16x16x32_bf16 v[20:23], v[76:79], v[100:103], v[20:23]
	v_mfma_f32_16x16x32_bf16 v[16:19], v[76:79], v[108:111], v[16:19]
	v_mfma_f32_16x16x32_bf16 v[0:3], v[208:211], v[108:111], v[0:3]
	v_mfma_f32_16x16x32_bf16 v[28:31], v[72:75], v[104:107], v[28:31]
	v_mfma_f32_16x16x32_bf16 v[24:27], v[68:71], v[108:111], v[24:27]
	v_mfma_f32_16x16x32_bf16 v[20:23], v[88:91], v[104:107], v[20:23]
	v_mfma_f32_16x16x32_bf16 v[16:19], v[88:91], v[120:123], v[16:19]
	v_mfma_f32_16x16x32_bf16 v[12:15], v[190:193], v[100:103], v[12:15]
	v_mfma_f32_16x16x32_bf16 v[8:11], v[190:193], v[108:111], v[8:11]
	v_mfma_f32_16x16x32_bf16 v[4:7], v[208:211], v[100:103], v[4:7]
	v_mfma_f32_16x16x32_bf16 v[0:3], v[212:215], v[120:123], v[0:3]
	v_mfma_f32_16x16x32_bf16 v[136:139], v[72:75], v[120:123], v[24:27]
	v_mfma_f32_16x16x32_bf16 v[150:153], v[196:199], v[104:107], v[12:15]
	v_mfma_f32_16x16x32_bf16 v[172:175], v[196:199], v[120:123], v[8:11]
	v_mfma_f32_16x16x32_bf16 v[190:193], v[212:215], v[104:107], v[4:7]
	s_setprio 0
	s_barrier
	s_nop 0
	ds_read_b128 v[4:7], v149
	ds_read_b128 v[8:11], v149 offset:1024
	ds_read_b128 v[12:15], v149 offset:2048
	ds_read_b128 v[24:27], v149 offset:3072
	ds_read_b128 v[36:39], v147 offset:32768
	ds_read_b128 v[40:43], v147 offset:33792
	ds_read_b128 v[44:47], v146 offset:32768
	ds_read_b128 v[56:59], v146 offset:33792
	ds_read_b128 v[68:71], v145 offset:32768
	ds_read_b128 v[196:199], v145 offset:33792
	ds_read_b128 v[208:211], v144 offset:32768
	ds_read_b128 v[212:215], v144 offset:33792
	s_waitcnt vmcnt(2)
	s_barrier
; #define P8_LDA(dst,b,h) _Pragma("unroll") for(int m=0;m<4;++m) _Pragma("unroll") for(int k=0;k<2;++k) \
;     dst[m][k]=*reinterpret_cast<const bf16x8*>((char*)P8_SA(b,h)+lds_byte(wr*64+m*16+fr,k*32+fq*8))
; #define P8_LDB(dst,b,h) _Pragma("unroll") for(int n=0;n<2;++n) _Pragma("unroll") for(int k=0;k<2;++k) \
;     dst[n][k]=*reinterpret_cast<const bf16x8*>((char*)P8_SB(b,h)+lds_byte(wc*32+n*16+fr,k*32+fq*8))
; #define P8_MMA(ai,bj,At,Bt) do{__builtin_amdgcn_s_setprio(1); \
;     _Pragma("unroll") for(int m=0;m<4;++m) _Pragma("unroll") for(int n=0;n<2;++n) _Pragma("unroll") for(int k=0;k<2;++k) \
;       acc[ai][bj][m][n]=__builtin_amdgcn_mfma_f32_16x16x32_bf16(At[m][k],Bt[n][k],acc[ai][bj][m][n],0,0,0); \
;     __builtin_amdgcn_s_setprio(0);}while(0)
; #define P8_WAIT_V(n) asm volatile("s_waitcnt vmcnt(" #n ")":::"memory")
; #define P8_WAIT_L(n) asm volatile("s_waitcnt lgkmcnt(" #n ")":::"memory")
; #define P8_BAR __builtin_amdgcn_s_barrier()
; template <class EPI>
; DEVI void gemm8_tile(const bfr* __restrict__ A, const bfr* __restrict__ Bt, int K, int brow, int bcol, int nbrow, int nbcol, char* shmc, EPI epi) {
;     ...
;   { P8_LDB(B0,1,0); P8_LDA(At,1,0); P8_WAIT_V(2); P8_BAR; P8_WAIT_L(0); P8_MMA(0,0,At,B0); P8_BAR;
;     P8_LDB(B1,1,1); P8_WAIT_V(0); P8_BAR; P8_WAIT_L(0); P8_MMA(0,1,At,B1); P8_BAR;
;     P8_LDA(At,1,1); P8_BAR; P8_WAIT_L(0); P8_MMA(1,0,At,B0); P8_MMA(1,1,At,B1); P8_BAR; }
;   if(wr==0)P8_BAR;
	s_waitcnt lgkmcnt(0)
	s_setprio 1
	s_waitcnt lgkmcnt(0)
	v_mfma_f32_16x16x32_bf16 v[72:75], v[36:39], v[4:7], v[124:127]
	v_mfma_f32_16x16x32_bf16 v[120:123], v[40:43], v[8:11], v[72:75]
	v_mfma_f32_16x16x32_bf16 v[72:75], v[36:39], v[12:15], v[220:223]
	v_mfma_f32_16x16x32_bf16 v[104:107], v[40:43], v[24:27], v[72:75]
	v_mfma_f32_16x16x32_bf16 v[72:75], v[44:47], v[4:7], v[116:119]
	v_mfma_f32_16x16x32_bf16 v[124:127], v[56:59], v[8:11], v[72:75]
	v_mfma_f32_16x16x32_bf16 v[72:75], v[44:47], v[12:15], v[112:115]
	v_mfma_f32_16x16x32_bf16 v[108:111], v[56:59], v[24:27], v[72:75]
	v_mfma_f32_16x16x32_bf16 v[72:75], v[68:71], v[4:7], v[224:227]
	v_mfma_f32_16x16x32_bf16 v[112:115], v[196:199], v[8:11], v[72:75]
	v_mfma_f32_16x16x32_bf16 v[72:75], v[68:71], v[12:15], v[228:231]
	v_mfma_f32_16x16x32_bf16 v[100:103], v[196:199], v[24:27], v[72:75]
	v_mfma_f32_16x16x32_bf16 v[72:75], v[208:211], v[4:7], v[232:235]
	v_mfma_f32_16x16x32_bf16 v[116:119], v[212:215], v[8:11], v[72:75]
	v_mfma_f32_16x16x32_bf16 v[72:75], v[208:211], v[12:15], v[96:99]
	v_mfma_f32_16x16x32_bf16 v[96:99], v[212:215], v[24:27], v[72:75]
	s_setprio 0
	s_barrier
	ds_read_b128 v[220:223], v148
	ds_read_b128 v[224:227], v148 offset:1024
	ds_read_b128 v[228:231], v148 offset:2048
	ds_read_b128 v[232:235], v148 offset:3072
	s_waitcnt vmcnt(0)
	s_barrier
	s_waitcnt lgkmcnt(0)
	s_setprio 1
	s_waitcnt lgkmcnt(0)
	v_mfma_f32_16x16x32_bf16 v[72:75], v[36:39], v[220:223], v[92:95]
	v_mfma_f32_16x16x32_bf16 v[36:39], v[36:39], v[228:231], v[154:157]
	v_mfma_f32_16x16x32_bf16 v[88:91], v[40:43], v[224:227], v[72:75]
	v_mfma_f32_16x16x32_bf16 v[72:75], v[40:43], v[232:235], v[36:39]
	v_mfma_f32_16x16x32_bf16 v[36:39], v[44:47], v[220:223], v[84:87]
	v_mfma_f32_16x16x32_bf16 v[92:95], v[56:59], v[224:227], v[36:39]
	v_mfma_f32_16x16x32_bf16 v[36:39], v[44:47], v[228:231], v[80:83]
	v_mfma_f32_16x16x32_bf16 v[76:79], v[56:59], v[232:235], v[36:39]
	v_mfma_f32_16x16x32_bf16 v[36:39], v[68:71], v[220:223], v[178:181]
	v_mfma_f32_16x16x32_bf16 v[80:83], v[196:199], v[224:227], v[36:39]
	v_mfma_f32_16x16x32_bf16 v[36:39], v[68:71], v[228:231], v[182:185]
	v_mfma_f32_16x16x32_bf16 v[68:71], v[196:199], v[232:235], v[36:39]
	v_mfma_f32_16x16x32_bf16 v[36:39], v[208:211], v[220:223], v[186:189]
	v_mfma_f32_16x16x32_bf16 v[84:87], v[212:215], v[224:227], v[36:39]
	v_mfma_f32_16x16x32_bf16 v[36:39], v[208:211], v[228:231], v[64:67]
	v_mfma_f32_16x16x32_bf16 v[64:67], v[212:215], v[232:235], v[36:39]
	s_setprio 0
	s_barrier
	ds_read_b128 v[154:157], v147 offset:49152
	ds_read_b128 v[176:179], v147 offset:50176
	ds_read_b128 v[180:183], v146 offset:49152
	ds_read_b128 v[146:149], v146 offset:50176
	ds_read_b128 v[184:187], v145 offset:49152
	ds_read_b128 v[196:199], v145 offset:50176
	ds_read_b128 v[208:211], v144 offset:49152
	ds_read_b128 v[212:215], v144 offset:50176
	s_barrier
	s_waitcnt lgkmcnt(0)
	s_setprio 1
	s_waitcnt lgkmcnt(0)
	v_mfma_f32_16x16x32_bf16 v[36:39], v[154:157], v[4:7], v[60:63]
	v_mfma_f32_16x16x32_bf16 v[56:59], v[176:179], v[8:11], v[36:39]
	v_mfma_f32_16x16x32_bf16 v[36:39], v[154:157], v[12:15], v[216:219]
	v_mfma_f32_16x16x32_bf16 v[40:43], v[176:179], v[24:27], v[36:39]
	v_mfma_f32_16x16x32_bf16 v[36:39], v[180:183], v[4:7], v[52:55]
	v_mfma_f32_16x16x32_bf16 v[60:63], v[146:149], v[8:11], v[36:39]
	v_mfma_f32_16x16x32_bf16 v[36:39], v[180:183], v[12:15], v[48:51]
	v_mfma_f32_16x16x32_bf16 v[44:47], v[146:149], v[24:27], v[36:39]
	v_mfma_f32_16x16x32_bf16 v[36:39], v[184:187], v[4:7], v[236:239]
	v_mfma_f32_16x16x32_bf16 v[4:7], v[208:211], v[4:7], v[132:135]
	v_mfma_f32_16x16x32_bf16 v[48:51], v[196:199], v[8:11], v[36:39]
	v_mfma_f32_16x16x32_bf16 v[36:39], v[184:187], v[12:15], v[240:243]
	v_mfma_f32_16x16x32_bf16 v[52:55], v[212:215], v[8:11], v[4:7]
	v_mfma_f32_16x16x32_bf16 v[4:7], v[208:211], v[12:15], v[32:35]
	v_mfma_f32_16x16x32_bf16 v[36:39], v[196:199], v[24:27], v[36:39]
	v_mfma_f32_16x16x32_bf16 v[32:35], v[212:215], v[24:27], v[4:7]
	s_setprio 0
	s_setprio 1
	v_mfma_f32_16x16x32_bf16 v[4:7], v[154:157], v[220:223], v[28:31]
	v_mfma_f32_16x16x32_bf16 v[24:27], v[176:179], v[224:227], v[4:7]
	v_mfma_f32_16x16x32_bf16 v[4:7], v[154:157], v[228:231], v[136:139]
	v_mfma_f32_16x16x32_bf16 v[8:11], v[176:179], v[232:235], v[4:7]
	v_mfma_f32_16x16x32_bf16 v[4:7], v[180:183], v[220:223], v[20:23]
	v_mfma_f32_16x16x32_bf16 v[28:31], v[146:149], v[224:227], v[4:7]
	v_mfma_f32_16x16x32_bf16 v[4:7], v[180:183], v[228:231], v[16:19]
	v_mfma_f32_16x16x32_bf16 v[12:15], v[146:149], v[232:235], v[4:7]
	v_mfma_f32_16x16x32_bf16 v[4:7], v[184:187], v[220:223], v[150:153]
	v_mfma_f32_16x16x32_bf16 v[16:19], v[196:199], v[224:227], v[4:7]
	v_mfma_f32_16x16x32_bf16 v[4:7], v[184:187], v[228:231], v[172:175]
	v_mfma_f32_16x16x32_bf16 v[20:23], v[208:211], v[220:223], v[190:193]
	v_mfma_f32_16x16x32_bf16 v[0:3], v[208:211], v[228:231], v[0:3]
	v_mfma_f32_16x16x32_bf16 v[4:7], v[196:199], v[232:235], v[4:7]
	v_mfma_f32_16x16x32_bf16 v[20:23], v[212:215], v[224:227], v[20:23]
	v_mfma_f32_16x16x32_bf16 v[0:3], v[212:215], v[232:235], v[0:3]
	s_setprio 0
	v_cmp_gt_u32_e32 vcc, s57, v142
	s_barrier
	s_and_saveexec_b64 s[0:1], vcc
	s_cbranch_execz .LBB0_385
	s_barrier

; #define P8_STAGE(P,BASE,br,kt) do{const bfr* _ub=(BASE)+((long)(br)*K+(long)(kt)*BK); \
;     __builtin_amdgcn_global_load_lds((const unsigned*)(_ub+so0),(unsigned*)((char*)(P)+wid*1024),16,0,0); \
;     __builtin_amdgcn_global_load_lds((const unsigned*)(_ub+so1),(unsigned*)((char*)(P)+wid*1024+8192),16,0,0);}while(0)
; #define P8_LDA(dst,b,h) _Pragma("unroll") for(int m=0;m<4;++m) _Pragma("unroll") for(int k=0;k<2;++k) \
;     dst[m][k]=*reinterpret_cast<const bf16x8*>((char*)P8_SA(b,h)+lds_byte(wr*64+m*16+fr,k*32+fq*8))
; #define P8_LDB(dst,b,h) _Pragma("unroll") for(int n=0;n<2;++n) _Pragma("unroll") for(int k=0;k<2;++k) \
;     dst[n][k]=*reinterpret_cast<const bf16x8*>((char*)P8_SB(b,h)+lds_byte(wc*32+n*16+fr,k*32+fq*8))
; #define P8_MMA(ai,bj,At,Bt) do{__builtin_amdgcn_s_setprio(1); \
;     _Pragma("unroll") for(int m=0;m<4;++m) _Pragma("unroll") for(int n=0;n<2;++n) _Pragma("unroll") for(int k=0;k<2;++k) \
;       acc[ai][bj][m][n]=__builtin_amdgcn_mfma_f32_16x16x32_bf16(At[m][k],Bt[n][k],acc[ai][bj][m][n],0,0,0); \
;     __builtin_amdgcn_s_setprio(0);}while(0)
; #define P8_WAIT_V(n) asm volatile("s_waitcnt vmcnt(" #n ")":::"memory")
; #define P8_WAIT_L(n) asm volatile("s_waitcnt lgkmcnt(" #n ")":::"memory")
; #define P8_BAR __builtin_amdgcn_s_barrier()
; #define P8_SCHED __builtin_amdgcn_sched_barrier(0)
; template <class EPI>
; DEVI void gemm8_tile(const bfr* __restrict__ A, const bfr* __restrict__ Bt, int K, int brow, int bcol, int nbrow, int nbcol, char* shmc, EPI epi) {
;     ...
;     P8_LDB(B0,0,0); P8_SCHED; P8_LDA(At,0,0); P8_STAGE(P8_SA(1,1),A,brow+128,t+1);
;     P8_WAIT_L(8); P8_BAR; P8_WAIT_L(0); P8_MMA(0,0,At,B0); P8_BAR; P8_SCHED;
;     P8_LDB(B1,0,1); P8_STAGE(P8_SB(0,0),Bt,bcol,t+2);
;     P8_BAR; P8_WAIT_L(0); P8_MMA(0,1,At,B1); P8_BAR;
;     P8_LDA(At,0,1); P8_STAGE(P8_SA(0,0),A,brow,t+2);
;     P8_BAR; P8_WAIT_L(0); P8_MMA(1,0,At,B0); P8_BAR; P8_SCHED;
;     P8_STAGE(P8_SB(0,1),Bt,bcol+128,t+2);
;     P8_WAIT_V(6); P8_BAR; P8_MMA(1,1,At,B1); P8_BAR;
.LBB0_401:
	ds_read_b128 v[174:177], v157
	ds_read_b128 v[178:181], v157 offset:1024
	ds_read_b128 v[182:185], v157 offset:2048
	ds_read_b128 v[186:189], v157 offset:3072
	v_add_u32_e32 v158, s54, v136
	s_add_i32 m0, s100, 0xc000
	ds_read_b128 v[160:163], v147
	ds_read_b128 v[190:193], v147 offset:1024
	ds_read_b128 v[196:199], v146
	ds_read_b128 v[208:211], v146 offset:1024
	ds_read_b128 v[212:215], v145
	ds_read_b128 v[216:219], v145 offset:1024
	ds_read_b128 v[220:223], v144
	ds_read_b128 v[224:227], v144 offset:1024
	global_load_lds_dwordx4 v158, s[86:87]
	v_add_u32_e32 v158, s54, v134
	s_add_i32 m0, s100, 0xe000
	s_nop 0
	global_load_lds_dwordx4 v158, s[86:87]
	s_waitcnt lgkmcnt(8)
	s_barrier
	s_waitcnt lgkmcnt(0)
	v_mfma_f32_16x16x32_bf16 v[124:127], v[160:163], v[174:177], v[124:127]
	v_mfma_f32_16x16x32_bf16 v[120:123], v[160:163], v[182:185], v[120:123]
	v_mfma_f32_16x16x32_bf16 v[116:119], v[196:199], v[174:177], v[116:119]
	v_mfma_f32_16x16x32_bf16 v[112:115], v[196:199], v[182:185], v[112:115]
	v_mfma_f32_16x16x32_bf16 v[108:111], v[212:215], v[174:177], v[108:111]
	v_mfma_f32_16x16x32_bf16 v[104:107], v[212:215], v[182:185], v[104:107]
	v_mfma_f32_16x16x32_bf16 v[100:103], v[220:223], v[174:177], v[100:103]
	v_mfma_f32_16x16x32_bf16 v[96:99], v[220:223], v[182:185], v[96:99]
	v_mfma_f32_16x16x32_bf16 v[124:127], v[190:193], v[178:181], v[124:127]
	v_mfma_f32_16x16x32_bf16 v[120:123], v[190:193], v[186:189], v[120:123]
	v_mfma_f32_16x16x32_bf16 v[116:119], v[208:211], v[178:181], v[116:119]
	v_mfma_f32_16x16x32_bf16 v[112:115], v[208:211], v[186:189], v[112:115]
	v_mfma_f32_16x16x32_bf16 v[108:111], v[216:219], v[178:181], v[108:111]
	v_mfma_f32_16x16x32_bf16 v[104:107], v[216:219], v[186:189], v[104:107]
	v_mfma_f32_16x16x32_bf16 v[100:103], v[224:227], v[178:181], v[100:103]
	v_mfma_f32_16x16x32_bf16 v[96:99], v[224:227], v[186:189], v[96:99]
	s_barrier
	v_add_u32_e32 v206, s66, v140
	s_add_i32 m0, s100, 0x10000
	ds_read_b128 v[228:231], v155
	ds_read_b128 v[232:235], v155 offset:1024
	ds_read_b128 v[236:239], v155 offset:2048
	ds_read_b128 v[240:243], v155 offset:3072
	global_load_lds_dwordx4 v206, s[86:87]
	v_add_u32_e32 v244, s66, v138
	s_add_i32 m0, s100, 0x12000
	s_nop 0
	global_load_lds_dwordx4 v244, s[86:87]
	s_barrier
	s_waitcnt lgkmcnt(0)
	v_mfma_f32_16x16x32_bf16 v[92:95], v[160:163], v[228:231], v[92:95]
	v_mfma_f32_16x16x32_bf16 v[88:91], v[160:163], v[236:239], v[88:91]
	v_mfma_f32_16x16x32_bf16 v[84:87], v[196:199], v[228:231], v[84:87]
	v_mfma_f32_16x16x32_bf16 v[80:83], v[196:199], v[236:239], v[80:83]
	v_mfma_f32_16x16x32_bf16 v[76:79], v[212:215], v[228:231], v[76:79]
	v_mfma_f32_16x16x32_bf16 v[72:75], v[212:215], v[236:239], v[72:75]
	v_mfma_f32_16x16x32_bf16 v[68:71], v[220:223], v[228:231], v[68:71]
	v_mfma_f32_16x16x32_bf16 v[64:67], v[220:223], v[236:239], v[64:67]
	v_mfma_f32_16x16x32_bf16 v[92:95], v[190:193], v[232:235], v[92:95]
	v_mfma_f32_16x16x32_bf16 v[88:91], v[190:193], v[240:243], v[88:91]
	v_mfma_f32_16x16x32_bf16 v[84:87], v[208:211], v[232:235], v[84:87]
	v_mfma_f32_16x16x32_bf16 v[80:83], v[208:211], v[240:243], v[80:83]
	v_mfma_f32_16x16x32_bf16 v[76:79], v[216:219], v[232:235], v[76:79]
	v_mfma_f32_16x16x32_bf16 v[72:75], v[216:219], v[240:243], v[72:75]
	v_mfma_f32_16x16x32_bf16 v[68:71], v[224:227], v[232:235], v[68:71]
	v_mfma_f32_16x16x32_bf16 v[64:67], v[224:227], v[240:243], v[64:67]
	v_add_u32_e32 v160, s60, v136
	s_mov_b32 m0, s100
	s_barrier
	ds_read_b128 v[190:193], v147 offset:16384
	ds_read_b128 v[196:199], v147 offset:17408
	ds_read_b128 v[208:211], v146 offset:16384
	ds_read_b128 v[212:215], v146 offset:17408
	ds_read_b128 v[216:219], v145 offset:16384
	ds_read_b128 v[220:223], v145 offset:17408
	ds_read_b128 v[224:227], v144 offset:16384
	ds_read_b128 v[244:247], v144 offset:17408
	global_load_lds_dwordx4 v160, s[86:87]
	v_add_u32_e32 v162, s60, v134
	s_add_i32 m0, s100, 0x2000
	s_nop 0
	global_load_lds_dwordx4 v162, s[86:87]
	s_barrier
	s_waitcnt lgkmcnt(0)
	v_mfma_f32_16x16x32_bf16 v[60:63], v[190:193], v[174:177], v[60:63]
	v_mfma_f32_16x16x32_bf16 v[56:59], v[190:193], v[182:185], v[56:59]
	v_mfma_f32_16x16x32_bf16 v[52:55], v[208:211], v[174:177], v[52:55]
	v_mfma_f32_16x16x32_bf16 v[48:51], v[208:211], v[182:185], v[48:51]
	v_mfma_f32_16x16x32_bf16 v[44:47], v[216:219], v[174:177], v[44:47]
	v_mfma_f32_16x16x32_bf16 v[40:43], v[216:219], v[182:185], v[40:43]
	v_mfma_f32_16x16x32_bf16 v[36:39], v[224:227], v[174:177], v[36:39]
	v_mfma_f32_16x16x32_bf16 v[32:35], v[224:227], v[182:185], v[32:35]
	v_mfma_f32_16x16x32_bf16 v[60:63], v[196:199], v[178:181], v[60:63]
	v_mfma_f32_16x16x32_bf16 v[56:59], v[196:199], v[186:189], v[56:59]
	v_mfma_f32_16x16x32_bf16 v[52:55], v[212:215], v[178:181], v[52:55]
	v_mfma_f32_16x16x32_bf16 v[48:51], v[212:215], v[186:189], v[48:51]
	v_mfma_f32_16x16x32_bf16 v[44:47], v[220:223], v[178:181], v[44:47]
	v_mfma_f32_16x16x32_bf16 v[40:43], v[220:223], v[186:189], v[40:43]
	v_mfma_f32_16x16x32_bf16 v[36:39], v[244:247], v[178:181], v[36:39]
	v_mfma_f32_16x16x32_bf16 v[32:35], v[244:247], v[186:189], v[32:35]
	s_barrier
	v_add_u32_e32 v162, s70, v140
	s_add_i32 m0, s100, 0x14000
	v_add_u32_e32 v174, s70, v138
	global_load_lds_dwordx4 v162, s[86:87]
	s_nop 0
	s_add_i32 m0, s100, 0x16000
	s_nop 0
	global_load_lds_dwordx4 v174, s[86:87]
	s_waitcnt vmcnt(6)
	s_barrier
; #define P8_STAGE(P,BASE,br,kt) do{const bfr* _ub=(BASE)+((long)(br)*K+(long)(kt)*BK); \
;     __builtin_amdgcn_global_load_lds((const unsigned*)(_ub+so0),(unsigned*)((char*)(P)+wid*1024),16,0,0); \
;     __builtin_amdgcn_global_load_lds((const unsigned*)(_ub+so1),(unsigned*)((char*)(P)+wid*1024+8192),16,0,0);}while(0)
; #define P8_LDA(dst,b,h) _Pragma("unroll") for(int m=0;m<4;++m) _Pragma("unroll") for(int k=0;k<2;++k) \
;     dst[m][k]=*reinterpret_cast<const bf16x8*>((char*)P8_SA(b,h)+lds_byte(wr*64+m*16+fr,k*32+fq*8))
; #define P8_LDB(dst,b,h) _Pragma("unroll") for(int n=0;n<2;++n) _Pragma("unroll") for(int k=0;k<2;++k) \
;     dst[n][k]=*reinterpret_cast<const bf16x8*>((char*)P8_SB(b,h)+lds_byte(wc*32+n*16+fr,k*32+fq*8))
; #define P8_MMA(ai,bj,At,Bt) do{__builtin_amdgcn_s_setprio(1); \
;     _Pragma("unroll") for(int m=0;m<4;++m) _Pragma("unroll") for(int n=0;n<2;++n) _Pragma("unroll") for(int k=0;k<2;++k) \
;       acc[ai][bj][m][n]=__builtin_amdgcn_mfma_f32_16x16x32_bf16(At[m][k],Bt[n][k],acc[ai][bj][m][n],0,0,0); \
;     __builtin_amdgcn_s_setprio(0);}while(0)
; #define P8_WAIT_V(n) asm volatile("s_waitcnt vmcnt(" #n ")":::"memory")
; #define P8_WAIT_L(n) asm volatile("s_waitcnt lgkmcnt(" #n ")":::"memory")
; #define P8_BAR __builtin_amdgcn_s_barrier()
; #define P8_SCHED __builtin_amdgcn_sched_barrier(0)
; template <class EPI>
; DEVI void gemm8_tile(const bfr* __restrict__ A, const bfr* __restrict__ Bt, int K, int brow, int bcol, int nbrow, int nbcol, char* shmc, EPI epi) {
;     ...
;     P8_WAIT_V(6); P8_BAR; P8_MMA(1,1,At,B1); P8_BAR;
;     P8_LDB(B0,1,0); P8_SCHED; P8_LDA(At,1,0); P8_STAGE(P8_SA(0,1),A,brow+128,t+2);
;     P8_WAIT_L(8); P8_BAR; P8_WAIT_L(0); P8_MMA(0,0,At,B0); P8_BAR; P8_SCHED;
;     P8_LDB(B1,1,1); P8_STAGE(P8_SB(1,0),Bt,bcol,t+3);
;     P8_BAR; P8_WAIT_L(0); P8_MMA(0,1,At,B1); P8_BAR;
;     P8_LDA(At,1,1); P8_STAGE(P8_SA(1,0),A,brow,t+3);
	v_mfma_f32_16x16x32_bf16 v[28:31], v[190:193], v[228:231], v[28:31]
	v_mfma_f32_16x16x32_bf16 v[24:27], v[190:193], v[236:239], v[24:27]
	v_mfma_f32_16x16x32_bf16 v[20:23], v[208:211], v[228:231], v[20:23]
	v_mfma_f32_16x16x32_bf16 v[16:19], v[208:211], v[236:239], v[16:19]
	v_mfma_f32_16x16x32_bf16 v[12:15], v[216:219], v[228:231], v[12:15]
	v_mfma_f32_16x16x32_bf16 v[8:11], v[216:219], v[236:239], v[8:11]
	v_mfma_f32_16x16x32_bf16 v[4:7], v[224:227], v[228:231], v[4:7]
	v_mfma_f32_16x16x32_bf16 v[0:3], v[224:227], v[236:239], v[0:3]
	v_mfma_f32_16x16x32_bf16 v[28:31], v[196:199], v[232:235], v[28:31]
	v_mfma_f32_16x16x32_bf16 v[24:27], v[196:199], v[240:243], v[24:27]
	v_mfma_f32_16x16x32_bf16 v[20:23], v[212:215], v[232:235], v[20:23]
	v_mfma_f32_16x16x32_bf16 v[16:19], v[212:215], v[240:243], v[16:19]
	v_mfma_f32_16x16x32_bf16 v[12:15], v[220:223], v[232:235], v[12:15]
	v_mfma_f32_16x16x32_bf16 v[8:11], v[220:223], v[240:243], v[8:11]
	v_mfma_f32_16x16x32_bf16 v[4:7], v[244:247], v[232:235], v[4:7]
	v_mfma_f32_16x16x32_bf16 v[0:3], v[244:247], v[240:243], v[0:3]
	s_barrier
	ds_read_b128 v[174:177], v149
	ds_read_b128 v[178:181], v149 offset:1024
	ds_read_b128 v[182:185], v149 offset:2048
	ds_read_b128 v[186:189], v149 offset:3072
	v_add_u32_e32 v232, s68, v136
	s_add_i32 m0, s100, 0x4000
	ds_read_b128 v[190:193], v147 offset:32768
	ds_read_b128 v[196:199], v147 offset:33792
	ds_read_b128 v[208:211], v146 offset:32768
	ds_read_b128 v[212:215], v146 offset:33792
	ds_read_b128 v[216:219], v145 offset:32768
	ds_read_b128 v[220:223], v145 offset:33792
	ds_read_b128 v[224:227], v144 offset:32768
	ds_read_b128 v[228:231], v144 offset:33792
	global_load_lds_dwordx4 v232, s[86:87]
	v_add_u32_e32 v232, s68, v134
	s_add_i32 m0, s100, 0x6000
	s_nop 0
	global_load_lds_dwordx4 v232, s[86:87]
	s_waitcnt lgkmcnt(8)
	s_barrier
	s_waitcnt lgkmcnt(0)
	v_mfma_f32_16x16x32_bf16 v[124:127], v[190:193], v[174:177], v[124:127]
	v_mfma_f32_16x16x32_bf16 v[120:123], v[190:193], v[182:185], v[120:123]
	v_mfma_f32_16x16x32_bf16 v[116:119], v[208:211], v[174:177], v[116:119]
	v_mfma_f32_16x16x32_bf16 v[112:115], v[208:211], v[182:185], v[112:115]
	v_mfma_f32_16x16x32_bf16 v[108:111], v[216:219], v[174:177], v[108:111]
	v_mfma_f32_16x16x32_bf16 v[104:107], v[216:219], v[182:185], v[104:107]
	v_mfma_f32_16x16x32_bf16 v[100:103], v[224:227], v[174:177], v[100:103]
	v_mfma_f32_16x16x32_bf16 v[96:99], v[224:227], v[182:185], v[96:99]
	v_mfma_f32_16x16x32_bf16 v[124:127], v[196:199], v[178:181], v[124:127]
	v_mfma_f32_16x16x32_bf16 v[120:123], v[196:199], v[186:189], v[120:123]
	v_mfma_f32_16x16x32_bf16 v[116:119], v[212:215], v[178:181], v[116:119]
	v_mfma_f32_16x16x32_bf16 v[112:115], v[212:215], v[186:189], v[112:115]
	v_mfma_f32_16x16x32_bf16 v[108:111], v[220:223], v[178:181], v[108:111]
	v_mfma_f32_16x16x32_bf16 v[104:107], v[220:223], v[186:189], v[104:107]
	v_mfma_f32_16x16x32_bf16 v[100:103], v[228:231], v[178:181], v[100:103]
	v_mfma_f32_16x16x32_bf16 v[96:99], v[228:231], v[186:189], v[96:99]
	s_barrier
	v_add_u32_e32 v248, s74, v140
	s_add_i32 m0, s100, 0x18000
	ds_read_b128 v[232:235], v148
	ds_read_b128 v[236:239], v148 offset:1024
	ds_read_b128 v[240:243], v148 offset:2048
	ds_read_b128 v[244:247], v148 offset:3072
	global_load_lds_dwordx4 v248, s[86:87]
	v_add_u32_e32 v248, s74, v138
	s_add_i32 m0, s100, 0x1a000
	s_nop 0
	global_load_lds_dwordx4 v248, s[86:87]
	s_barrier
	s_waitcnt lgkmcnt(0)
	v_mfma_f32_16x16x32_bf16 v[92:95], v[190:193], v[232:235], v[92:95]
	v_mfma_f32_16x16x32_bf16 v[88:91], v[190:193], v[240:243], v[88:91]
	v_mfma_f32_16x16x32_bf16 v[84:87], v[208:211], v[232:235], v[84:87]
	v_mfma_f32_16x16x32_bf16 v[80:83], v[208:211], v[240:243], v[80:83]
	v_mfma_f32_16x16x32_bf16 v[76:79], v[216:219], v[232:235], v[76:79]
	v_mfma_f32_16x16x32_bf16 v[72:75], v[216:219], v[240:243], v[72:75]
	v_mfma_f32_16x16x32_bf16 v[68:71], v[224:227], v[232:235], v[68:71]
	v_mfma_f32_16x16x32_bf16 v[64:67], v[224:227], v[240:243], v[64:67]
	v_mfma_f32_16x16x32_bf16 v[92:95], v[196:199], v[236:239], v[92:95]
	v_mfma_f32_16x16x32_bf16 v[88:91], v[196:199], v[244:247], v[88:91]
	v_mfma_f32_16x16x32_bf16 v[84:87], v[212:215], v[236:239], v[84:87]
	v_mfma_f32_16x16x32_bf16 v[80:83], v[212:215], v[244:247], v[80:83]
	v_mfma_f32_16x16x32_bf16 v[76:79], v[220:223], v[236:239], v[76:79]
	v_mfma_f32_16x16x32_bf16 v[72:75], v[220:223], v[244:247], v[72:75]
	v_mfma_f32_16x16x32_bf16 v[68:71], v[228:231], v[236:239], v[68:71]
	v_mfma_f32_16x16x32_bf16 v[64:67], v[228:231], v[244:247], v[64:67]
	v_add_u32_e32 v200, s72, v136
	s_add_i32 m0, s100, 0x8000
	s_barrier
	ds_read_b128 v[190:193], v147 offset:49152
	ds_read_b128 v[196:199], v147 offset:50176
	ds_read_b128 v[208:211], v146 offset:49152
	ds_read_b128 v[212:215], v146 offset:50176
	ds_read_b128 v[216:219], v145 offset:49152
	ds_read_b128 v[220:223], v145 offset:50176
	ds_read_b128 v[224:227], v144 offset:49152
	ds_read_b128 v[228:231], v144 offset:50176
	global_load_lds_dwordx4 v200, s[86:87]
	v_add_u32_e32 v200, s72, v134
	s_add_i32 m0, s100, 0xa000
	s_nop 0
	global_load_lds_dwordx4 v200, s[86:87]
	s_barrier
; #define P8_STAGE(P,BASE,br,kt) do{const bfr* _ub=(BASE)+((long)(br)*K+(long)(kt)*BK); \
;     __builtin_amdgcn_global_load_lds((const unsigned*)(_ub+so0),(unsigned*)((char*)(P)+wid*1024),16,0,0); \
;     __builtin_amdgcn_global_load_lds((const unsigned*)(_ub+so1),(unsigned*)((char*)(P)+wid*1024+8192),16,0,0);}while(0)
; #define P8_LDA(dst,b,h) _Pragma("unroll") for(int m=0;m<4;++m) _Pragma("unroll") for(int k=0;k<2;++k) \
;     dst[m][k]=*reinterpret_cast<const bf16x8*>((char*)P8_SA(b,h)+lds_byte(wr*64+m*16+fr,k*32+fq*8))
; #define P8_LDB(dst,b,h) _Pragma("unroll") for(int n=0;n<2;++n) _Pragma("unroll") for(int k=0;k<2;++k) \
;     dst[n][k]=*reinterpret_cast<const bf16x8*>((char*)P8_SB(b,h)+lds_byte(wc*32+n*16+fr,k*32+fq*8))
; #define P8_MMA(ai,bj,At,Bt) do{__builtin_amdgcn_s_setprio(1); \
;     _Pragma("unroll") for(int m=0;m<4;++m) _Pragma("unroll") for(int n=0;n<2;++n) _Pragma("unroll") for(int k=0;k<2;++k) \
;       acc[ai][bj][m][n]=__builtin_amdgcn_mfma_f32_16x16x32_bf16(At[m][k],Bt[n][k],acc[ai][bj][m][n],0,0,0); \
;     __builtin_amdgcn_s_setprio(0);}while(0)
; #define P8_WAIT_V(n) asm volatile("s_waitcnt vmcnt(" #n ")":::"memory")
; #define P8_WAIT_L(n) asm volatile("s_waitcnt lgkmcnt(" #n ")":::"memory")
; #define P8_BAR __builtin_amdgcn_s_barrier()
; #define P8_SCHED __builtin_amdgcn_sched_barrier(0)
; template <class EPI>
; DEVI void gemm8_tile(const bfr* __restrict__ A, const bfr* __restrict__ Bt, int K, int brow, int bcol, int nbrow, int nbcol, char* shmc, EPI epi) {
;     ...
;     P8_BAR; P8_WAIT_L(0); P8_MMA(1,0,At,B0); P8_BAR; P8_SCHED;
;     P8_STAGE(P8_SB(1,1),Bt,bcol+128,t+3);
;     P8_WAIT_V(6); P8_BAR; P8_MMA(1,1,At,B1); P8_BAR;
;   }
;   { P8_LDB(B0,0,0); P8_LDA(At,0,0); P8_STAGE(P8_SA(1,1),A,brow+128,nt-1);
;     P8_BAR; P8_WAIT_L(0); P8_MMA(0,0,At,B0); P8_BAR;
	s_waitcnt lgkmcnt(0)
	v_mfma_f32_16x16x32_bf16 v[60:63], v[190:193], v[174:177], v[60:63]
	v_mfma_f32_16x16x32_bf16 v[56:59], v[190:193], v[182:185], v[56:59]
	v_mfma_f32_16x16x32_bf16 v[52:55], v[208:211], v[174:177], v[52:55]
	v_mfma_f32_16x16x32_bf16 v[48:51], v[208:211], v[182:185], v[48:51]
	v_mfma_f32_16x16x32_bf16 v[44:47], v[216:219], v[174:177], v[44:47]
	v_mfma_f32_16x16x32_bf16 v[40:43], v[216:219], v[182:185], v[40:43]
	v_mfma_f32_16x16x32_bf16 v[36:39], v[224:227], v[174:177], v[36:39]
	v_mfma_f32_16x16x32_bf16 v[32:35], v[224:227], v[182:185], v[32:35]
	v_mfma_f32_16x16x32_bf16 v[60:63], v[196:199], v[178:181], v[60:63]
	v_mfma_f32_16x16x32_bf16 v[56:59], v[196:199], v[186:189], v[56:59]
	v_mfma_f32_16x16x32_bf16 v[52:55], v[212:215], v[178:181], v[52:55]
	v_mfma_f32_16x16x32_bf16 v[48:51], v[212:215], v[186:189], v[48:51]
	v_mfma_f32_16x16x32_bf16 v[44:47], v[220:223], v[178:181], v[44:47]
	v_mfma_f32_16x16x32_bf16 v[40:43], v[220:223], v[186:189], v[40:43]
	v_mfma_f32_16x16x32_bf16 v[36:39], v[228:231], v[178:181], v[36:39]
	v_mfma_f32_16x16x32_bf16 v[32:35], v[228:231], v[186:189], v[32:35]
	s_barrier
	v_add_u32_e32 v174, s78, v140
	s_add_i32 m0, s100, 0x1c000
	s_nop 0
	global_load_lds_dwordx4 v174, s[86:87]
	v_add_u32_e32 v174, s78, v138
	s_add_i32 m0, s100, 0x1e000
	s_nop 0
	global_load_lds_dwordx4 v174, s[86:87]
	s_waitcnt vmcnt(6)
	s_barrier
	v_mfma_f32_16x16x32_bf16 v[28:31], v[190:193], v[232:235], v[28:31]
	v_mfma_f32_16x16x32_bf16 v[24:27], v[190:193], v[240:243], v[24:27]
	v_mfma_f32_16x16x32_bf16 v[20:23], v[208:211], v[232:235], v[20:23]
	v_mfma_f32_16x16x32_bf16 v[16:19], v[208:211], v[240:243], v[16:19]
	v_mfma_f32_16x16x32_bf16 v[12:15], v[216:219], v[232:235], v[12:15]
	v_mfma_f32_16x16x32_bf16 v[8:11], v[216:219], v[240:243], v[8:11]
	v_mfma_f32_16x16x32_bf16 v[4:7], v[224:227], v[232:235], v[4:7]
	v_mfma_f32_16x16x32_bf16 v[0:3], v[224:227], v[240:243], v[0:3]
	v_mfma_f32_16x16x32_bf16 v[28:31], v[196:199], v[236:239], v[28:31]
	v_mfma_f32_16x16x32_bf16 v[24:27], v[196:199], v[244:247], v[24:27]
	v_mfma_f32_16x16x32_bf16 v[20:23], v[212:215], v[236:239], v[20:23]
	v_mfma_f32_16x16x32_bf16 v[16:19], v[212:215], v[244:247], v[16:19]
	v_mfma_f32_16x16x32_bf16 v[12:15], v[220:223], v[236:239], v[12:15]
	v_mfma_f32_16x16x32_bf16 v[8:11], v[220:223], v[244:247], v[8:11]
	v_mfma_f32_16x16x32_bf16 v[4:7], v[228:231], v[236:239], v[4:7]
	v_mfma_f32_16x16x32_bf16 v[0:3], v[228:231], v[244:247], v[0:3]
	s_add_i32 s0, s0, 2
	v_lshl_add_u64 v[134:135], v[134:135], 0, s[80:81]
	v_lshl_add_u64 v[136:137], v[136:137], 0, s[80:81]
	v_lshl_add_u64 v[138:139], v[138:139], 0, s[80:81]
	s_cmp_lt_u32 s0, 28
	v_lshl_add_u64 v[140:141], v[140:141], 0, s[80:81]
	s_barrier
	s_cbranch_scc1 .LBB0_401
	v_add_u32_e32 v171, 0xc000, v143
	v_add_u32_e32 v172, 0xe000, v143
	v_add_u32_e32 v158, 0x10000, v143
	v_add_u32_e32 v159, 0x12000, v143
	v_add_u32_e32 v160, 0x2000, v143
	v_add_u32_e32 v161, 0x14000, v143
	v_add_u32_e32 v162, 0x16000, v143
	v_add_u32_e32 v163, 0x4000, v143
	v_add_u32_e32 v170, 0x6000, v143
	s_or_b32 s0, s34, 0x80
	s_ashr_i32 s1, s0, 31
	s_lshl_b64 s[0:1], s[0:1], 12
	s_add_u32 s0, s31, s0
	s_addc_u32 s1, s64, s1
	ds_read_b128 v[134:137], v157
	ds_read_b128 v[138:141], v157 offset:1024
	ds_read_b128 v[150:153], v157 offset:2048
	ds_read_b128 v[174:177], v157 offset:3072
	ds_read_b128 v[178:181], v147
	ds_read_b128 v[182:185], v147 offset:1024
	ds_read_b128 v[186:189], v146
	ds_read_b128 v[190:193], v146 offset:1024
	ds_read_b128 v[196:199], v145
	ds_read_b128 v[208:211], v145 offset:1024
	ds_read_b128 v[212:215], v144
	ds_read_b128 v[216:219], v144 offset:1024
	v_lshl_add_u64 v[156:157], v[166:167], 1, s[0:1]
	s_mov_b64 s[54:55], 0xf80
	v_lshl_add_u64 v[156:157], v[156:157], 0, s[54:55]
	s_add_i32 m0, s100, 0xc000
	v_lshl_add_u64 v[132:133], v[132:133], 1, s[0:1]
	global_load_lds_dwordx4 v[156:157], off
	v_lshl_add_u64 v[132:133], v[132:133], 0, s[54:55]
	s_add_i32 m0, s100, 0xe000
	s_nop 0
	global_load_lds_dwordx4 v[132:133], off
	s_barrier
	s_waitcnt lgkmcnt(0)
	s_setprio 1
	s_waitcnt lgkmcnt(0)
	v_mfma_f32_16x16x32_bf16 v[124:127], v[178:181], v[134:137], v[124:127]
	v_mfma_f32_16x16x32_bf16 v[116:119], v[186:189], v[134:137], v[116:119]
	v_mfma_f32_16x16x32_bf16 v[112:115], v[186:189], v[150:153], v[112:115]
	v_mfma_f32_16x16x32_bf16 v[100:103], v[212:215], v[134:137], v[100:103]
	v_mfma_f32_16x16x32_bf16 v[124:127], v[182:185], v[138:141], v[124:127]
	v_mfma_f32_16x16x32_bf16 v[120:123], v[178:181], v[150:153], v[120:123]
	v_mfma_f32_16x16x32_bf16 v[116:119], v[190:193], v[138:141], v[116:119]
	v_mfma_f32_16x16x32_bf16 v[112:115], v[190:193], v[174:177], v[112:115]
	v_mfma_f32_16x16x32_bf16 v[108:111], v[196:199], v[134:137], v[108:111]
	v_mfma_f32_16x16x32_bf16 v[104:107], v[196:199], v[150:153], v[104:107]
	v_mfma_f32_16x16x32_bf16 v[100:103], v[216:219], v[138:141], v[100:103]
	v_mfma_f32_16x16x32_bf16 v[96:99], v[212:215], v[150:153], v[96:99]
	v_mfma_f32_16x16x32_bf16 v[220:223], v[182:185], v[174:177], v[120:123]
	v_mfma_f32_16x16x32_bf16 v[224:227], v[208:211], v[138:141], v[108:111]
	v_mfma_f32_16x16x32_bf16 v[228:231], v[208:211], v[174:177], v[104:107]
	v_mfma_f32_16x16x32_bf16 v[232:235], v[216:219], v[174:177], v[96:99]
	s_setprio 0
	s_barrier
	s_nop 1
	ds_read_b128 v[96:99], v155
	ds_read_b128 v[104:107], v155 offset:1024
	ds_read_b128 v[108:111], v155 offset:2048
	ds_read_b128 v[120:123], v155 offset:3072
	s_barrier
; #define P8_LDA(dst,b,h) _Pragma("unroll") for(int m=0;m<4;++m) _Pragma("unroll") for(int k=0;k<2;++k) \
;     dst[m][k]=*reinterpret_cast<const bf16x8*>((char*)P8_SA(b,h)+lds_byte(wr*64+m*16+fr,k*32+fq*8))
; #define P8_LDB(dst,b,h) _Pragma("unroll") for(int n=0;n<2;++n) _Pragma("unroll") for(int k=0;k<2;++k) \
;     dst[n][k]=*reinterpret_cast<const bf16x8*>((char*)P8_SB(b,h)+lds_byte(wc*32+n*16+fr,k*32+fq*8))
; #define P8_MMA(ai,bj,At,Bt) do{__builtin_amdgcn_s_setprio(1); \
;     _Pragma("unroll") for(int m=0;m<4;++m) _Pragma("unroll") for(int n=0;n<2;++n) _Pragma("unroll") for(int k=0;k<2;++k) \
;       acc[ai][bj][m][n]=__builtin_amdgcn_mfma_f32_16x16x32_bf16(At[m][k],Bt[n][k],acc[ai][bj][m][n],0,0,0); \
;     __builtin_amdgcn_s_setprio(0);}while(0)
; #define P8_WAIT_V(n) asm volatile("s_waitcnt vmcnt(" #n ")":::"memory")
; #define P8_WAIT_L(n) asm volatile("s_waitcnt lgkmcnt(" #n ")":::"memory")
; #define P8_BAR __builtin_amdgcn_s_barrier()
; template <class EPI>
; DEVI void gemm8_tile(const bfr* __restrict__ A, const bfr* __restrict__ Bt, int K, int brow, int bcol, int nbrow, int nbcol, char* shmc, EPI epi) {
;     ...
;     P8_BAR; P8_WAIT_L(0); P8_MMA(0,0,At,B0); P8_BAR;
;     P8_LDB(B1,0,1); P8_BAR; P8_WAIT_L(0); P8_MMA(0,1,At,B1); P8_BAR;
;     P8_LDA(At,0,1); P8_WAIT_V(4); P8_BAR; P8_WAIT_L(0); P8_MMA(1,0,At,B0); P8_MMA(1,1,At,B1); P8_BAR; }
;   { P8_LDB(B0,1,0); P8_LDA(At,1,0); P8_WAIT_V(2); P8_BAR; P8_WAIT_L(0); P8_MMA(0,0,At,B0); P8_BAR;
	s_waitcnt lgkmcnt(0)
	s_setprio 1
	s_waitcnt lgkmcnt(0)
	v_mfma_f32_16x16x32_bf16 v[92:95], v[178:181], v[96:99], v[92:95]
	v_mfma_f32_16x16x32_bf16 v[84:87], v[186:189], v[96:99], v[84:87]
	v_mfma_f32_16x16x32_bf16 v[80:83], v[186:189], v[108:111], v[80:83]
	v_mfma_f32_16x16x32_bf16 v[68:71], v[212:215], v[96:99], v[68:71]
	v_mfma_f32_16x16x32_bf16 v[92:95], v[182:185], v[104:107], v[92:95]
	v_mfma_f32_16x16x32_bf16 v[88:91], v[178:181], v[108:111], v[88:91]
	v_mfma_f32_16x16x32_bf16 v[84:87], v[190:193], v[104:107], v[84:87]
	v_mfma_f32_16x16x32_bf16 v[80:83], v[190:193], v[120:123], v[80:83]
	v_mfma_f32_16x16x32_bf16 v[76:79], v[196:199], v[96:99], v[76:79]
	v_mfma_f32_16x16x32_bf16 v[72:75], v[196:199], v[108:111], v[72:75]
	v_mfma_f32_16x16x32_bf16 v[68:71], v[216:219], v[104:107], v[68:71]
	v_mfma_f32_16x16x32_bf16 v[64:67], v[212:215], v[108:111], v[64:67]
	v_mfma_f32_16x16x32_bf16 v[154:157], v[182:185], v[120:123], v[88:91]
	v_mfma_f32_16x16x32_bf16 v[178:181], v[208:211], v[104:107], v[76:79]
	v_mfma_f32_16x16x32_bf16 v[182:185], v[208:211], v[120:123], v[72:75]
	v_mfma_f32_16x16x32_bf16 v[186:189], v[216:219], v[120:123], v[64:67]
	s_setprio 0
	s_barrier
	s_nop 1
	ds_read_b128 v[64:67], v147 offset:16384
	ds_read_b128 v[72:75], v147 offset:17408
	ds_read_b128 v[76:79], v146 offset:16384
	ds_read_b128 v[88:91], v146 offset:17408
	ds_read_b128 v[190:193], v145 offset:16384
	ds_read_b128 v[196:199], v145 offset:17408
	ds_read_b128 v[208:211], v144 offset:16384
	ds_read_b128 v[212:215], v144 offset:17408
	s_waitcnt vmcnt(4)
	s_barrier
	s_waitcnt lgkmcnt(0)
	s_setprio 1
	s_waitcnt lgkmcnt(0)
	v_mfma_f32_16x16x32_bf16 v[60:63], v[64:67], v[134:137], v[60:63]
	v_mfma_f32_16x16x32_bf16 v[52:55], v[76:79], v[134:137], v[52:55]
	v_mfma_f32_16x16x32_bf16 v[48:51], v[76:79], v[150:153], v[48:51]
	v_mfma_f32_16x16x32_bf16 v[36:39], v[208:211], v[134:137], v[36:39]
	v_mfma_f32_16x16x32_bf16 v[60:63], v[72:75], v[138:141], v[60:63]
	v_mfma_f32_16x16x32_bf16 v[56:59], v[64:67], v[150:153], v[56:59]
	v_mfma_f32_16x16x32_bf16 v[52:55], v[88:91], v[138:141], v[52:55]
	v_mfma_f32_16x16x32_bf16 v[48:51], v[88:91], v[174:177], v[48:51]
	v_mfma_f32_16x16x32_bf16 v[44:47], v[190:193], v[134:137], v[44:47]
	v_mfma_f32_16x16x32_bf16 v[40:43], v[190:193], v[150:153], v[40:43]
	v_mfma_f32_16x16x32_bf16 v[36:39], v[212:215], v[138:141], v[36:39]
	v_mfma_f32_16x16x32_bf16 v[32:35], v[208:211], v[150:153], v[32:35]
	v_mfma_f32_16x16x32_bf16 v[216:219], v[72:75], v[174:177], v[56:59]
	v_mfma_f32_16x16x32_bf16 v[236:239], v[196:199], v[138:141], v[44:47]
	v_mfma_f32_16x16x32_bf16 v[240:243], v[196:199], v[174:177], v[40:43]
	v_mfma_f32_16x16x32_bf16 v[132:135], v[212:215], v[174:177], v[32:35]
	s_setprio 0
	s_setprio 1
	v_mfma_f32_16x16x32_bf16 v[28:31], v[64:67], v[96:99], v[28:31]
	v_mfma_f32_16x16x32_bf16 v[20:23], v[76:79], v[96:99], v[20:23]
	v_mfma_f32_16x16x32_bf16 v[16:19], v[76:79], v[108:111], v[16:19]
	v_mfma_f32_16x16x32_bf16 v[4:7], v[208:211], v[96:99], v[4:7]
	v_mfma_f32_16x16x32_bf16 v[28:31], v[72:75], v[104:107], v[28:31]
	v_mfma_f32_16x16x32_bf16 v[24:27], v[64:67], v[108:111], v[24:27]
	v_mfma_f32_16x16x32_bf16 v[20:23], v[88:91], v[104:107], v[20:23]
	v_mfma_f32_16x16x32_bf16 v[16:19], v[88:91], v[120:123], v[16:19]
	v_mfma_f32_16x16x32_bf16 v[12:15], v[190:193], v[96:99], v[12:15]
	v_mfma_f32_16x16x32_bf16 v[8:11], v[190:193], v[108:111], v[8:11]
	v_mfma_f32_16x16x32_bf16 v[4:7], v[212:215], v[104:107], v[4:7]
	v_mfma_f32_16x16x32_bf16 v[0:3], v[208:211], v[108:111], v[0:3]
	v_mfma_f32_16x16x32_bf16 v[136:139], v[72:75], v[120:123], v[24:27]
	v_mfma_f32_16x16x32_bf16 v[150:153], v[196:199], v[104:107], v[12:15]
	v_mfma_f32_16x16x32_bf16 v[172:175], v[196:199], v[120:123], v[8:11]
	v_mfma_f32_16x16x32_bf16 v[190:193], v[212:215], v[120:123], v[0:3]
	s_setprio 0
	s_barrier
	s_nop 1
	ds_read_b128 v[0:3], v149
	ds_read_b128 v[8:11], v149 offset:1024
	ds_read_b128 v[12:15], v149 offset:2048
	ds_read_b128 v[24:27], v149 offset:3072
	ds_read_b128 v[32:35], v147 offset:32768
	ds_read_b128 v[40:43], v147 offset:33792
	ds_read_b128 v[44:47], v146 offset:32768
	ds_read_b128 v[56:59], v146 offset:33792
	ds_read_b128 v[64:67], v145 offset:32768
	ds_read_b128 v[196:199], v145 offset:33792
	ds_read_b128 v[208:211], v144 offset:32768
	ds_read_b128 v[212:215], v144 offset:33792
	s_waitcnt vmcnt(2)
	s_barrier
; #define P8_LDA(dst,b,h) _Pragma("unroll") for(int m=0;m<4;++m) _Pragma("unroll") for(int k=0;k<2;++k) \
;     dst[m][k]=*reinterpret_cast<const bf16x8*>((char*)P8_SA(b,h)+lds_byte(wr*64+m*16+fr,k*32+fq*8))
; #define P8_LDB(dst,b,h) _Pragma("unroll") for(int n=0;n<2;++n) _Pragma("unroll") for(int k=0;k<2;++k) \
;     dst[n][k]=*reinterpret_cast<const bf16x8*>((char*)P8_SB(b,h)+lds_byte(wc*32+n*16+fr,k*32+fq*8))
; #define P8_MMA(ai,bj,At,Bt) do{__builtin_amdgcn_s_setprio(1); \
;     _Pragma("unroll") for(int m=0;m<4;++m) _Pragma("unroll") for(int n=0;n<2;++n) _Pragma("unroll") for(int k=0;k<2;++k) \
;       acc[ai][bj][m][n]=__builtin_amdgcn_mfma_f32_16x16x32_bf16(At[m][k],Bt[n][k],acc[ai][bj][m][n],0,0,0); \
;     __builtin_amdgcn_s_setprio(0);}while(0)
; #define P8_WAIT_V(n) asm volatile("s_waitcnt vmcnt(" #n ")":::"memory")
; #define P8_WAIT_L(n) asm volatile("s_waitcnt lgkmcnt(" #n ")":::"memory")
; #define P8_BAR __builtin_amdgcn_s_barrier()
; template <class EPI>
; DEVI void gemm8_tile(const bfr* __restrict__ A, const bfr* __restrict__ Bt, int K, int brow, int bcol, int nbrow, int nbcol, char* shmc, EPI epi) {
;     ...
;   { P8_LDB(B0,1,0); P8_LDA(At,1,0); P8_WAIT_V(2); P8_BAR; P8_WAIT_L(0); P8_MMA(0,0,At,B0); P8_BAR;
;     P8_LDB(B1,1,1); P8_WAIT_V(0); P8_BAR; P8_WAIT_L(0); P8_MMA(0,1,At,B1); P8_BAR;
;     P8_LDA(At,1,1); P8_BAR; P8_WAIT_L(0); P8_MMA(1,0,At,B0); P8_MMA(1,1,At,B1); P8_BAR; }
;   if(wr==0)P8_BAR;
	s_waitcnt lgkmcnt(0)
	s_setprio 1
	s_waitcnt lgkmcnt(0)
	v_mfma_f32_16x16x32_bf16 v[72:75], v[32:35], v[0:3], v[124:127]
	v_mfma_f32_16x16x32_bf16 v[120:123], v[40:43], v[8:11], v[72:75]
	v_mfma_f32_16x16x32_bf16 v[72:75], v[32:35], v[12:15], v[220:223]
	v_mfma_f32_16x16x32_bf16 v[104:107], v[40:43], v[24:27], v[72:75]
	v_mfma_f32_16x16x32_bf16 v[72:75], v[44:47], v[0:3], v[116:119]
	v_mfma_f32_16x16x32_bf16 v[124:127], v[56:59], v[8:11], v[72:75]
	v_mfma_f32_16x16x32_bf16 v[72:75], v[44:47], v[12:15], v[112:115]
	v_mfma_f32_16x16x32_bf16 v[108:111], v[56:59], v[24:27], v[72:75]
	v_mfma_f32_16x16x32_bf16 v[72:75], v[64:67], v[0:3], v[224:227]
	v_mfma_f32_16x16x32_bf16 v[112:115], v[196:199], v[8:11], v[72:75]
	v_mfma_f32_16x16x32_bf16 v[72:75], v[64:67], v[12:15], v[228:231]
	v_mfma_f32_16x16x32_bf16 v[96:99], v[196:199], v[24:27], v[72:75]
	v_mfma_f32_16x16x32_bf16 v[72:75], v[208:211], v[0:3], v[100:103]
	v_mfma_f32_16x16x32_bf16 v[116:119], v[212:215], v[8:11], v[72:75]
	v_mfma_f32_16x16x32_bf16 v[72:75], v[208:211], v[12:15], v[232:235]
	v_mfma_f32_16x16x32_bf16 v[100:103], v[212:215], v[24:27], v[72:75]
	s_setprio 0
	s_barrier
	ds_read_b128 v[220:223], v148
	ds_read_b128 v[224:227], v148 offset:1024
	ds_read_b128 v[228:231], v148 offset:2048
	ds_read_b128 v[232:235], v148 offset:3072
	s_waitcnt vmcnt(0)
	s_barrier
	s_waitcnt lgkmcnt(0)
	s_setprio 1
	s_waitcnt lgkmcnt(0)
	v_mfma_f32_16x16x32_bf16 v[72:75], v[32:35], v[220:223], v[92:95]
	v_mfma_f32_16x16x32_bf16 v[32:35], v[32:35], v[228:231], v[154:157]
	v_mfma_f32_16x16x32_bf16 v[88:91], v[40:43], v[224:227], v[72:75]
	v_mfma_f32_16x16x32_bf16 v[72:75], v[40:43], v[232:235], v[32:35]
	v_mfma_f32_16x16x32_bf16 v[32:35], v[44:47], v[220:223], v[84:87]
	v_mfma_f32_16x16x32_bf16 v[92:95], v[56:59], v[224:227], v[32:35]
	v_mfma_f32_16x16x32_bf16 v[32:35], v[44:47], v[228:231], v[80:83]
	v_mfma_f32_16x16x32_bf16 v[76:79], v[56:59], v[232:235], v[32:35]
	v_mfma_f32_16x16x32_bf16 v[32:35], v[64:67], v[220:223], v[178:181]
	v_mfma_f32_16x16x32_bf16 v[80:83], v[196:199], v[224:227], v[32:35]
	v_mfma_f32_16x16x32_bf16 v[32:35], v[64:67], v[228:231], v[182:185]
	v_mfma_f32_16x16x32_bf16 v[64:67], v[196:199], v[232:235], v[32:35]
	v_mfma_f32_16x16x32_bf16 v[32:35], v[208:211], v[220:223], v[68:71]
	v_mfma_f32_16x16x32_bf16 v[84:87], v[212:215], v[224:227], v[32:35]
	v_mfma_f32_16x16x32_bf16 v[32:35], v[208:211], v[228:231], v[186:189]
	v_mfma_f32_16x16x32_bf16 v[68:71], v[212:215], v[232:235], v[32:35]
	s_setprio 0
	s_barrier
	ds_read_b128 v[154:157], v147 offset:49152
	ds_read_b128 v[176:179], v147 offset:50176
	ds_read_b128 v[180:183], v146 offset:49152
	ds_read_b128 v[146:149], v146 offset:50176
	ds_read_b128 v[184:187], v145 offset:49152
	ds_read_b128 v[196:199], v145 offset:50176
	ds_read_b128 v[208:211], v144 offset:49152
	ds_read_b128 v[212:215], v144 offset:50176
	s_barrier
	s_waitcnt lgkmcnt(0)
	s_setprio 1
	s_waitcnt lgkmcnt(0)
	v_mfma_f32_16x16x32_bf16 v[32:35], v[154:157], v[0:3], v[60:63]
	v_mfma_f32_16x16x32_bf16 v[56:59], v[176:179], v[8:11], v[32:35]
	v_mfma_f32_16x16x32_bf16 v[32:35], v[154:157], v[12:15], v[216:219]
	v_mfma_f32_16x16x32_bf16 v[40:43], v[176:179], v[24:27], v[32:35]
	v_mfma_f32_16x16x32_bf16 v[32:35], v[180:183], v[0:3], v[52:55]
	v_mfma_f32_16x16x32_bf16 v[60:63], v[146:149], v[8:11], v[32:35]
	v_mfma_f32_16x16x32_bf16 v[32:35], v[180:183], v[12:15], v[48:51]
	v_mfma_f32_16x16x32_bf16 v[44:47], v[146:149], v[24:27], v[32:35]
	v_mfma_f32_16x16x32_bf16 v[32:35], v[184:187], v[0:3], v[236:239]
	v_mfma_f32_16x16x32_bf16 v[0:3], v[208:211], v[0:3], v[36:39]
	v_mfma_f32_16x16x32_bf16 v[48:51], v[196:199], v[8:11], v[32:35]
	v_mfma_f32_16x16x32_bf16 v[32:35], v[184:187], v[12:15], v[240:243]
	v_mfma_f32_16x16x32_bf16 v[52:55], v[212:215], v[8:11], v[0:3]
	v_mfma_f32_16x16x32_bf16 v[0:3], v[208:211], v[12:15], v[132:135]
	v_mfma_f32_16x16x32_bf16 v[32:35], v[196:199], v[24:27], v[32:35]
	v_mfma_f32_16x16x32_bf16 v[36:39], v[212:215], v[24:27], v[0:3]
	s_setprio 0
	s_setprio 1
	v_mfma_f32_16x16x32_bf16 v[0:3], v[154:157], v[220:223], v[28:31]
	v_mfma_f32_16x16x32_bf16 v[24:27], v[176:179], v[224:227], v[0:3]
	v_mfma_f32_16x16x32_bf16 v[0:3], v[154:157], v[228:231], v[136:139]
	v_mfma_f32_16x16x32_bf16 v[8:11], v[176:179], v[232:235], v[0:3]
	v_mfma_f32_16x16x32_bf16 v[0:3], v[180:183], v[220:223], v[20:23]
	v_mfma_f32_16x16x32_bf16 v[28:31], v[146:149], v[224:227], v[0:3]
	v_mfma_f32_16x16x32_bf16 v[0:3], v[180:183], v[228:231], v[16:19]
	v_mfma_f32_16x16x32_bf16 v[12:15], v[146:149], v[232:235], v[0:3]
	v_mfma_f32_16x16x32_bf16 v[0:3], v[184:187], v[220:223], v[150:153]
	v_mfma_f32_16x16x32_bf16 v[4:7], v[208:211], v[220:223], v[4:7]
	v_mfma_f32_16x16x32_bf16 v[16:19], v[196:199], v[224:227], v[0:3]
	v_mfma_f32_16x16x32_bf16 v[0:3], v[184:187], v[228:231], v[172:175]
	v_mfma_f32_16x16x32_bf16 v[20:23], v[212:215], v[224:227], v[4:7]
	v_mfma_f32_16x16x32_bf16 v[4:7], v[208:211], v[228:231], v[190:193]
	v_mfma_f32_16x16x32_bf16 v[0:3], v[196:199], v[232:235], v[0:3]
	v_mfma_f32_16x16x32_bf16 v[4:7], v[212:215], v[232:235], v[4:7]
	s_setprio 0
	v_cmp_gt_u32_e32 vcc, s57, v142
	s_barrier
	s_and_saveexec_b64 s[0:1], vcc
	s_cbranch_execz .LBB0_404
	s_barrier
